# plus: prev-token rows via DPP row_shr in prep; P2 K-loop hand-scheduled with LDS-DMA prefetch distance 2; attention row-max via permlane swaps instead of ds_bpermute
# speedup vs baseline: 1.0358x; 1.0205x over previous
.LBB0_261:
	s_and_b32 s0, s15, 7
	s_cmpk_gt_u32 s34, 0xd7
	s_cselect_b32 s1, 0xffffff28, 0
	s_cselect_b32 s40, 8, 0
	s_and_b32 s13, s34, 7
	v_mov_b32_e32 v149, v178
	s_or_b32 s13, s13, s40
	v_readlane_b32 s41, v235, 6
	s_or_b32 s13, s13, s41
	v_ashrrev_i32_e32 v2, 6, v149
	v_bfe_u32 v12, v149, 3, 3
	v_lshlrev_b32_e32 v13, 5, v2
	s_add_i32 s1, s1, s34
	s_lshl_b32 s13, s13, 7
	v_or_b32_e32 v4, v13, v12
	s_lshl_b32 s1, s1, 4
	v_add_u32_e32 v0, s13, v4
	s_and_b32 s44, s1, 0xffffff80
	v_ashrrev_i32_e32 v1, 31, v0
	v_readlane_b32 s42, v236, 42
	v_lshlrev_b64 v[0:1], 11, v[0:1]
	v_add_u32_e32 v4, s44, v4
	v_bfe_u32 v147, v149, 4, 2
	v_readlane_b32 s43, v236, 43
	v_ashrrev_i32_e32 v5, 31, v4
	v_xor_b32_e32 v6, v147, v149
	v_lshl_add_u64 v[0:1], s[42:43], 0, v[0:1]
	v_readlane_b32 s42, v234, 18
	v_lshlrev_b64 v[4:5], 11, v[4:5]
	v_lshrrev_b32_e32 v7, 4, v149
	v_readlane_b32 s43, v234, 19
	v_lshlrev_b32_e32 v150, 12, v2
	v_lshlrev_b32_e32 v2, 4, v6
	v_bitop3_b32 v10, v7, v149, 4 bitop3:0x36
	v_lshl_add_u64 v[4:5], s[42:43], 0, v[4:5]
	v_and_b32_e32 v2, 0x70, v2
	v_or_b32_e32 v14, 4, v7
	v_add_u32_e32 v151, 0x4000, v150
	v_lshl_add_u64 v[6:7], v[0:1], 0, v[2:3]
	v_readfirstlane_b32 s1, v150
	v_lshl_add_u64 v[8:9], v[4:5], 0, v[2:3]
	v_lshlrev_b32_e32 v2, 4, v10
	s_mov_b32 m0, s1
	v_readfirstlane_b32 s1, v151
	v_and_b32_e32 v2, 0x70, v2
	v_or_b32_e32 v15, 0x400, v150
	global_load_lds_dwordx4 v[6:7], off
	s_mov_b32 m0, s1
	v_lshl_add_u64 v[0:1], v[0:1], 0, v[2:3]
	s_mov_b64 s[42:43], 0x4000
	v_readfirstlane_b32 s1, v15
	v_add_u32_e32 v152, 0x4400, v150
	global_load_lds_dwordx4 v[8:9], off
	v_lshl_add_u64 v[10:11], v[0:1], 0, s[42:43]
	s_mov_b32 m0, s1
	v_lshl_add_u64 v[4:5], v[4:5], 0, v[2:3]
	v_readfirstlane_b32 s1, v152
	v_or_b32_e32 v2, 0x800, v150
	global_load_lds_dwordx4 v[10:11], off
	v_lshl_add_u64 v[10:11], v[4:5], 0, s[42:43]
	s_mov_b32 m0, s1
	s_mov_b64 s[42:43], 0x8000
	v_readfirstlane_b32 s1, v2
	v_add_u32_e32 v153, 0x4800, v150
	global_load_lds_dwordx4 v[10:11], off
	v_lshl_add_u64 v[6:7], v[6:7], 0, s[42:43]
	s_mov_b32 m0, s1
	v_readfirstlane_b32 s1, v153
	v_or_b32_e32 v2, 0xc00, v150
	global_load_lds_dwordx4 v[6:7], off
	v_lshl_add_u64 v[6:7], v[8:9], 0, s[42:43]
	s_mov_b32 m0, s1
	s_mov_b64 s[42:43], 0xc000
	v_readfirstlane_b32 s1, v2
	v_add_u32_e32 v154, 0x4c00, v150
	global_load_lds_dwordx4 v[6:7], off
	v_lshl_add_u64 v[0:1], v[0:1], 0, s[42:43]
	s_mov_b32 m0, s1
	v_readfirstlane_b32 s1, v154
	global_load_lds_dwordx4 v[0:1], off
	v_lshl_add_u64 v[0:1], v[4:5], 0, s[42:43]
	s_mov_b32 m0, s1
	v_ashrrev_i32_e32 v155, 1, v149
	global_load_lds_dwordx4 v[0:1], off
	v_lshrrev_b32_e32 v0, 1, v149
	v_bfe_u32 v1, v149, 1, 3
	v_bitop3_b32 v0, v147, v0, 7 bitop3:0x78
	s_add_i32 s1, s41, s40
	v_and_b32_e32 v146, 15, v149
	v_and_b32_e32 v156, 0xffffffc0, v155
	v_lshlrev_b32_e32 v10, 4, v0
	v_bitop3_b32 v0, v147, v1, 4 bitop3:0x36
	s_add_i32 s1, s1, s0
	v_or_b32_e32 v6, s44, v12
	v_or_b32_e32 v2, v156, v146
	v_lshlrev_b32_e32 v11, 4, v0
	v_lshl_or_b32 v0, s1, 7, v12
	v_add_u32_e32 v6, v6, v13
	v_lshlrev_b32_e32 v8, 7, v2
	v_lshlrev_b32_e32 v2, 7, v149
	v_add_u32_e32 v0, v0, v13
	v_ashrrev_i32_e32 v7, 31, v6
	v_readlane_b32 s0, v234, 9
	v_and_b32_e32 v9, 0x2780, v2
	v_ashrrev_i32_e32 v1, 31, v0
	v_bitop3_b32 v2, v147, 7, v149 bitop3:0x48
	v_bitop3_b32 v4, v14, 7, v149 bitop3:0x48
	v_lshlrev_b64 v[6:7], 11, v[6:7]
	v_readlane_b32 s1, v234, 10
	v_lshlrev_b64 v[0:1], 11, v[0:1]
	v_lshlrev_b32_e32 v2, 4, v2
	v_lshlrev_b32_e32 v4, 4, v4
	v_mov_b32_e32 v5, v3
	v_lshl_add_u64 v[6:7], s[0:1], 0, v[6:7]
	v_mov_b32_e32 v52, 0
	s_mov_b32 s12, 0
	v_and_b32_e32 v148, 63, v149
	v_or_b32_e32 v132, v0, v2
	v_mov_b32_e32 v133, v1
	v_or_b32_e32 v0, v0, v4
	v_lshl_add_u64 v[134:135], v[6:7], 0, v[2:3]
	v_lshl_add_u64 v[136:137], v[6:7], 0, v[4:5]
	v_add_u32_e32 v2, v8, v10
	v_add_u32_e32 v157, v9, v10
	v_add_u32_e32 v158, v8, v11
	v_add_u32_e32 v159, v9, v11
	v_add_u32_e32 v160, 0x8000, v150
	v_add_u32_e32 v161, 0xc000, v150
	v_add_u32_e32 v162, 0x8400, v150
	v_add_u32_e32 v163, 0xc400, v150
	v_add_u32_e32 v164, 0x8800, v150
	v_add_u32_e32 v165, 0xc800, v150
	v_add_u32_e32 v166, 0x8c00, v150
	v_add_u32_e32 v167, 0xcc00, v150
	s_mov_b64 s[0:1], s[24:25]
	v_mov_b32_e32 v53, v52
	v_mov_b32_e32 v54, v52
	v_mov_b32_e32 v55, v52
	v_mov_b32_e32 v64, v52
	v_mov_b32_e32 v65, v52
	v_mov_b32_e32 v66, v52
	v_mov_b32_e32 v67, v52
	v_mov_b32_e32 v60, v52
	v_mov_b32_e32 v61, v52
	v_mov_b32_e32 v62, v52
	v_mov_b32_e32 v63, v52
	v_mov_b32_e32 v56, v52
	v_mov_b32_e32 v57, v52
	v_mov_b32_e32 v58, v52
	v_mov_b32_e32 v59, v52
	v_mov_b32_e32 v48, v52
	v_mov_b32_e32 v49, v52
	v_mov_b32_e32 v50, v52
	v_mov_b32_e32 v51, v52
	v_mov_b32_e32 v44, v52
	v_mov_b32_e32 v45, v52
	v_mov_b32_e32 v46, v52
	v_mov_b32_e32 v47, v52
	v_mov_b32_e32 v40, v52
	v_mov_b32_e32 v41, v52
	v_mov_b32_e32 v42, v52
	v_mov_b32_e32 v43, v52
	v_mov_b32_e32 v36, v52
	v_mov_b32_e32 v37, v52
	v_mov_b32_e32 v38, v52
	v_mov_b32_e32 v39, v52
	v_mov_b32_e32 v32, v52
	v_mov_b32_e32 v33, v52
	v_mov_b32_e32 v34, v52
	v_mov_b32_e32 v35, v52
	v_mov_b32_e32 v28, v52
	v_mov_b32_e32 v29, v52
	v_mov_b32_e32 v30, v52
	v_mov_b32_e32 v31, v52
	v_mov_b32_e32 v24, v52
	v_mov_b32_e32 v25, v52
	v_mov_b32_e32 v26, v52
	v_mov_b32_e32 v27, v52
	v_mov_b32_e32 v20, v52
	v_mov_b32_e32 v21, v52
	v_mov_b32_e32 v22, v52
	v_mov_b32_e32 v23, v52
	v_mov_b32_e32 v16, v52
	v_mov_b32_e32 v17, v52
	v_mov_b32_e32 v18, v52
	v_mov_b32_e32 v19, v52
	v_mov_b32_e32 v12, v52
	v_mov_b32_e32 v13, v52
	v_mov_b32_e32 v14, v52
	v_mov_b32_e32 v15, v52
	v_mov_b32_e32 v8, v52
	v_mov_b32_e32 v9, v52
	v_mov_b32_e32 v10, v52
	v_mov_b32_e32 v11, v52
	v_mov_b32_e32 v4, v52
	v_mov_b32_e32 v5, v52
	v_mov_b32_e32 v6, v52
	v_mov_b32_e32 v7, v52
	v_add_u32_e32 v172, 0x4000, v0
	v_add_u32_e32 v173, 0x8000, v132
	v_add_u32_e32 v174, 0xc000, v0
	v_add_u32_e32 v175, 0x4000, v136
	v_add_u32_e32 v176, 0x8000, v134
	v_add_u32_e32 v177, 0xc000, v136
	v_readfirstlane_b32 s42, v150
	s_add_u32 s0, s24, 0x4c47080
	s_addc_u32 s1, s25, 0
	s_add_u32 s40, s24, 0x467080
	s_addc_u32 s41, s25, 0
	s_add_u32 m0, s42, 0x8000
	s_nop 0
	global_load_lds_dwordx4 v132, s[0:1]
	s_add_u32 m0, s42, 0xc000
	s_nop 0
	global_load_lds_dwordx4 v134, s[40:41]
	s_add_u32 m0, s42, 0x8400
	s_nop 0
	global_load_lds_dwordx4 v172, s[0:1]
	s_add_u32 m0, s42, 0xc400
	s_nop 0
	global_load_lds_dwordx4 v175, s[40:41]
	s_add_u32 m0, s42, 0x8800
	s_nop 0
	global_load_lds_dwordx4 v173, s[0:1]
	s_add_u32 m0, s42, 0xc800
	s_nop 0
	global_load_lds_dwordx4 v176, s[40:41]
	s_add_u32 m0, s42, 0x8c00
	s_nop 0
	global_load_lds_dwordx4 v174, s[0:1]
	s_add_u32 m0, s42, 0xcc00
	s_nop 0
	global_load_lds_dwordx4 v177, s[40:41]
	s_add_u32 s0, s0, 0x80
	s_addc_u32 s1, s1, 0
	s_add_u32 s40, s40, 0x80
	s_addc_u32 s41, s41, 0
	s_waitcnt vmcnt(0)
	s_barrier
	s_mov_b32 s12, 0
.Lp2k_loop:
	ds_read_b128 v[76:79], v157 offset:16384
	ds_read_b128 v[68:71], v2 offset:0
	ds_read_b128 v[80:83], v157 offset:18432
	ds_read_b128 v[72:75], v2 offset:2048
	ds_read_b128 v[92:95], v157 offset:20480
	ds_read_b128 v[84:87], v2 offset:4096
	ds_read_b128 v[96:99], v157 offset:22528
	ds_read_b128 v[88:91], v2 offset:6144
	ds_read_b128 v[108:111], v159 offset:16384
	ds_read_b128 v[100:103], v158 offset:0
	ds_read_b128 v[112:115], v159 offset:18432
	ds_read_b128 v[104:107], v158 offset:2048
	ds_read_b128 v[124:127], v159 offset:20480
	ds_read_b128 v[116:119], v158 offset:4096
	ds_read_b128 v[128:131], v159 offset:22528
	ds_read_b128 v[120:123], v158 offset:6144
	s_waitcnt lgkmcnt(0)
	s_barrier
	v_mfma_f32_16x16x32_bf16 v[52:55], v[76:79], v[68:71], v[52:55]
	v_mfma_f32_16x16x32_bf16 v[64:67], v[80:83], v[68:71], v[64:67]
	v_mfma_f32_16x16x32_bf16 v[60:63], v[92:95], v[68:71], v[60:63]
	s_add_u32 m0, s42, 0x0
	v_mfma_f32_16x16x32_bf16 v[56:59], v[96:99], v[68:71], v[56:59]
	global_load_lds_dwordx4 v132, s[0:1]
	v_mfma_f32_16x16x32_bf16 v[48:51], v[76:79], v[72:75], v[48:51]
	v_mfma_f32_16x16x32_bf16 v[44:47], v[80:83], v[72:75], v[44:47]
	v_mfma_f32_16x16x32_bf16 v[40:43], v[92:95], v[72:75], v[40:43]
	s_add_u32 m0, s42, 0x4000
	v_mfma_f32_16x16x32_bf16 v[36:39], v[96:99], v[72:75], v[36:39]
	global_load_lds_dwordx4 v134, s[40:41]
	v_mfma_f32_16x16x32_bf16 v[32:35], v[76:79], v[84:87], v[32:35]
	v_mfma_f32_16x16x32_bf16 v[28:31], v[80:83], v[84:87], v[28:31]
	v_mfma_f32_16x16x32_bf16 v[24:27], v[92:95], v[84:87], v[24:27]
	s_add_u32 m0, s42, 0x400
	v_mfma_f32_16x16x32_bf16 v[20:23], v[96:99], v[84:87], v[20:23]
	global_load_lds_dwordx4 v172, s[0:1]
	v_mfma_f32_16x16x32_bf16 v[16:19], v[76:79], v[88:91], v[16:19]
	v_mfma_f32_16x16x32_bf16 v[12:15], v[80:83], v[88:91], v[12:15]
	v_mfma_f32_16x16x32_bf16 v[8:11], v[92:95], v[88:91], v[8:11]
	s_add_u32 m0, s42, 0x4400
	v_mfma_f32_16x16x32_bf16 v[4:7], v[96:99], v[88:91], v[4:7]
	global_load_lds_dwordx4 v175, s[40:41]
	v_mfma_f32_16x16x32_bf16 v[52:55], v[108:111], v[100:103], v[52:55]
	v_mfma_f32_16x16x32_bf16 v[64:67], v[112:115], v[100:103], v[64:67]
	v_mfma_f32_16x16x32_bf16 v[60:63], v[124:127], v[100:103], v[60:63]
	s_add_u32 m0, s42, 0x800
	v_mfma_f32_16x16x32_bf16 v[56:59], v[128:131], v[100:103], v[56:59]
	global_load_lds_dwordx4 v173, s[0:1]
	v_mfma_f32_16x16x32_bf16 v[48:51], v[108:111], v[104:107], v[48:51]
	v_mfma_f32_16x16x32_bf16 v[44:47], v[112:115], v[104:107], v[44:47]
	v_mfma_f32_16x16x32_bf16 v[40:43], v[124:127], v[104:107], v[40:43]
	s_add_u32 m0, s42, 0x4800
	v_mfma_f32_16x16x32_bf16 v[36:39], v[128:131], v[104:107], v[36:39]
	global_load_lds_dwordx4 v176, s[40:41]
	v_mfma_f32_16x16x32_bf16 v[32:35], v[108:111], v[116:119], v[32:35]
	v_mfma_f32_16x16x32_bf16 v[28:31], v[112:115], v[116:119], v[28:31]
	v_mfma_f32_16x16x32_bf16 v[24:27], v[124:127], v[116:119], v[24:27]
	s_add_u32 m0, s42, 0xc00
	v_mfma_f32_16x16x32_bf16 v[20:23], v[128:131], v[116:119], v[20:23]
	global_load_lds_dwordx4 v174, s[0:1]
	v_mfma_f32_16x16x32_bf16 v[16:19], v[108:111], v[120:123], v[16:19]
	v_mfma_f32_16x16x32_bf16 v[12:15], v[112:115], v[120:123], v[12:15]
	v_mfma_f32_16x16x32_bf16 v[8:11], v[124:127], v[120:123], v[8:11]
	s_add_u32 m0, s42, 0x4c00
	v_mfma_f32_16x16x32_bf16 v[4:7], v[128:131], v[120:123], v[4:7]
	global_load_lds_dwordx4 v177, s[40:41]
	s_add_u32 s0, s0, 0x80
	s_addc_u32 s1, s1, 0
	s_add_u32 s40, s40, 0x80
	s_addc_u32 s41, s41, 0
	s_waitcnt vmcnt(8)
	s_barrier
	ds_read_b128 v[76:79], v157 offset:49152
	ds_read_b128 v[68:71], v2 offset:32768
	ds_read_b128 v[80:83], v157 offset:51200
	ds_read_b128 v[72:75], v2 offset:34816
	ds_read_b128 v[92:95], v157 offset:53248
	ds_read_b128 v[84:87], v2 offset:36864
	ds_read_b128 v[96:99], v157 offset:55296
	ds_read_b128 v[88:91], v2 offset:38912
	ds_read_b128 v[108:111], v159 offset:49152
	ds_read_b128 v[100:103], v158 offset:32768
	ds_read_b128 v[112:115], v159 offset:51200
	ds_read_b128 v[104:107], v158 offset:34816
	ds_read_b128 v[124:127], v159 offset:53248
	ds_read_b128 v[116:119], v158 offset:36864
	ds_read_b128 v[128:131], v159 offset:55296
	ds_read_b128 v[120:123], v158 offset:38912
	s_waitcnt lgkmcnt(0)
	s_barrier
	v_mfma_f32_16x16x32_bf16 v[52:55], v[76:79], v[68:71], v[52:55]
	v_mfma_f32_16x16x32_bf16 v[64:67], v[80:83], v[68:71], v[64:67]
	v_mfma_f32_16x16x32_bf16 v[60:63], v[92:95], v[68:71], v[60:63]
	s_add_u32 m0, s42, 0x8000
	v_mfma_f32_16x16x32_bf16 v[56:59], v[96:99], v[68:71], v[56:59]
	global_load_lds_dwordx4 v132, s[0:1]
	v_mfma_f32_16x16x32_bf16 v[48:51], v[76:79], v[72:75], v[48:51]
	v_mfma_f32_16x16x32_bf16 v[44:47], v[80:83], v[72:75], v[44:47]
	v_mfma_f32_16x16x32_bf16 v[40:43], v[92:95], v[72:75], v[40:43]
	s_add_u32 m0, s42, 0xc000
	v_mfma_f32_16x16x32_bf16 v[36:39], v[96:99], v[72:75], v[36:39]
	global_load_lds_dwordx4 v134, s[40:41]
	v_mfma_f32_16x16x32_bf16 v[32:35], v[76:79], v[84:87], v[32:35]
	v_mfma_f32_16x16x32_bf16 v[28:31], v[80:83], v[84:87], v[28:31]
	v_mfma_f32_16x16x32_bf16 v[24:27], v[92:95], v[84:87], v[24:27]
	s_add_u32 m0, s42, 0x8400
	v_mfma_f32_16x16x32_bf16 v[20:23], v[96:99], v[84:87], v[20:23]
	global_load_lds_dwordx4 v172, s[0:1]
	v_mfma_f32_16x16x32_bf16 v[16:19], v[76:79], v[88:91], v[16:19]
	v_mfma_f32_16x16x32_bf16 v[12:15], v[80:83], v[88:91], v[12:15]
	v_mfma_f32_16x16x32_bf16 v[8:11], v[92:95], v[88:91], v[8:11]
	s_add_u32 m0, s42, 0xc400
	v_mfma_f32_16x16x32_bf16 v[4:7], v[96:99], v[88:91], v[4:7]
	global_load_lds_dwordx4 v175, s[40:41]
	v_mfma_f32_16x16x32_bf16 v[52:55], v[108:111], v[100:103], v[52:55]
	v_mfma_f32_16x16x32_bf16 v[64:67], v[112:115], v[100:103], v[64:67]
	v_mfma_f32_16x16x32_bf16 v[60:63], v[124:127], v[100:103], v[60:63]
	s_add_u32 m0, s42, 0x8800
	v_mfma_f32_16x16x32_bf16 v[56:59], v[128:131], v[100:103], v[56:59]
	global_load_lds_dwordx4 v173, s[0:1]
	v_mfma_f32_16x16x32_bf16 v[48:51], v[108:111], v[104:107], v[48:51]
	v_mfma_f32_16x16x32_bf16 v[44:47], v[112:115], v[104:107], v[44:47]
	v_mfma_f32_16x16x32_bf16 v[40:43], v[124:127], v[104:107], v[40:43]
	s_add_u32 m0, s42, 0xc800
	v_mfma_f32_16x16x32_bf16 v[36:39], v[128:131], v[104:107], v[36:39]
	global_load_lds_dwordx4 v176, s[40:41]
	v_mfma_f32_16x16x32_bf16 v[32:35], v[108:111], v[116:119], v[32:35]
	v_mfma_f32_16x16x32_bf16 v[28:31], v[112:115], v[116:119], v[28:31]
	v_mfma_f32_16x16x32_bf16 v[24:27], v[124:127], v[116:119], v[24:27]
	s_add_u32 m0, s42, 0x8c00
	v_mfma_f32_16x16x32_bf16 v[20:23], v[128:131], v[116:119], v[20:23]
	global_load_lds_dwordx4 v174, s[0:1]
	v_mfma_f32_16x16x32_bf16 v[16:19], v[108:111], v[120:123], v[16:19]
	v_mfma_f32_16x16x32_bf16 v[12:15], v[112:115], v[120:123], v[12:15]
	v_mfma_f32_16x16x32_bf16 v[8:11], v[124:127], v[120:123], v[8:11]
	s_add_u32 m0, s42, 0xcc00
	v_mfma_f32_16x16x32_bf16 v[4:7], v[128:131], v[120:123], v[4:7]
	global_load_lds_dwordx4 v177, s[40:41]
	s_add_u32 s0, s0, 0x80
	s_addc_u32 s1, s1, 0
	s_add_u32 s40, s40, 0x80
	s_addc_u32 s41, s41, 0
	s_waitcnt vmcnt(8)
	s_barrier
	s_add_u32 s12, s12, 1
	s_cmp_lt_u32 s12, 7
	s_cbranch_scc1 .Lp2k_loop
	ds_read_b128 v[76:79], v157 offset:16384
	ds_read_b128 v[68:71], v2 offset:0
	ds_read_b128 v[80:83], v157 offset:18432
	ds_read_b128 v[72:75], v2 offset:2048
	ds_read_b128 v[92:95], v157 offset:20480
	ds_read_b128 v[84:87], v2 offset:4096
	ds_read_b128 v[96:99], v157 offset:22528
	ds_read_b128 v[88:91], v2 offset:6144
	ds_read_b128 v[108:111], v159 offset:16384
	ds_read_b128 v[100:103], v158 offset:0
	ds_read_b128 v[112:115], v159 offset:18432
	ds_read_b128 v[104:107], v158 offset:2048
	ds_read_b128 v[124:127], v159 offset:20480
	ds_read_b128 v[116:119], v158 offset:4096
	ds_read_b128 v[128:131], v159 offset:22528
	ds_read_b128 v[120:123], v158 offset:6144
	s_waitcnt lgkmcnt(0)
	s_barrier
	v_mfma_f32_16x16x32_bf16 v[52:55], v[76:79], v[68:71], v[52:55]
	v_mfma_f32_16x16x32_bf16 v[64:67], v[80:83], v[68:71], v[64:67]
	v_mfma_f32_16x16x32_bf16 v[60:63], v[92:95], v[68:71], v[60:63]
	v_mfma_f32_16x16x32_bf16 v[56:59], v[96:99], v[68:71], v[56:59]
	v_mfma_f32_16x16x32_bf16 v[48:51], v[76:79], v[72:75], v[48:51]
	v_mfma_f32_16x16x32_bf16 v[44:47], v[80:83], v[72:75], v[44:47]
	v_mfma_f32_16x16x32_bf16 v[40:43], v[92:95], v[72:75], v[40:43]
	v_mfma_f32_16x16x32_bf16 v[36:39], v[96:99], v[72:75], v[36:39]
	v_mfma_f32_16x16x32_bf16 v[32:35], v[76:79], v[84:87], v[32:35]
	v_mfma_f32_16x16x32_bf16 v[28:31], v[80:83], v[84:87], v[28:31]
	v_mfma_f32_16x16x32_bf16 v[24:27], v[92:95], v[84:87], v[24:27]
	v_mfma_f32_16x16x32_bf16 v[20:23], v[96:99], v[84:87], v[20:23]
	v_mfma_f32_16x16x32_bf16 v[16:19], v[76:79], v[88:91], v[16:19]
	v_mfma_f32_16x16x32_bf16 v[12:15], v[80:83], v[88:91], v[12:15]
	v_mfma_f32_16x16x32_bf16 v[8:11], v[92:95], v[88:91], v[8:11]
	v_mfma_f32_16x16x32_bf16 v[4:7], v[96:99], v[88:91], v[4:7]
	v_mfma_f32_16x16x32_bf16 v[52:55], v[108:111], v[100:103], v[52:55]
	v_mfma_f32_16x16x32_bf16 v[64:67], v[112:115], v[100:103], v[64:67]
	v_mfma_f32_16x16x32_bf16 v[60:63], v[124:127], v[100:103], v[60:63]
	v_mfma_f32_16x16x32_bf16 v[56:59], v[128:131], v[100:103], v[56:59]
	v_mfma_f32_16x16x32_bf16 v[48:51], v[108:111], v[104:107], v[48:51]
	v_mfma_f32_16x16x32_bf16 v[44:47], v[112:115], v[104:107], v[44:47]
	v_mfma_f32_16x16x32_bf16 v[40:43], v[124:127], v[104:107], v[40:43]
	v_mfma_f32_16x16x32_bf16 v[36:39], v[128:131], v[104:107], v[36:39]
	v_mfma_f32_16x16x32_bf16 v[32:35], v[108:111], v[116:119], v[32:35]
	v_mfma_f32_16x16x32_bf16 v[28:31], v[112:115], v[116:119], v[28:31]
	v_mfma_f32_16x16x32_bf16 v[24:27], v[124:127], v[116:119], v[24:27]
	v_mfma_f32_16x16x32_bf16 v[20:23], v[128:131], v[116:119], v[20:23]
	v_mfma_f32_16x16x32_bf16 v[16:19], v[108:111], v[120:123], v[16:19]
	v_mfma_f32_16x16x32_bf16 v[12:15], v[112:115], v[120:123], v[12:15]
	v_mfma_f32_16x16x32_bf16 v[8:11], v[124:127], v[120:123], v[8:11]
	v_mfma_f32_16x16x32_bf16 v[4:7], v[128:131], v[120:123], v[4:7]
	s_waitcnt vmcnt(0)
	s_barrier
	ds_read_b128 v[76:79], v157 offset:49152
	ds_read_b128 v[68:71], v2 offset:32768
	ds_read_b128 v[80:83], v157 offset:51200
	ds_read_b128 v[72:75], v2 offset:34816
	ds_read_b128 v[92:95], v157 offset:53248
	ds_read_b128 v[84:87], v2 offset:36864
	ds_read_b128 v[96:99], v157 offset:55296
	ds_read_b128 v[88:91], v2 offset:38912
	ds_read_b128 v[108:111], v159 offset:49152
	ds_read_b128 v[100:103], v158 offset:32768
	ds_read_b128 v[112:115], v159 offset:51200
	ds_read_b128 v[104:107], v158 offset:34816
	ds_read_b128 v[124:127], v159 offset:53248
	ds_read_b128 v[116:119], v158 offset:36864
	ds_read_b128 v[128:131], v159 offset:55296
	ds_read_b128 v[120:123], v158 offset:38912
	s_waitcnt lgkmcnt(0)
	s_barrier
	v_mfma_f32_16x16x32_bf16 v[52:55], v[76:79], v[68:71], v[52:55]
	v_mfma_f32_16x16x32_bf16 v[64:67], v[80:83], v[68:71], v[64:67]
	v_mfma_f32_16x16x32_bf16 v[60:63], v[92:95], v[68:71], v[60:63]
	v_mfma_f32_16x16x32_bf16 v[56:59], v[96:99], v[68:71], v[56:59]
	v_mfma_f32_16x16x32_bf16 v[48:51], v[76:79], v[72:75], v[48:51]
	v_mfma_f32_16x16x32_bf16 v[44:47], v[80:83], v[72:75], v[44:47]
	v_mfma_f32_16x16x32_bf16 v[40:43], v[92:95], v[72:75], v[40:43]
	v_mfma_f32_16x16x32_bf16 v[36:39], v[96:99], v[72:75], v[36:39]
	v_mfma_f32_16x16x32_bf16 v[32:35], v[76:79], v[84:87], v[32:35]
	v_mfma_f32_16x16x32_bf16 v[28:31], v[80:83], v[84:87], v[28:31]
	v_mfma_f32_16x16x32_bf16 v[24:27], v[92:95], v[84:87], v[24:27]
	v_mfma_f32_16x16x32_bf16 v[20:23], v[96:99], v[84:87], v[20:23]
	v_mfma_f32_16x16x32_bf16 v[16:19], v[76:79], v[88:91], v[16:19]
	v_mfma_f32_16x16x32_bf16 v[12:15], v[80:83], v[88:91], v[12:15]
	v_mfma_f32_16x16x32_bf16 v[8:11], v[92:95], v[88:91], v[8:11]
	v_mfma_f32_16x16x32_bf16 v[4:7], v[96:99], v[88:91], v[4:7]
	v_mfma_f32_16x16x32_bf16 v[52:55], v[108:111], v[100:103], v[52:55]
	v_mfma_f32_16x16x32_bf16 v[64:67], v[112:115], v[100:103], v[64:67]
	v_mfma_f32_16x16x32_bf16 v[60:63], v[124:127], v[100:103], v[60:63]
	v_mfma_f32_16x16x32_bf16 v[56:59], v[128:131], v[100:103], v[56:59]
	v_mfma_f32_16x16x32_bf16 v[48:51], v[108:111], v[104:107], v[48:51]
	v_mfma_f32_16x16x32_bf16 v[44:47], v[112:115], v[104:107], v[44:47]
	v_mfma_f32_16x16x32_bf16 v[40:43], v[124:127], v[104:107], v[40:43]
	v_mfma_f32_16x16x32_bf16 v[36:39], v[128:131], v[104:107], v[36:39]
	v_mfma_f32_16x16x32_bf16 v[32:35], v[108:111], v[116:119], v[32:35]
	v_mfma_f32_16x16x32_bf16 v[28:31], v[112:115], v[116:119], v[28:31]
	v_mfma_f32_16x16x32_bf16 v[24:27], v[124:127], v[116:119], v[24:27]
	v_mfma_f32_16x16x32_bf16 v[20:23], v[128:131], v[116:119], v[20:23]
	v_mfma_f32_16x16x32_bf16 v[16:19], v[108:111], v[120:123], v[16:19]
	v_mfma_f32_16x16x32_bf16 v[12:15], v[112:115], v[120:123], v[12:15]
	v_mfma_f32_16x16x32_bf16 v[8:11], v[124:127], v[120:123], v[8:11]
	v_mfma_f32_16x16x32_bf16 v[4:7], v[128:131], v[120:123], v[4:7]
	s_barrier
	s_branch .LBB0_265

.LBB0_332:
.Lprep2_entry:
	s_lshr_b32 s34, s13, 2
	v_and_b32_e32 v35, 63, v178
	v_lshrrev_b32_e32 v36, 6, v178
	v_and_b32_e32 v37, 15, v35
	v_lshrrev_b32_e32 v38, 4, v35
	s_nop 0
	v_readfirstlane_b32 s0, v36
	s_lshl_b32 s34, s34, 6
	s_lshl_b32 s0, s0, 4
	s_add_u32 s34, s34, s0
	s_and_b32 s1, s13, 3
	s_add_u32 s0, s15, s34
	v_add_u32_e32 v39, s0, v37
	v_and_b32_e32 v39, 0xfff, v39
	v_cmp_ne_u32_e32 vcc, 0, v39
	s_nop 1
	v_cndmask_b32_e64 v5, 0, -1, vcc
	s_movk_i32 s0, 0x1b00
	v_mul_lo_u32 v0, v37, s0
	v_lshlrev_b32_e32 v1, 4, v38
	v_lshlrev_b32_e32 v33, 5, v38
	s_lshl_b32 s0, s1, 8
	v_lshl_add_u32 v2, v38, 3, v0
	v_add_u32_e32 v2, s0, v2
	v_add_u32_e32 v4, v0, v1
	s_lshl_b32 s0, s1, 9
	v_add_u32_e32 v1, s0, v1
	v_lshlrev_b32_e32 v39, 7, v37
	s_lshl_b32 s0, s1, 14
	v_lshl_add_u32 v6, v38, 4, v39
	v_add_u32_e32 v6, s0, v6
	v_lshlrev_b32_e32 v39, 6, v37
	s_lshl_b32 s0, s1, 13
	v_lshl_add_u32 v7, v38, 4, v39
	v_add_u32_e32 v7, s0, v7
	v_lshlrev_b32_e32 v39, 10, v37
	s_lshl_b32 s0, s1, 8
	v_lshl_add_u32 v8, v38, 3, v39
	v_add_u32_e32 v8, s0, v8
	s_add_u32 s0, s15, s34
	s_lshl_b32 s0, s0, 10
	v_add_u32_e32 v8, s0, v8
	s_movk_i32 s0, 0x3e00
	v_mul_lo_u32 v36, v36, s0
	s_movk_i32 s0, 0x90
	v_mul_lo_u32 v39, v37, s0
	v_add_u32_e32 v9, v36, v39
	v_lshl_add_u32 v9, v38, 3, v9
	v_lshrrev_b32_e32 v39, 3, v35
	v_and_b32_e32 v35, 7, v35
	v_mul_lo_u32 v10, v39, s0
	v_add_u32_e32 v10, v36, v10
	v_lshl_add_u32 v10, v35, 4, v10
	v_lshlrev_b32_e32 v11, 10, v39
	v_lshl_add_u32 v11, v35, 4, v11
	s_lshl_b32 s0, s1, 8
	v_add_u32_e32 v11, s0, v11
	s_lshl_b32 s0, s34, 10
	v_add_u32_e32 v11, s0, v11
	v_add_u32_e32 v32, 0x2000, v11
	v_readlane_b32 s0, v233, 62
	v_readlane_b32 s1, v233, 63
	s_nop 4
	s_load_dwordx4 s[60:63], s[0:1], 0x40
	s_load_dwordx2 s[50:51], s[0:1], 0x50
	s_load_dwordx2 s[52:53], s[0:1], 0x60
	s_load_dwordx2 s[54:55], s[0:1], 0x70
	s_load_dwordx4 s[56:59], s[0:1], 0x80
	v_readlane_b32 s32, v234, 33
	s_mul_i32 s0, s34, 0x1b00
	s_add_u32 s40, s24, 0xa247000
	s_addc_u32 s41, s25, 0
	s_add_u32 s40, s40, s0
	s_addc_u32 s41, s41, 0
	s_sub_u32 s42, s40, 0x1b00
	s_subb_u32 s43, s41, 0
	s_sub_u32 s32, s32, 1
	s_waitcnt lgkmcnt(0)
	s_mul_i32 s0, s32, 0x1a00
	s_add_u32 s60, s60, s0
	s_addc_u32 s61, s61, 0
	s_add_u32 s46, s60, 0x800
	s_addc_u32 s47, s61, 0
	s_add_u32 s60, s60, 0x1800
	s_addc_u32 s61, s61, 0
	s_lshl_b32 s0, s32, 11
	s_add_u32 s50, s50, s0
	s_addc_u32 s51, s51, 0
	s_add_u32 s52, s52, s0
	s_addc_u32 s53, s53, 0
	s_add_u32 s56, s56, s0
	s_addc_u32 s57, s57, 0
	s_add_u32 s58, s58, s0
	s_addc_u32 s59, s59, 0
	s_max_i32 s1, s32, 1
	s_sub_u32 s1, s1, 1
	s_lshl_b32 s0, s1, 11
	s_add_u32 s54, s54, s0
	s_addc_u32 s55, s55, 0
	s_lshl_b32 s0, s1, 7
	s_add_u32 s62, s62, s0
	s_addc_u32 s63, s63, 0
	global_load_dwordx4 v[40:43], v4, s[40:41] offset:3072
	global_load_dwordx4 v[56:59], v4, s[40:41] offset:3136
	global_load_dwordx4 v[72:75], v4, s[40:41] offset:3200
	global_load_dwordx4 v[88:91], v4, s[40:41] offset:3264
	s_mov_b32 exec_lo, 0x10001
	s_mov_b32 exec_hi, 0x10001
	global_load_dwordx4 v[44:47], v4, s[42:43] offset:3072
	global_load_dwordx4 v[48:51], v33, s[60:61] offset:0
	global_load_dwordx4 v[52:55], v33, s[60:61] offset:16
	global_load_dwordx4 v[60:63], v4, s[42:43] offset:3136
	global_load_dwordx4 v[64:67], v33, s[60:61] offset:128
	global_load_dwordx4 v[68:71], v33, s[60:61] offset:144
	global_load_dwordx4 v[76:79], v4, s[42:43] offset:3200
	global_load_dwordx4 v[80:83], v33, s[60:61] offset:256
	global_load_dwordx4 v[84:87], v33, s[60:61] offset:272
	global_load_dwordx4 v[92:95], v4, s[42:43] offset:3264
	global_load_dwordx4 v[96:99], v33, s[60:61] offset:384
	global_load_dwordx4 v[100:103], v33, s[60:61] offset:400
	s_mov_b64 exec, -1
	s_cmp_eq_u32 s32, 0
	s_cbranch_scc1 .Lprep2_noV
	s_add_u32 s0, s40, 0x1000
	s_addc_u32 s1, s41, 0
	global_load_dwordx4 v[104:107], v4, s[0:1] offset:2624
	s_add_u32 s0, s42, 0x1000
	s_addc_u32 s1, s43, 0
	s_mov_b32 exec_lo, 0x10001
	s_mov_b32 exec_hi, 0x10001
	global_load_dwordx4 v[108:111], v4, s[0:1] offset:2624
	global_load_dwordx4 v[112:115], v33, s[62:63]
	global_load_dwordx4 v[116:119], v33, s[62:63] offset:16
	s_mov_b64 exec, -1
.Lprep2_noV:
	s_lshl_b32 s0, s32, 16
	s_add_u32 s60, s24, 0x2ba7000
	s_addc_u32 s61, s25, 0
	s_add_u32 s60, s60, s0
	s_addc_u32 s61, s61, 0
	s_lshl_b32 s0, s32, 15
	s_add_u32 s100, s24, 0x2c27000
	s_addc_u32 s101, s25, 0
	s_add_u32 s100, s100, s0
	s_addc_u32 s101, s101, 0
	s_add_u32 s0, s24, 0x2c47000
	s_addc_u32 s1, s25, 0
	s_waitcnt vmcnt(0)
	v_mov_b32_dpp v48, v48 row_newbcast:0 row_mask:0xf bank_mask:0xf
	v_mov_b32_dpp v49, v49 row_newbcast:0 row_mask:0xf bank_mask:0xf
	v_mov_b32_dpp v50, v50 row_newbcast:0 row_mask:0xf bank_mask:0xf
	v_mov_b32_dpp v51, v51 row_newbcast:0 row_mask:0xf bank_mask:0xf
	v_mov_b32_dpp v52, v52 row_newbcast:0 row_mask:0xf bank_mask:0xf
	v_mov_b32_dpp v53, v53 row_newbcast:0 row_mask:0xf bank_mask:0xf
	v_mov_b32_dpp v54, v54 row_newbcast:0 row_mask:0xf bank_mask:0xf
	v_mov_b32_dpp v55, v55 row_newbcast:0 row_mask:0xf bank_mask:0xf
	v_mov_b32_dpp v44, v40 row_shr:1 row_mask:0xf bank_mask:0xf
	v_mov_b32_dpp v45, v41 row_shr:1 row_mask:0xf bank_mask:0xf
	v_mov_b32_dpp v46, v42 row_shr:1 row_mask:0xf bank_mask:0xf
	v_mov_b32_dpp v47, v43 row_shr:1 row_mask:0xf bank_mask:0xf
	v_and_b32_e32 v44, v5, v44
	v_lshlrev_b32_e32 v164, 16, v40
	v_and_b32_e32 v165, 0xffff0000, v40
	v_lshlrev_b32_e32 v166, 16, v44
	v_and_b32_e32 v167, 0xffff0000, v44
	v_sub_f32_e32 v166, v166, v164
	v_sub_f32_e32 v167, v167, v165
	v_fmac_f32_e32 v164, v48, v166
	v_fmac_f32_e32 v165, v49, v167
	v_add_f32_e32 v164, v164, v164
	v_mul_f32_e32 v164, 0x3fb8aa3b, v164
	v_exp_f32_e32 v164, v164
	s_nop 0
	v_add_f32_e32 v164, 1.0, v164
	v_rcp_f32_e32 v164, v164
	s_nop 0
	v_fma_f32 v164, v164, -2.0, 1.0
	v_add_f32_e32 v165, v165, v165
	v_mul_f32_e32 v165, 0x3fb8aa3b, v165
	v_exp_f32_e32 v165, v165
	s_nop 0
	v_add_f32_e32 v165, 1.0, v165
	v_rcp_f32_e32 v165, v165
	s_nop 0
	v_fma_f32 v165, v165, -2.0, 1.0
	v_cvt_pk_bf16_f32 v12, v164, v165
	v_and_b32_e32 v45, v5, v45
	v_lshlrev_b32_e32 v164, 16, v41
	v_and_b32_e32 v165, 0xffff0000, v41
	v_lshlrev_b32_e32 v166, 16, v45
	v_and_b32_e32 v167, 0xffff0000, v45
	v_sub_f32_e32 v166, v166, v164
	v_sub_f32_e32 v167, v167, v165
	v_fmac_f32_e32 v164, v50, v166
	v_fmac_f32_e32 v165, v51, v167
	v_add_f32_e32 v164, v164, v164
	v_mul_f32_e32 v164, 0x3fb8aa3b, v164
	v_exp_f32_e32 v164, v164
	s_nop 0
	v_add_f32_e32 v164, 1.0, v164
	v_rcp_f32_e32 v164, v164
	s_nop 0
	v_fma_f32 v164, v164, -2.0, 1.0
	v_add_f32_e32 v165, v165, v165
	v_mul_f32_e32 v165, 0x3fb8aa3b, v165
	v_exp_f32_e32 v165, v165
	s_nop 0
	v_add_f32_e32 v165, 1.0, v165
	v_rcp_f32_e32 v165, v165
	s_nop 0
	v_fma_f32 v165, v165, -2.0, 1.0
	v_cvt_pk_bf16_f32 v13, v164, v165
	v_and_b32_e32 v46, v5, v46
	v_lshlrev_b32_e32 v164, 16, v42
	v_and_b32_e32 v165, 0xffff0000, v42
	v_lshlrev_b32_e32 v166, 16, v46
	v_and_b32_e32 v167, 0xffff0000, v46
	v_sub_f32_e32 v166, v166, v164
	v_sub_f32_e32 v167, v167, v165
	v_fmac_f32_e32 v164, v52, v166
	v_fmac_f32_e32 v165, v53, v167
	v_add_f32_e32 v164, v164, v164
	v_mul_f32_e32 v164, 0x3fb8aa3b, v164
	v_exp_f32_e32 v164, v164
	s_nop 0
	v_add_f32_e32 v164, 1.0, v164
	v_rcp_f32_e32 v164, v164
	s_nop 0
	v_fma_f32 v164, v164, -2.0, 1.0
	v_add_f32_e32 v165, v165, v165
	v_mul_f32_e32 v165, 0x3fb8aa3b, v165
	v_exp_f32_e32 v165, v165
	s_nop 0
	v_add_f32_e32 v165, 1.0, v165
	v_rcp_f32_e32 v165, v165
	s_nop 0
	v_fma_f32 v165, v165, -2.0, 1.0
	v_cvt_pk_bf16_f32 v14, v164, v165
	v_and_b32_e32 v47, v5, v47
	v_lshlrev_b32_e32 v164, 16, v43
	v_and_b32_e32 v165, 0xffff0000, v43
	v_lshlrev_b32_e32 v166, 16, v47
	v_and_b32_e32 v167, 0xffff0000, v47
	v_sub_f32_e32 v166, v166, v164
	v_sub_f32_e32 v167, v167, v165
	v_fmac_f32_e32 v164, v54, v166
	v_fmac_f32_e32 v165, v55, v167
	v_add_f32_e32 v164, v164, v164
	v_mul_f32_e32 v164, 0x3fb8aa3b, v164
	v_exp_f32_e32 v164, v164
	s_nop 0
	v_add_f32_e32 v164, 1.0, v164
	v_rcp_f32_e32 v164, v164
	s_nop 0
	v_fma_f32 v164, v164, -2.0, 1.0
	v_add_f32_e32 v165, v165, v165
	v_mul_f32_e32 v165, 0x3fb8aa3b, v165
	v_exp_f32_e32 v165, v165
	s_nop 0
	v_add_f32_e32 v165, 1.0, v165
	v_rcp_f32_e32 v165, v165
	s_nop 0
	v_fma_f32 v165, v165, -2.0, 1.0
	v_cvt_pk_bf16_f32 v15, v164, v165
	v_mov_b32_dpp v64, v64 row_newbcast:0 row_mask:0xf bank_mask:0xf
	v_mov_b32_dpp v65, v65 row_newbcast:0 row_mask:0xf bank_mask:0xf
	v_mov_b32_dpp v66, v66 row_newbcast:0 row_mask:0xf bank_mask:0xf
	v_mov_b32_dpp v67, v67 row_newbcast:0 row_mask:0xf bank_mask:0xf
	v_mov_b32_dpp v68, v68 row_newbcast:0 row_mask:0xf bank_mask:0xf
	v_mov_b32_dpp v69, v69 row_newbcast:0 row_mask:0xf bank_mask:0xf
	v_mov_b32_dpp v70, v70 row_newbcast:0 row_mask:0xf bank_mask:0xf
	v_mov_b32_dpp v71, v71 row_newbcast:0 row_mask:0xf bank_mask:0xf
	v_mov_b32_dpp v60, v56 row_shr:1 row_mask:0xf bank_mask:0xf
	v_mov_b32_dpp v61, v57 row_shr:1 row_mask:0xf bank_mask:0xf
	v_mov_b32_dpp v62, v58 row_shr:1 row_mask:0xf bank_mask:0xf
	v_mov_b32_dpp v63, v59 row_shr:1 row_mask:0xf bank_mask:0xf
	v_and_b32_e32 v60, v5, v60
	v_lshlrev_b32_e32 v164, 16, v56
	v_and_b32_e32 v165, 0xffff0000, v56
	v_lshlrev_b32_e32 v166, 16, v60
	v_and_b32_e32 v167, 0xffff0000, v60
	v_sub_f32_e32 v166, v166, v164
	v_sub_f32_e32 v167, v167, v165
	v_fmac_f32_e32 v164, v64, v166
	v_fmac_f32_e32 v165, v65, v167
	v_add_f32_e32 v164, v164, v164
	v_mul_f32_e32 v164, 0x3fb8aa3b, v164
	v_exp_f32_e32 v164, v164
	s_nop 0
	v_add_f32_e32 v164, 1.0, v164
	v_rcp_f32_e32 v164, v164
	s_nop 0
	v_fma_f32 v164, v164, -2.0, 1.0
	v_add_f32_e32 v165, v165, v165
	v_mul_f32_e32 v165, 0x3fb8aa3b, v165
	v_exp_f32_e32 v165, v165
	s_nop 0
	v_add_f32_e32 v165, 1.0, v165
	v_rcp_f32_e32 v165, v165
	s_nop 0
	v_fma_f32 v165, v165, -2.0, 1.0
	v_cvt_pk_bf16_f32 v16, v164, v165
	v_and_b32_e32 v61, v5, v61
	v_lshlrev_b32_e32 v164, 16, v57
	v_and_b32_e32 v165, 0xffff0000, v57
	v_lshlrev_b32_e32 v166, 16, v61
	v_and_b32_e32 v167, 0xffff0000, v61
	v_sub_f32_e32 v166, v166, v164
	v_sub_f32_e32 v167, v167, v165
	v_fmac_f32_e32 v164, v66, v166
	v_fmac_f32_e32 v165, v67, v167
	v_add_f32_e32 v164, v164, v164
	v_mul_f32_e32 v164, 0x3fb8aa3b, v164
	v_exp_f32_e32 v164, v164
	s_nop 0
	v_add_f32_e32 v164, 1.0, v164
	v_rcp_f32_e32 v164, v164
	s_nop 0
	v_fma_f32 v164, v164, -2.0, 1.0
	v_add_f32_e32 v165, v165, v165
	v_mul_f32_e32 v165, 0x3fb8aa3b, v165
	v_exp_f32_e32 v165, v165
	s_nop 0
	v_add_f32_e32 v165, 1.0, v165
	v_rcp_f32_e32 v165, v165
	s_nop 0
	v_fma_f32 v165, v165, -2.0, 1.0
	v_cvt_pk_bf16_f32 v17, v164, v165
	v_and_b32_e32 v62, v5, v62
	v_lshlrev_b32_e32 v164, 16, v58
	v_and_b32_e32 v165, 0xffff0000, v58
	v_lshlrev_b32_e32 v166, 16, v62
	v_and_b32_e32 v167, 0xffff0000, v62
	v_sub_f32_e32 v166, v166, v164
	v_sub_f32_e32 v167, v167, v165
	v_fmac_f32_e32 v164, v68, v166
	v_fmac_f32_e32 v165, v69, v167
	v_add_f32_e32 v164, v164, v164
	v_mul_f32_e32 v164, 0x3fb8aa3b, v164
	v_exp_f32_e32 v164, v164
	s_nop 0
	v_add_f32_e32 v164, 1.0, v164
	v_rcp_f32_e32 v164, v164
	s_nop 0
	v_fma_f32 v164, v164, -2.0, 1.0
	v_add_f32_e32 v165, v165, v165
	v_mul_f32_e32 v165, 0x3fb8aa3b, v165
	v_exp_f32_e32 v165, v165
	s_nop 0
	v_add_f32_e32 v165, 1.0, v165
	v_rcp_f32_e32 v165, v165
	s_nop 0
	v_fma_f32 v165, v165, -2.0, 1.0
	v_cvt_pk_bf16_f32 v18, v164, v165
	v_and_b32_e32 v63, v5, v63
	v_lshlrev_b32_e32 v164, 16, v59
	v_and_b32_e32 v165, 0xffff0000, v59
	v_lshlrev_b32_e32 v166, 16, v63
	v_and_b32_e32 v167, 0xffff0000, v63
	v_sub_f32_e32 v166, v166, v164
	v_sub_f32_e32 v167, v167, v165
	v_fmac_f32_e32 v164, v70, v166
	v_fmac_f32_e32 v165, v71, v167
	v_add_f32_e32 v164, v164, v164
	v_mul_f32_e32 v164, 0x3fb8aa3b, v164
	v_exp_f32_e32 v164, v164
	s_nop 0
	v_add_f32_e32 v164, 1.0, v164
	v_rcp_f32_e32 v164, v164
	s_nop 0
	v_fma_f32 v164, v164, -2.0, 1.0
	v_add_f32_e32 v165, v165, v165
	v_mul_f32_e32 v165, 0x3fb8aa3b, v165
	v_exp_f32_e32 v165, v165
	s_nop 0
	v_add_f32_e32 v165, 1.0, v165
	v_rcp_f32_e32 v165, v165
	s_nop 0
	v_fma_f32 v165, v165, -2.0, 1.0
	v_cvt_pk_bf16_f32 v19, v164, v165
	v_mov_b32_dpp v80, v80 row_newbcast:0 row_mask:0xf bank_mask:0xf
	v_mov_b32_dpp v81, v81 row_newbcast:0 row_mask:0xf bank_mask:0xf
	v_mov_b32_dpp v82, v82 row_newbcast:0 row_mask:0xf bank_mask:0xf
	v_mov_b32_dpp v83, v83 row_newbcast:0 row_mask:0xf bank_mask:0xf
	v_mov_b32_dpp v84, v84 row_newbcast:0 row_mask:0xf bank_mask:0xf
	v_mov_b32_dpp v85, v85 row_newbcast:0 row_mask:0xf bank_mask:0xf
	v_mov_b32_dpp v86, v86 row_newbcast:0 row_mask:0xf bank_mask:0xf
	v_mov_b32_dpp v87, v87 row_newbcast:0 row_mask:0xf bank_mask:0xf
	v_mov_b32_dpp v76, v72 row_shr:1 row_mask:0xf bank_mask:0xf
	v_mov_b32_dpp v77, v73 row_shr:1 row_mask:0xf bank_mask:0xf
	v_mov_b32_dpp v78, v74 row_shr:1 row_mask:0xf bank_mask:0xf
	v_mov_b32_dpp v79, v75 row_shr:1 row_mask:0xf bank_mask:0xf
	v_and_b32_e32 v76, v5, v76
	v_lshlrev_b32_e32 v164, 16, v72
	v_and_b32_e32 v165, 0xffff0000, v72
	v_lshlrev_b32_e32 v166, 16, v76
	v_and_b32_e32 v167, 0xffff0000, v76
	v_sub_f32_e32 v166, v166, v164
	v_sub_f32_e32 v167, v167, v165
	v_fmac_f32_e32 v164, v80, v166
	v_fmac_f32_e32 v165, v81, v167
	v_cvt_pk_bf16_f32 v20, v164, v165
	v_and_b32_e32 v77, v5, v77
	v_lshlrev_b32_e32 v164, 16, v73
	v_and_b32_e32 v165, 0xffff0000, v73
	v_lshlrev_b32_e32 v166, 16, v77
	v_and_b32_e32 v167, 0xffff0000, v77
	v_sub_f32_e32 v166, v166, v164
	v_sub_f32_e32 v167, v167, v165
	v_fmac_f32_e32 v164, v82, v166
	v_fmac_f32_e32 v165, v83, v167
	v_cvt_pk_bf16_f32 v21, v164, v165
	v_and_b32_e32 v78, v5, v78
	v_lshlrev_b32_e32 v164, 16, v74
	v_and_b32_e32 v165, 0xffff0000, v74
	v_lshlrev_b32_e32 v166, 16, v78
	v_and_b32_e32 v167, 0xffff0000, v78
	v_sub_f32_e32 v166, v166, v164
	v_sub_f32_e32 v167, v167, v165
	v_fmac_f32_e32 v164, v84, v166
	v_fmac_f32_e32 v165, v85, v167
	v_cvt_pk_bf16_f32 v22, v164, v165
	v_and_b32_e32 v79, v5, v79
	v_lshlrev_b32_e32 v164, 16, v75
	v_and_b32_e32 v165, 0xffff0000, v75
	v_lshlrev_b32_e32 v166, 16, v79
	v_and_b32_e32 v167, 0xffff0000, v79
	v_sub_f32_e32 v166, v166, v164
	v_sub_f32_e32 v167, v167, v165
	v_fmac_f32_e32 v164, v86, v166
	v_fmac_f32_e32 v165, v87, v167
	v_cvt_pk_bf16_f32 v23, v164, v165
	v_mov_b32_dpp v96, v96 row_newbcast:0 row_mask:0xf bank_mask:0xf
	v_mov_b32_dpp v97, v97 row_newbcast:0 row_mask:0xf bank_mask:0xf
	v_mov_b32_dpp v98, v98 row_newbcast:0 row_mask:0xf bank_mask:0xf
	v_mov_b32_dpp v99, v99 row_newbcast:0 row_mask:0xf bank_mask:0xf
	v_mov_b32_dpp v100, v100 row_newbcast:0 row_mask:0xf bank_mask:0xf
	v_mov_b32_dpp v101, v101 row_newbcast:0 row_mask:0xf bank_mask:0xf
	v_mov_b32_dpp v102, v102 row_newbcast:0 row_mask:0xf bank_mask:0xf
	v_mov_b32_dpp v103, v103 row_newbcast:0 row_mask:0xf bank_mask:0xf
	v_mov_b32_dpp v92, v88 row_shr:1 row_mask:0xf bank_mask:0xf
	v_mov_b32_dpp v93, v89 row_shr:1 row_mask:0xf bank_mask:0xf
	v_mov_b32_dpp v94, v90 row_shr:1 row_mask:0xf bank_mask:0xf
	v_mov_b32_dpp v95, v91 row_shr:1 row_mask:0xf bank_mask:0xf
	v_and_b32_e32 v92, v5, v92
	v_lshlrev_b32_e32 v164, 16, v88
	v_and_b32_e32 v165, 0xffff0000, v88
	v_lshlrev_b32_e32 v166, 16, v92
	v_and_b32_e32 v167, 0xffff0000, v92
	v_sub_f32_e32 v166, v166, v164
	v_sub_f32_e32 v167, v167, v165
	v_fmac_f32_e32 v164, v96, v166
	v_fmac_f32_e32 v165, v97, v167
	v_cvt_pk_bf16_f32 v24, v164, v165
	v_and_b32_e32 v93, v5, v93
	v_lshlrev_b32_e32 v164, 16, v89
	v_and_b32_e32 v165, 0xffff0000, v89
	v_lshlrev_b32_e32 v166, 16, v93
	v_and_b32_e32 v167, 0xffff0000, v93
	v_sub_f32_e32 v166, v166, v164
	v_sub_f32_e32 v167, v167, v165
	v_fmac_f32_e32 v164, v98, v166
	v_fmac_f32_e32 v165, v99, v167
	v_cvt_pk_bf16_f32 v25, v164, v165
	v_and_b32_e32 v94, v5, v94
	v_lshlrev_b32_e32 v164, 16, v90
	v_and_b32_e32 v165, 0xffff0000, v90
	v_lshlrev_b32_e32 v166, 16, v94
	v_and_b32_e32 v167, 0xffff0000, v94
	v_sub_f32_e32 v166, v166, v164
	v_sub_f32_e32 v167, v167, v165
	v_fmac_f32_e32 v164, v100, v166
	v_fmac_f32_e32 v165, v101, v167
	v_cvt_pk_bf16_f32 v26, v164, v165
	v_and_b32_e32 v95, v5, v95
	v_lshlrev_b32_e32 v164, 16, v91
	v_and_b32_e32 v165, 0xffff0000, v91
	v_lshlrev_b32_e32 v166, 16, v95
	v_and_b32_e32 v167, 0xffff0000, v95
	v_sub_f32_e32 v166, v166, v164
	v_sub_f32_e32 v167, v167, v165
	v_fmac_f32_e32 v164, v102, v166
	v_fmac_f32_e32 v165, v103, v167
	v_cvt_pk_bf16_f32 v27, v164, v165
	s_cmp_eq_u32 s32, 0
	s_cbranch_scc1 .Lprep2_bvz
	v_mov_b32_dpp v112, v112 row_newbcast:0 row_mask:0xf bank_mask:0xf
	v_mov_b32_dpp v113, v113 row_newbcast:0 row_mask:0xf bank_mask:0xf
	v_mov_b32_dpp v114, v114 row_newbcast:0 row_mask:0xf bank_mask:0xf
	v_mov_b32_dpp v115, v115 row_newbcast:0 row_mask:0xf bank_mask:0xf
	v_mov_b32_dpp v116, v116 row_newbcast:0 row_mask:0xf bank_mask:0xf
	v_mov_b32_dpp v117, v117 row_newbcast:0 row_mask:0xf bank_mask:0xf
	v_mov_b32_dpp v118, v118 row_newbcast:0 row_mask:0xf bank_mask:0xf
	v_mov_b32_dpp v119, v119 row_newbcast:0 row_mask:0xf bank_mask:0xf
	v_mov_b32_dpp v108, v104 row_shr:1 row_mask:0xf bank_mask:0xf
	v_mov_b32_dpp v109, v105 row_shr:1 row_mask:0xf bank_mask:0xf
	v_mov_b32_dpp v110, v106 row_shr:1 row_mask:0xf bank_mask:0xf
	v_mov_b32_dpp v111, v107 row_shr:1 row_mask:0xf bank_mask:0xf
	v_and_b32_e32 v108, v5, v108
	v_lshlrev_b32_e32 v164, 16, v104
	v_and_b32_e32 v165, 0xffff0000, v104
	v_lshlrev_b32_e32 v166, 16, v108
	v_and_b32_e32 v167, 0xffff0000, v108
	v_sub_f32_e32 v166, v166, v164
	v_sub_f32_e32 v167, v167, v165
	v_fmac_f32_e32 v164, v112, v166
	v_fmac_f32_e32 v165, v113, v167
	v_cvt_pk_bf16_f32 v28, v164, v165
	v_and_b32_e32 v109, v5, v109
	v_lshlrev_b32_e32 v164, 16, v105
	v_and_b32_e32 v165, 0xffff0000, v105
	v_lshlrev_b32_e32 v166, 16, v109
	v_and_b32_e32 v167, 0xffff0000, v109
	v_sub_f32_e32 v166, v166, v164
	v_sub_f32_e32 v167, v167, v165
	v_fmac_f32_e32 v164, v114, v166
	v_fmac_f32_e32 v165, v115, v167
	v_cvt_pk_bf16_f32 v29, v164, v165
	v_and_b32_e32 v110, v5, v110
	v_lshlrev_b32_e32 v164, 16, v106
	v_and_b32_e32 v165, 0xffff0000, v106
	v_lshlrev_b32_e32 v166, 16, v110
	v_and_b32_e32 v167, 0xffff0000, v110
	v_sub_f32_e32 v166, v166, v164
	v_sub_f32_e32 v167, v167, v165
	v_fmac_f32_e32 v164, v116, v166
	v_fmac_f32_e32 v165, v117, v167
	v_cvt_pk_bf16_f32 v30, v164, v165
	v_and_b32_e32 v111, v5, v111
	v_lshlrev_b32_e32 v164, 16, v107
	v_and_b32_e32 v165, 0xffff0000, v107
	v_lshlrev_b32_e32 v166, 16, v111
	v_and_b32_e32 v167, 0xffff0000, v111
	v_sub_f32_e32 v166, v166, v164
	v_sub_f32_e32 v167, v167, v165
	v_fmac_f32_e32 v164, v118, v166
	v_fmac_f32_e32 v165, v119, v167
	v_cvt_pk_bf16_f32 v31, v164, v165
	s_branch .Lprep2_bvd

.Lprep2_bvd:
	v_mov_b32_e32 v176, v6
	v_add_u32_e32 v177, 0x1000, v6
	v_mov_b32_e32 v181, v7
	v_add_u32_e32 v182, 0x40000, v6
	v_add_u32_e32 v183, 0x41000, v6
	global_load_dwordx2 v[40:41], v2, s[40:41] offset:1024
	global_load_dwordx2 v[52:53], v2, s[40:41] offset:1056
	global_load_dwordx2 v[64:65], v2, s[40:41] offset:1088
	global_load_dwordx2 v[76:77], v2, s[40:41] offset:1120
	s_mov_b32 exec_lo, 0x10001
	s_mov_b32 exec_hi, 0x10001
	global_load_dwordx2 v[42:43], v2, s[42:43] offset:1024
	global_load_dwordx4 v[44:47], v1, s[46:47] offset:0
	global_load_dwordx4 v[48:51], v1, s[56:57] offset:0
	global_load_dwordx2 v[54:55], v2, s[42:43] offset:1056
	global_load_dwordx4 v[56:59], v1, s[46:47] offset:64
	global_load_dwordx4 v[60:63], v1, s[56:57] offset:64
	global_load_dwordx2 v[66:67], v2, s[42:43] offset:1088
	global_load_dwordx4 v[68:71], v1, s[46:47] offset:128
	global_load_dwordx4 v[72:75], v1, s[56:57] offset:128
	global_load_dwordx2 v[78:79], v2, s[42:43] offset:1120
	global_load_dwordx4 v[80:83], v1, s[46:47] offset:192
	global_load_dwordx4 v[84:87], v1, s[56:57] offset:192
	s_mov_b64 exec, -1
	global_load_dwordx2 v[88:89], v2, s[40:41] offset:0
	global_load_dwordx2 v[96:97], v2, s[40:41] offset:2048
	global_load_dwordx4 v[104:107], v176, s[60:61] offset:0
	global_load_dwordx4 v[108:111], v176, s[60:61] offset:64
	global_load_dwordx4 v[112:115], v182, s[60:61] offset:0
	global_load_dwordx4 v[116:119], v182, s[60:61] offset:64
	global_load_dwordx4 v[120:123], v181, s[100:101] offset:0
	global_load_dwordx2 v[140:141], v8, s[0:1] offset:0
	s_mov_b32 exec_lo, 0x10001
	s_mov_b32 exec_hi, 0x10001
	global_load_dwordx2 v[90:91], v2, s[42:43] offset:0
	global_load_dwordx2 v[98:99], v2, s[42:43] offset:2048
	global_load_dwordx4 v[92:95], v1, s[46:47] offset:-2048
	global_load_dwordx4 v[100:103], v1, s[46:47] offset:2048
	global_load_dwordx4 v[124:127], v1, s[50:51] offset:0
	global_load_dwordx4 v[128:131], v1, s[52:53] offset:0
	global_load_dwordx4 v[132:135], v1, s[58:59] offset:0
	global_load_dwordx4 v[136:139], v1, s[54:55] offset:0
	s_mov_b64 exec, -1
	s_waitcnt vmcnt(16)
	v_mov_b32_dpp v44, v44 row_newbcast:0 row_mask:0xf bank_mask:0xf
	v_mov_b32_dpp v45, v45 row_newbcast:0 row_mask:0xf bank_mask:0xf
	v_mov_b32_dpp v46, v46 row_newbcast:0 row_mask:0xf bank_mask:0xf
	v_mov_b32_dpp v47, v47 row_newbcast:0 row_mask:0xf bank_mask:0xf
	v_mov_b32_dpp v48, v48 row_newbcast:0 row_mask:0xf bank_mask:0xf
	v_mov_b32_dpp v49, v49 row_newbcast:0 row_mask:0xf bank_mask:0xf
	v_mov_b32_dpp v50, v50 row_newbcast:0 row_mask:0xf bank_mask:0xf
	v_mov_b32_dpp v51, v51 row_newbcast:0 row_mask:0xf bank_mask:0xf
	v_mov_b32_dpp v42, v40 row_shr:1 row_mask:0xf bank_mask:0xf
	v_mov_b32_dpp v43, v41 row_shr:1 row_mask:0xf bank_mask:0xf
	v_and_b32_e32 v42, v5, v42
	v_and_b32_e32 v43, v5, v43
	v_lshlrev_b32_e32 v204, 16, v40
	v_and_b32_e32 v205, 0xffff0000, v40
	v_lshlrev_b32_e32 v220, 16, v42
	v_and_b32_e32 v221, 0xffff0000, v42
	v_sub_f32_e32 v220, v220, v204
	v_sub_f32_e32 v221, v221, v205
	v_fmac_f32_e32 v204, v44, v220
	v_fmac_f32_e32 v205, v45, v221
	v_lshlrev_b32_e32 v206, 16, v41
	v_and_b32_e32 v207, 0xffff0000, v41
	v_lshlrev_b32_e32 v220, 16, v43
	v_and_b32_e32 v221, 0xffff0000, v43
	v_sub_f32_e32 v220, v220, v206
	v_sub_f32_e32 v221, v221, v207
	v_fmac_f32_e32 v206, v46, v220
	v_fmac_f32_e32 v207, v47, v221
	v_mul_f32_e32 v148, v204, v48
	v_mul_f32_e32 v149, v205, v49
	v_mul_f32_e32 v150, v206, v50
	v_mul_f32_e32 v151, v207, v51
	v_mul_f32_e32 v223, v148, v148
	v_fma_f32 v223, v149, v149, v223
	v_fma_f32 v223, v150, v150, v223
	v_fma_f32 v223, v151, v151, v223
	v_mov_b32_e32 v222, v223
	v_mov_b32_dpp v56, v56 row_newbcast:0 row_mask:0xf bank_mask:0xf
	v_mov_b32_dpp v57, v57 row_newbcast:0 row_mask:0xf bank_mask:0xf
	v_mov_b32_dpp v58, v58 row_newbcast:0 row_mask:0xf bank_mask:0xf
	v_mov_b32_dpp v59, v59 row_newbcast:0 row_mask:0xf bank_mask:0xf
	v_mov_b32_dpp v60, v60 row_newbcast:0 row_mask:0xf bank_mask:0xf
	v_mov_b32_dpp v61, v61 row_newbcast:0 row_mask:0xf bank_mask:0xf
	v_mov_b32_dpp v62, v62 row_newbcast:0 row_mask:0xf bank_mask:0xf
	v_mov_b32_dpp v63, v63 row_newbcast:0 row_mask:0xf bank_mask:0xf
	v_mov_b32_dpp v54, v52 row_shr:1 row_mask:0xf bank_mask:0xf
	v_mov_b32_dpp v55, v53 row_shr:1 row_mask:0xf bank_mask:0xf
	v_and_b32_e32 v54, v5, v54
	v_and_b32_e32 v55, v5, v55
	v_lshlrev_b32_e32 v208, 16, v52
	v_and_b32_e32 v209, 0xffff0000, v52
	v_lshlrev_b32_e32 v220, 16, v54
	v_and_b32_e32 v221, 0xffff0000, v54
	v_sub_f32_e32 v220, v220, v208
	v_sub_f32_e32 v221, v221, v209
	v_fmac_f32_e32 v208, v56, v220
	v_fmac_f32_e32 v209, v57, v221
	v_lshlrev_b32_e32 v210, 16, v53
	v_and_b32_e32 v211, 0xffff0000, v53
	v_lshlrev_b32_e32 v220, 16, v55
	v_and_b32_e32 v221, 0xffff0000, v55
	v_sub_f32_e32 v220, v220, v210
	v_sub_f32_e32 v221, v221, v211
	v_fmac_f32_e32 v210, v58, v220
	v_fmac_f32_e32 v211, v59, v221
	v_mul_f32_e32 v152, v208, v60
	v_mul_f32_e32 v153, v209, v61
	v_mul_f32_e32 v154, v210, v62
	v_mul_f32_e32 v155, v211, v63
	v_mul_f32_e32 v223, v152, v152
	v_fma_f32 v223, v153, v153, v223
	v_fma_f32 v223, v154, v154, v223
	v_fma_f32 v223, v155, v155, v223
	v_add_f32_e32 v222, v222, v223
	v_mov_b32_dpp v68, v68 row_newbcast:0 row_mask:0xf bank_mask:0xf
	v_mov_b32_dpp v69, v69 row_newbcast:0 row_mask:0xf bank_mask:0xf
	v_mov_b32_dpp v70, v70 row_newbcast:0 row_mask:0xf bank_mask:0xf
	v_mov_b32_dpp v71, v71 row_newbcast:0 row_mask:0xf bank_mask:0xf
	v_mov_b32_dpp v72, v72 row_newbcast:0 row_mask:0xf bank_mask:0xf
	v_mov_b32_dpp v73, v73 row_newbcast:0 row_mask:0xf bank_mask:0xf
	v_mov_b32_dpp v74, v74 row_newbcast:0 row_mask:0xf bank_mask:0xf
	v_mov_b32_dpp v75, v75 row_newbcast:0 row_mask:0xf bank_mask:0xf
	v_mov_b32_dpp v66, v64 row_shr:1 row_mask:0xf bank_mask:0xf
	v_mov_b32_dpp v67, v65 row_shr:1 row_mask:0xf bank_mask:0xf
	v_and_b32_e32 v66, v5, v66
	v_and_b32_e32 v67, v5, v67
	v_lshlrev_b32_e32 v212, 16, v64
	v_and_b32_e32 v213, 0xffff0000, v64
	v_lshlrev_b32_e32 v220, 16, v66
	v_and_b32_e32 v221, 0xffff0000, v66
	v_sub_f32_e32 v220, v220, v212
	v_sub_f32_e32 v221, v221, v213
	v_fmac_f32_e32 v212, v68, v220
	v_fmac_f32_e32 v213, v69, v221
	v_lshlrev_b32_e32 v214, 16, v65
	v_and_b32_e32 v215, 0xffff0000, v65
	v_lshlrev_b32_e32 v220, 16, v67
	v_and_b32_e32 v221, 0xffff0000, v67
	v_sub_f32_e32 v220, v220, v214
	v_sub_f32_e32 v221, v221, v215
	v_fmac_f32_e32 v214, v70, v220
	v_fmac_f32_e32 v215, v71, v221
	v_mul_f32_e32 v156, v212, v72
	v_mul_f32_e32 v157, v213, v73
	v_mul_f32_e32 v158, v214, v74
	v_mul_f32_e32 v159, v215, v75
	v_mul_f32_e32 v223, v156, v156
	v_fma_f32 v223, v157, v157, v223
	v_fma_f32 v223, v158, v158, v223
	v_fma_f32 v223, v159, v159, v223
	v_add_f32_e32 v222, v222, v223
	v_mov_b32_dpp v80, v80 row_newbcast:0 row_mask:0xf bank_mask:0xf
	v_mov_b32_dpp v81, v81 row_newbcast:0 row_mask:0xf bank_mask:0xf
	v_mov_b32_dpp v82, v82 row_newbcast:0 row_mask:0xf bank_mask:0xf
	v_mov_b32_dpp v83, v83 row_newbcast:0 row_mask:0xf bank_mask:0xf
	v_mov_b32_dpp v84, v84 row_newbcast:0 row_mask:0xf bank_mask:0xf
	v_mov_b32_dpp v85, v85 row_newbcast:0 row_mask:0xf bank_mask:0xf
	v_mov_b32_dpp v86, v86 row_newbcast:0 row_mask:0xf bank_mask:0xf
	v_mov_b32_dpp v87, v87 row_newbcast:0 row_mask:0xf bank_mask:0xf
	v_mov_b32_dpp v78, v76 row_shr:1 row_mask:0xf bank_mask:0xf
	v_mov_b32_dpp v79, v77 row_shr:1 row_mask:0xf bank_mask:0xf
	v_and_b32_e32 v78, v5, v78
	v_and_b32_e32 v79, v5, v79
	v_lshlrev_b32_e32 v216, 16, v76
	v_and_b32_e32 v217, 0xffff0000, v76
	v_lshlrev_b32_e32 v220, 16, v78
	v_and_b32_e32 v221, 0xffff0000, v78
	v_sub_f32_e32 v220, v220, v216
	v_sub_f32_e32 v221, v221, v217
	v_fmac_f32_e32 v216, v80, v220
	v_fmac_f32_e32 v217, v81, v221
	v_lshlrev_b32_e32 v218, 16, v77
	v_and_b32_e32 v219, 0xffff0000, v77
	v_lshlrev_b32_e32 v220, 16, v79
	v_and_b32_e32 v221, 0xffff0000, v79
	v_sub_f32_e32 v220, v220, v218
	v_sub_f32_e32 v221, v221, v219
	v_fmac_f32_e32 v218, v82, v220
	v_fmac_f32_e32 v219, v83, v221
	v_mul_f32_e32 v160, v216, v84
	v_mul_f32_e32 v161, v217, v85
	v_mul_f32_e32 v162, v218, v86
	v_mul_f32_e32 v163, v219, v87
	v_mul_f32_e32 v223, v160, v160
	v_fma_f32 v223, v161, v161, v223
	v_fma_f32 v223, v162, v162, v223
	v_fma_f32 v223, v163, v163, v223
	v_add_f32_e32 v222, v222, v223
	v_mov_b32_e32 v223, v222
	s_nop 1
	v_permlane16_swap_b32_e32 v222, v223
	s_nop 1
	v_add_f32_e32 v222, v222, v223
	v_mov_b32_e32 v223, v222
	s_nop 1
	v_permlane32_swap_b32_e32 v222, v223
	s_nop 1
	v_add_f32_e32 v222, v222, v223
	s_mov_b32 s34, 0xf800000
	v_cmp_gt_f32_e32 vcc, s34, v222
	v_mul_f32_e32 v220, 0x4f800000, v222
	s_nop 0
	v_cndmask_b32_e32 v222, v222, v220, vcc
	v_sqrt_f32_e32 v224, v222
	s_nop 0
	v_add_u32_e32 v225, -1, v224
	v_fma_f32 v226, -v225, v224, v222
	v_cmp_ge_f32_e64 s[62:63], 0, v226
	v_add_u32_e32 v227, 1, v224
	s_nop 0
	v_cndmask_b32_e64 v225, v224, v225, s[62:63]
	v_fma_f32 v226, -v227, v224, v222
	v_cmp_lt_f32_e64 s[62:63], 0, v226
	s_nop 1
	v_cndmask_b32_e64 v224, v225, v227, s[62:63]
	v_mul_f32_e32 v220, 0x37800000, v224
	v_cndmask_b32_e32 v224, v224, v220, vcc
	v_cmp_class_f32_e32 vcc, v222, v193
	s_nop 1
	v_cndmask_b32_e32 v222, v224, v222, vcc
	v_max_f32_e32 v222, 0x2b8cbccc, v222
	v_div_scale_f32 v224, s[62:63], v222, v222, 1.0
	v_rcp_f32_e32 v225, v224
	s_nop 0
	v_fma_f32 v226, -v224, v225, 1.0
	v_fmac_f32_e32 v225, v226, v225
	v_div_scale_f32 v227, vcc, 1.0, v222, 1.0
	v_mul_f32_e32 v220, v227, v225
	v_fma_f32 v221, -v224, v220, v227
	v_fmac_f32_e32 v220, v221, v225
	v_fma_f32 v224, -v224, v220, v227
	s_nop 1
	v_div_fmas_f32 v224, v224, v225, v220
	v_div_fixup_f32 v34, v224, v222, 1.0
	global_load_dwordx2 v[40:41], v2, s[40:41] offset:32
	global_load_dwordx2 v[48:49], v2, s[40:41] offset:2080
	global_load_dwordx4 v[56:59], v176, s[60:61] offset:2048
	global_load_dwordx4 v[60:63], v176, s[60:61] offset:2112
	global_load_dwordx4 v[64:67], v182, s[60:61] offset:2048
	global_load_dwordx4 v[68:71], v182, s[60:61] offset:2112
	global_load_dwordx4 v[72:75], v181, s[100:101] offset:1024
	global_load_dwordx2 v[146:147], v8, s[0:1] offset:32
	s_mov_b32 exec_lo, 0x10001
	s_mov_b32 exec_hi, 0x10001
	global_load_dwordx2 v[42:43], v2, s[42:43] offset:32
	global_load_dwordx2 v[50:51], v2, s[42:43] offset:2080
	global_load_dwordx4 v[44:47], v1, s[46:47] offset:-1984
	global_load_dwordx4 v[52:55], v1, s[46:47] offset:2112
	global_load_dwordx4 v[76:79], v1, s[50:51] offset:64
	global_load_dwordx4 v[80:83], v1, s[52:53] offset:64
	global_load_dwordx4 v[84:87], v1, s[58:59] offset:64
	global_load_dwordx4 v[142:145], v1, s[54:55] offset:64
	s_mov_b64 exec, -1
	s_waitcnt vmcnt(16)
	v_mov_b32_dpp v92, v92 row_newbcast:0 row_mask:0xf bank_mask:0xf
	v_mov_b32_dpp v93, v93 row_newbcast:0 row_mask:0xf bank_mask:0xf
	v_mov_b32_dpp v94, v94 row_newbcast:0 row_mask:0xf bank_mask:0xf
	v_mov_b32_dpp v95, v95 row_newbcast:0 row_mask:0xf bank_mask:0xf
	v_mov_b32_dpp v100, v100 row_newbcast:0 row_mask:0xf bank_mask:0xf
	v_mov_b32_dpp v101, v101 row_newbcast:0 row_mask:0xf bank_mask:0xf
	v_mov_b32_dpp v102, v102 row_newbcast:0 row_mask:0xf bank_mask:0xf
	v_mov_b32_dpp v103, v103 row_newbcast:0 row_mask:0xf bank_mask:0xf
	v_mov_b32_dpp v124, v124 row_newbcast:0 row_mask:0xf bank_mask:0xf
	v_mov_b32_dpp v125, v125 row_newbcast:0 row_mask:0xf bank_mask:0xf
	v_mov_b32_dpp v126, v126 row_newbcast:0 row_mask:0xf bank_mask:0xf
	v_mov_b32_dpp v127, v127 row_newbcast:0 row_mask:0xf bank_mask:0xf
	v_mov_b32_dpp v128, v128 row_newbcast:0 row_mask:0xf bank_mask:0xf
	v_mov_b32_dpp v129, v129 row_newbcast:0 row_mask:0xf bank_mask:0xf
	v_mov_b32_dpp v130, v130 row_newbcast:0 row_mask:0xf bank_mask:0xf
	v_mov_b32_dpp v131, v131 row_newbcast:0 row_mask:0xf bank_mask:0xf
	v_mov_b32_dpp v132, v132 row_newbcast:0 row_mask:0xf bank_mask:0xf
	v_mov_b32_dpp v133, v133 row_newbcast:0 row_mask:0xf bank_mask:0xf
	v_mov_b32_dpp v134, v134 row_newbcast:0 row_mask:0xf bank_mask:0xf
	v_mov_b32_dpp v135, v135 row_newbcast:0 row_mask:0xf bank_mask:0xf
	v_mov_b32_dpp v136, v136 row_newbcast:0 row_mask:0xf bank_mask:0xf
	v_mov_b32_dpp v137, v137 row_newbcast:0 row_mask:0xf bank_mask:0xf
	v_mov_b32_dpp v138, v138 row_newbcast:0 row_mask:0xf bank_mask:0xf
	v_mov_b32_dpp v139, v139 row_newbcast:0 row_mask:0xf bank_mask:0xf
	s_nop 1
	v_mfma_f32_16x16x32_bf16 v[164:167], v[104:107], v[12:15], 0
	v_mfma_f32_16x16x32_bf16 v[168:171], v[112:115], v[20:23], 0
	v_mfma_f32_16x16x32_bf16 v[172:175], v[120:123], v[28:31], 0
	v_mfma_f32_16x16x32_bf16 v[164:167], v[108:111], v[16:19], v[164:167]
	v_mfma_f32_16x16x32_bf16 v[168:171], v[116:119], v[24:27], v[168:171]
	v_mov_b32_dpp v90, v88 row_shr:1 row_mask:0xf bank_mask:0xf
	v_mov_b32_dpp v91, v89 row_shr:1 row_mask:0xf bank_mask:0xf
	v_and_b32_e32 v90, v5, v90
	v_and_b32_e32 v91, v5, v91
	v_lshlrev_b32_e32 v184, 16, v88
	v_and_b32_e32 v185, 0xffff0000, v88
	v_lshlrev_b32_e32 v220, 16, v90
	v_and_b32_e32 v221, 0xffff0000, v90
	v_sub_f32_e32 v220, v220, v184
	v_sub_f32_e32 v221, v221, v185
	v_fmac_f32_e32 v184, v92, v220
	v_fmac_f32_e32 v185, v93, v221
	v_lshlrev_b32_e32 v186, 16, v89
	v_and_b32_e32 v187, 0xffff0000, v89
	v_lshlrev_b32_e32 v220, 16, v91
	v_and_b32_e32 v221, 0xffff0000, v91
	v_sub_f32_e32 v220, v220, v186
	v_sub_f32_e32 v221, v221, v187
	v_fmac_f32_e32 v186, v94, v220
	v_fmac_f32_e32 v187, v95, v221
	v_mov_b32_dpp v98, v96 row_shr:1 row_mask:0xf bank_mask:0xf
	v_mov_b32_dpp v99, v97 row_shr:1 row_mask:0xf bank_mask:0xf
	v_and_b32_e32 v98, v5, v98
	v_and_b32_e32 v99, v5, v99
	v_lshlrev_b32_e32 v228, 16, v96
	v_and_b32_e32 v229, 0xffff0000, v96
	v_lshlrev_b32_e32 v220, 16, v98
	v_and_b32_e32 v221, 0xffff0000, v98
	v_sub_f32_e32 v220, v220, v228
	v_sub_f32_e32 v221, v221, v229
	v_fmac_f32_e32 v228, v100, v220
	v_fmac_f32_e32 v229, v101, v221
	v_lshlrev_b32_e32 v230, 16, v97
	v_and_b32_e32 v231, 0xffff0000, v97
	v_lshlrev_b32_e32 v220, 16, v99
	v_and_b32_e32 v221, 0xffff0000, v99
	v_sub_f32_e32 v220, v220, v230
	v_sub_f32_e32 v221, v221, v231
	v_fmac_f32_e32 v230, v102, v220
	v_fmac_f32_e32 v231, v103, v221
	s_nop 7
	v_add_f32_e32 v164, v124, v164
	v_add_f32_e32 v168, v128, v168
	v_add_f32_e32 v172, v136, v172
	v_add_f32_e32 v165, v125, v165
	v_add_f32_e32 v169, v129, v169
	v_add_f32_e32 v173, v137, v173
	v_add_f32_e32 v166, v126, v166
	v_add_f32_e32 v170, v130, v170
	v_add_f32_e32 v174, v138, v174
	v_add_f32_e32 v167, v127, v167
	v_add_f32_e32 v171, v131, v171
	v_add_f32_e32 v175, v139, v175
	v_mul_f32_e32 v164, 0xbfb8aa3b, v164
	v_exp_f32_e32 v164, v164
	s_nop 0
	v_add_f32_e32 v164, 1.0, v164
	v_rcp_f32_e32 v164, v164
	v_mul_f32_e32 v168, 0xbfb8aa3b, v168
	v_exp_f32_e32 v168, v168
	s_nop 0
	v_add_f32_e32 v168, 1.0, v168
	v_rcp_f32_e32 v168, v168
	v_mul_f32_e32 v172, 0xbfb8aa3b, v172
	v_exp_f32_e32 v172, v172
	s_nop 0
	v_add_f32_e32 v172, 1.0, v172
	v_rcp_f32_e32 v172, v172
	v_mul_f32_e32 v165, 0xbfb8aa3b, v165
	v_exp_f32_e32 v165, v165
	s_nop 0
	v_add_f32_e32 v165, 1.0, v165
	v_rcp_f32_e32 v165, v165
	v_mul_f32_e32 v169, 0xbfb8aa3b, v169
	v_exp_f32_e32 v169, v169
	s_nop 0
	v_add_f32_e32 v169, 1.0, v169
	v_rcp_f32_e32 v169, v169
	v_mul_f32_e32 v173, 0xbfb8aa3b, v173
	v_exp_f32_e32 v173, v173
	s_nop 0
	v_add_f32_e32 v173, 1.0, v173
	v_rcp_f32_e32 v173, v173
	v_mul_f32_e32 v166, 0xbfb8aa3b, v166
	v_exp_f32_e32 v166, v166
	s_nop 0
	v_add_f32_e32 v166, 1.0, v166
	v_rcp_f32_e32 v166, v166
	v_mul_f32_e32 v170, 0xbfb8aa3b, v170
	v_exp_f32_e32 v170, v170
	s_nop 0
	v_add_f32_e32 v170, 1.0, v170
	v_rcp_f32_e32 v170, v170
	v_mul_f32_e32 v174, 0xbfb8aa3b, v174
	v_exp_f32_e32 v174, v174
	s_nop 0
	v_add_f32_e32 v174, 1.0, v174
	v_rcp_f32_e32 v174, v174
	v_mul_f32_e32 v167, 0xbfb8aa3b, v167
	v_exp_f32_e32 v167, v167
	s_nop 0
	v_add_f32_e32 v167, 1.0, v167
	v_rcp_f32_e32 v167, v167
	v_mul_f32_e32 v171, 0xbfb8aa3b, v171
	v_exp_f32_e32 v171, v171
	s_nop 0
	v_add_f32_e32 v171, 1.0, v171
	v_rcp_f32_e32 v171, v171
	v_mul_f32_e32 v175, 0xbfb8aa3b, v175
	v_exp_f32_e32 v175, v175
	s_nop 0
	v_add_f32_e32 v175, 1.0, v175
	v_rcp_f32_e32 v175, v175
	v_mul_f32_e32 v164, 0x3f1b4598, v164
	v_mul_f32_e32 v165, 0x3f1b4598, v165
	v_mul_f32_e32 v166, 0x3f1b4598, v166
	v_mul_f32_e32 v167, 0x3f1b4598, v167
	s_cmp_eq_u32 s32, 0
	s_cbranch_scc1 .Lprep2_l0_0_0
	v_lshlrev_b32_e32 v220, 16, v140
	v_and_b32_e32 v221, 0xffff0000, v140
	v_lshlrev_b32_e32 v222, 16, v141
	v_and_b32_e32 v223, 0xffff0000, v141
	v_sub_f32_e32 v220, v220, v228
	v_fmac_f32_e32 v228, v220, v172
	v_sub_f32_e32 v221, v221, v229
	v_fmac_f32_e32 v229, v221, v173
	v_sub_f32_e32 v222, v222, v230
	v_fmac_f32_e32 v230, v222, v174
	v_sub_f32_e32 v223, v223, v231
	v_fmac_f32_e32 v231, v223, v175
	s_branch .Lprep2_l0d_0_0

.Lprep2_l0d_0_0:
	global_store_dwordx2 v8, v[140:141], s[0:1] offset:0
	v_mul_f32_e32 v220, v148, v34
	v_mul_f32_e32 v224, v220, v168
	v_add_f32_e32 v168, -1.0, v168
	v_fma_f32 v168, v168, v132, 1.0
	v_mul_f32_e32 v168, v204, v168
	v_mul_f32_e32 v221, v149, v34
	v_mul_f32_e32 v225, v221, v169
	v_add_f32_e32 v169, -1.0, v169
	v_fma_f32 v169, v169, v133, 1.0
	v_mul_f32_e32 v169, v205, v169
	v_mul_f32_e32 v222, v150, v34
	v_mul_f32_e32 v226, v222, v170
	v_add_f32_e32 v170, -1.0, v170
	v_fma_f32 v170, v170, v134, 1.0
	v_mul_f32_e32 v170, v206, v170
	v_mul_f32_e32 v223, v151, v34
	v_mul_f32_e32 v227, v223, v171
	v_add_f32_e32 v171, -1.0, v171
	v_fma_f32 v171, v171, v135, 1.0
	v_mul_f32_e32 v171, v207, v171
	v_cvt_pk_bf16_f32 v88, v184, v185
	v_cvt_pk_bf16_f32 v89, v186, v187
	ds_write_b64 v9, v[88:89] offset:0
	v_cvt_pk_bf16_f32 v88, v168, v169
	v_cvt_pk_bf16_f32 v89, v170, v171
	ds_write_b64 v9, v[88:89] offset:2304
	v_cvt_pk_bf16_f32 v88, v228, v229
	v_cvt_pk_bf16_f32 v89, v230, v231
	ds_write_b64 v9, v[88:89] offset:4608
	v_cvt_pk_bf16_f32 v88, v220, v221
	v_cvt_pk_bf16_f32 v89, v222, v223
	ds_write_b64 v9, v[88:89] offset:6912
	v_cvt_pk_bf16_f32 v88, v224, v225
	v_cvt_pk_bf16_f32 v89, v226, v227
	ds_write_b64 v9, v[88:89] offset:9216
	v_cvt_pk_bf16_f32 v88, v164, v165
	v_cvt_pk_bf16_f32 v89, v166, v167
	ds_write_b64 v9, v[88:89] offset:11520
	global_load_dwordx2 v[88:89], v2, s[40:41] offset:64
	global_load_dwordx2 v[96:97], v2, s[40:41] offset:2112
	global_load_dwordx4 v[104:107], v177, s[60:61] offset:0
	global_load_dwordx4 v[108:111], v177, s[60:61] offset:64
	global_load_dwordx4 v[112:115], v183, s[60:61] offset:0
	global_load_dwordx4 v[116:119], v183, s[60:61] offset:64
	global_load_dwordx4 v[120:123], v181, s[100:101] offset:2048
	global_load_dwordx2 v[140:141], v8, s[0:1] offset:64
	s_mov_b32 exec_lo, 0x10001
	s_mov_b32 exec_hi, 0x10001
	global_load_dwordx2 v[90:91], v2, s[42:43] offset:64
	global_load_dwordx2 v[98:99], v2, s[42:43] offset:2112
	global_load_dwordx4 v[92:95], v1, s[46:47] offset:-1920
	global_load_dwordx4 v[100:103], v1, s[46:47] offset:2176
	global_load_dwordx4 v[124:127], v1, s[50:51] offset:128
	global_load_dwordx4 v[128:131], v1, s[52:53] offset:128
	global_load_dwordx4 v[132:135], v1, s[58:59] offset:128
	global_load_dwordx4 v[136:139], v1, s[54:55] offset:128
	s_mov_b64 exec, -1
	s_waitcnt vmcnt(17)
	v_mov_b32_dpp v44, v44 row_newbcast:0 row_mask:0xf bank_mask:0xf
	v_mov_b32_dpp v45, v45 row_newbcast:0 row_mask:0xf bank_mask:0xf
	v_mov_b32_dpp v46, v46 row_newbcast:0 row_mask:0xf bank_mask:0xf
	v_mov_b32_dpp v47, v47 row_newbcast:0 row_mask:0xf bank_mask:0xf
	v_mov_b32_dpp v52, v52 row_newbcast:0 row_mask:0xf bank_mask:0xf
	v_mov_b32_dpp v53, v53 row_newbcast:0 row_mask:0xf bank_mask:0xf
	v_mov_b32_dpp v54, v54 row_newbcast:0 row_mask:0xf bank_mask:0xf
	v_mov_b32_dpp v55, v55 row_newbcast:0 row_mask:0xf bank_mask:0xf
	v_mov_b32_dpp v76, v76 row_newbcast:0 row_mask:0xf bank_mask:0xf
	v_mov_b32_dpp v77, v77 row_newbcast:0 row_mask:0xf bank_mask:0xf
	v_mov_b32_dpp v78, v78 row_newbcast:0 row_mask:0xf bank_mask:0xf
	v_mov_b32_dpp v79, v79 row_newbcast:0 row_mask:0xf bank_mask:0xf
	v_mov_b32_dpp v80, v80 row_newbcast:0 row_mask:0xf bank_mask:0xf
	v_mov_b32_dpp v81, v81 row_newbcast:0 row_mask:0xf bank_mask:0xf
	v_mov_b32_dpp v82, v82 row_newbcast:0 row_mask:0xf bank_mask:0xf
	v_mov_b32_dpp v83, v83 row_newbcast:0 row_mask:0xf bank_mask:0xf
	v_mov_b32_dpp v84, v84 row_newbcast:0 row_mask:0xf bank_mask:0xf
	v_mov_b32_dpp v85, v85 row_newbcast:0 row_mask:0xf bank_mask:0xf
	v_mov_b32_dpp v86, v86 row_newbcast:0 row_mask:0xf bank_mask:0xf
	v_mov_b32_dpp v87, v87 row_newbcast:0 row_mask:0xf bank_mask:0xf
	v_mov_b32_dpp v142, v142 row_newbcast:0 row_mask:0xf bank_mask:0xf
	v_mov_b32_dpp v143, v143 row_newbcast:0 row_mask:0xf bank_mask:0xf
	v_mov_b32_dpp v144, v144 row_newbcast:0 row_mask:0xf bank_mask:0xf
	v_mov_b32_dpp v145, v145 row_newbcast:0 row_mask:0xf bank_mask:0xf
	s_nop 1
	v_mfma_f32_16x16x32_bf16 v[164:167], v[56:59], v[12:15], 0
	v_mfma_f32_16x16x32_bf16 v[168:171], v[64:67], v[20:23], 0
	v_mfma_f32_16x16x32_bf16 v[172:175], v[72:75], v[28:31], 0
	v_mfma_f32_16x16x32_bf16 v[164:167], v[60:63], v[16:19], v[164:167]
	v_mfma_f32_16x16x32_bf16 v[168:171], v[68:71], v[24:27], v[168:171]
	v_mov_b32_dpp v42, v40 row_shr:1 row_mask:0xf bank_mask:0xf
	v_mov_b32_dpp v43, v41 row_shr:1 row_mask:0xf bank_mask:0xf
	v_and_b32_e32 v42, v5, v42
	v_and_b32_e32 v43, v5, v43
	v_lshlrev_b32_e32 v184, 16, v40
	v_and_b32_e32 v185, 0xffff0000, v40
	v_lshlrev_b32_e32 v220, 16, v42
	v_and_b32_e32 v221, 0xffff0000, v42
	v_sub_f32_e32 v220, v220, v184
	v_sub_f32_e32 v221, v221, v185
	v_fmac_f32_e32 v184, v44, v220
	v_fmac_f32_e32 v185, v45, v221
	v_lshlrev_b32_e32 v186, 16, v41
	v_and_b32_e32 v187, 0xffff0000, v41
	v_lshlrev_b32_e32 v220, 16, v43
	v_and_b32_e32 v221, 0xffff0000, v43
	v_sub_f32_e32 v220, v220, v186
	v_sub_f32_e32 v221, v221, v187
	v_fmac_f32_e32 v186, v46, v220
	v_fmac_f32_e32 v187, v47, v221
	v_mov_b32_dpp v50, v48 row_shr:1 row_mask:0xf bank_mask:0xf
	v_mov_b32_dpp v51, v49 row_shr:1 row_mask:0xf bank_mask:0xf
	v_and_b32_e32 v50, v5, v50
	v_and_b32_e32 v51, v5, v51
	v_lshlrev_b32_e32 v228, 16, v48
	v_and_b32_e32 v229, 0xffff0000, v48
	v_lshlrev_b32_e32 v220, 16, v50
	v_and_b32_e32 v221, 0xffff0000, v50
	v_sub_f32_e32 v220, v220, v228
	v_sub_f32_e32 v221, v221, v229
	v_fmac_f32_e32 v228, v52, v220
	v_fmac_f32_e32 v229, v53, v221
	v_lshlrev_b32_e32 v230, 16, v49
	v_and_b32_e32 v231, 0xffff0000, v49
	v_lshlrev_b32_e32 v220, 16, v51
	v_and_b32_e32 v221, 0xffff0000, v51
	v_sub_f32_e32 v220, v220, v230
	v_sub_f32_e32 v221, v221, v231
	v_fmac_f32_e32 v230, v54, v220
	v_fmac_f32_e32 v231, v55, v221
	s_nop 7
	v_add_f32_e32 v164, v76, v164
	v_add_f32_e32 v168, v80, v168
	v_add_f32_e32 v172, v142, v172
	v_add_f32_e32 v165, v77, v165
	v_add_f32_e32 v169, v81, v169
	v_add_f32_e32 v173, v143, v173
	v_add_f32_e32 v166, v78, v166
	v_add_f32_e32 v170, v82, v170
	v_add_f32_e32 v174, v144, v174
	v_add_f32_e32 v167, v79, v167
	v_add_f32_e32 v171, v83, v171
	v_add_f32_e32 v175, v145, v175
	v_mul_f32_e32 v164, 0xbfb8aa3b, v164
	v_exp_f32_e32 v164, v164
	s_nop 0
	v_add_f32_e32 v164, 1.0, v164
	v_rcp_f32_e32 v164, v164
	v_mul_f32_e32 v168, 0xbfb8aa3b, v168
	v_exp_f32_e32 v168, v168
	s_nop 0
	v_add_f32_e32 v168, 1.0, v168
	v_rcp_f32_e32 v168, v168
	v_mul_f32_e32 v172, 0xbfb8aa3b, v172
	v_exp_f32_e32 v172, v172
	s_nop 0
	v_add_f32_e32 v172, 1.0, v172
	v_rcp_f32_e32 v172, v172
	v_mul_f32_e32 v165, 0xbfb8aa3b, v165
	v_exp_f32_e32 v165, v165
	s_nop 0
	v_add_f32_e32 v165, 1.0, v165
	v_rcp_f32_e32 v165, v165
	v_mul_f32_e32 v169, 0xbfb8aa3b, v169
	v_exp_f32_e32 v169, v169
	s_nop 0
	v_add_f32_e32 v169, 1.0, v169
	v_rcp_f32_e32 v169, v169
	v_mul_f32_e32 v173, 0xbfb8aa3b, v173
	v_exp_f32_e32 v173, v173
	s_nop 0
	v_add_f32_e32 v173, 1.0, v173
	v_rcp_f32_e32 v173, v173
	v_mul_f32_e32 v166, 0xbfb8aa3b, v166
	v_exp_f32_e32 v166, v166
	s_nop 0
	v_add_f32_e32 v166, 1.0, v166
	v_rcp_f32_e32 v166, v166
	v_mul_f32_e32 v170, 0xbfb8aa3b, v170
	v_exp_f32_e32 v170, v170
	s_nop 0
	v_add_f32_e32 v170, 1.0, v170
	v_rcp_f32_e32 v170, v170
	v_mul_f32_e32 v174, 0xbfb8aa3b, v174
	v_exp_f32_e32 v174, v174
	s_nop 0
	v_add_f32_e32 v174, 1.0, v174
	v_rcp_f32_e32 v174, v174
	v_mul_f32_e32 v167, 0xbfb8aa3b, v167
	v_exp_f32_e32 v167, v167
	s_nop 0
	v_add_f32_e32 v167, 1.0, v167
	v_rcp_f32_e32 v167, v167
	v_mul_f32_e32 v171, 0xbfb8aa3b, v171
	v_exp_f32_e32 v171, v171
	s_nop 0
	v_add_f32_e32 v171, 1.0, v171
	v_rcp_f32_e32 v171, v171
	v_mul_f32_e32 v175, 0xbfb8aa3b, v175
	v_exp_f32_e32 v175, v175
	s_nop 0
	v_add_f32_e32 v175, 1.0, v175
	v_rcp_f32_e32 v175, v175
	v_mul_f32_e32 v164, 0x3f1b4598, v164
	v_mul_f32_e32 v165, 0x3f1b4598, v165
	v_mul_f32_e32 v166, 0x3f1b4598, v166
	v_mul_f32_e32 v167, 0x3f1b4598, v167
	s_cmp_eq_u32 s32, 0
	s_cbranch_scc1 .Lprep2_l0_0_1
	v_lshlrev_b32_e32 v220, 16, v146
	v_and_b32_e32 v221, 0xffff0000, v146
	v_lshlrev_b32_e32 v222, 16, v147
	v_and_b32_e32 v223, 0xffff0000, v147
	v_sub_f32_e32 v220, v220, v228
	v_fmac_f32_e32 v228, v220, v172
	v_sub_f32_e32 v221, v221, v229
	v_fmac_f32_e32 v229, v221, v173
	v_sub_f32_e32 v222, v222, v230
	v_fmac_f32_e32 v230, v222, v174
	v_sub_f32_e32 v223, v223, v231
	v_fmac_f32_e32 v231, v223, v175
	s_branch .Lprep2_l0d_0_1

.Lprep2_l0d_0_1:
	global_store_dwordx2 v8, v[146:147], s[0:1] offset:32
	v_mul_f32_e32 v220, v152, v34
	v_mul_f32_e32 v224, v220, v168
	v_add_f32_e32 v168, -1.0, v168
	v_fma_f32 v168, v168, v84, 1.0
	v_mul_f32_e32 v168, v208, v168
	v_mul_f32_e32 v221, v153, v34
	v_mul_f32_e32 v225, v221, v169
	v_add_f32_e32 v169, -1.0, v169
	v_fma_f32 v169, v169, v85, 1.0
	v_mul_f32_e32 v169, v209, v169
	v_mul_f32_e32 v222, v154, v34
	v_mul_f32_e32 v226, v222, v170
	v_add_f32_e32 v170, -1.0, v170
	v_fma_f32 v170, v170, v86, 1.0
	v_mul_f32_e32 v170, v210, v170
	v_mul_f32_e32 v223, v155, v34
	v_mul_f32_e32 v227, v223, v171
	v_add_f32_e32 v171, -1.0, v171
	v_fma_f32 v171, v171, v87, 1.0
	v_mul_f32_e32 v171, v211, v171
	v_cvt_pk_bf16_f32 v40, v184, v185
	v_cvt_pk_bf16_f32 v41, v186, v187
	ds_write_b64 v9, v[40:41] offset:32
	v_cvt_pk_bf16_f32 v40, v168, v169
	v_cvt_pk_bf16_f32 v41, v170, v171
	ds_write_b64 v9, v[40:41] offset:2336
	v_cvt_pk_bf16_f32 v40, v228, v229
	v_cvt_pk_bf16_f32 v41, v230, v231
	ds_write_b64 v9, v[40:41] offset:4640
	v_cvt_pk_bf16_f32 v40, v220, v221
	v_cvt_pk_bf16_f32 v41, v222, v223
	ds_write_b64 v9, v[40:41] offset:6944
	v_cvt_pk_bf16_f32 v40, v224, v225
	v_cvt_pk_bf16_f32 v41, v226, v227
	ds_write_b64 v9, v[40:41] offset:9248
	v_cvt_pk_bf16_f32 v40, v164, v165
	v_cvt_pk_bf16_f32 v41, v166, v167
	ds_write_b64 v9, v[40:41] offset:11552
	global_load_dwordx2 v[40:41], v2, s[40:41] offset:96
	global_load_dwordx2 v[48:49], v2, s[40:41] offset:2144
	global_load_dwordx4 v[56:59], v177, s[60:61] offset:2048
	global_load_dwordx4 v[60:63], v177, s[60:61] offset:2112
	global_load_dwordx4 v[64:67], v183, s[60:61] offset:2048
	global_load_dwordx4 v[68:71], v183, s[60:61] offset:2112
	global_load_dwordx4 v[72:75], v181, s[100:101] offset:3072
	global_load_dwordx2 v[146:147], v8, s[0:1] offset:96
	s_mov_b32 exec_lo, 0x10001
	s_mov_b32 exec_hi, 0x10001
	global_load_dwordx2 v[42:43], v2, s[42:43] offset:96
	global_load_dwordx2 v[50:51], v2, s[42:43] offset:2144
	global_load_dwordx4 v[44:47], v1, s[46:47] offset:-1856
	global_load_dwordx4 v[52:55], v1, s[46:47] offset:2240
	global_load_dwordx4 v[76:79], v1, s[50:51] offset:192
	global_load_dwordx4 v[80:83], v1, s[52:53] offset:192
	global_load_dwordx4 v[84:87], v1, s[58:59] offset:192
	global_load_dwordx4 v[142:145], v1, s[54:55] offset:192
	s_mov_b64 exec, -1
	s_waitcnt vmcnt(17)
	v_mov_b32_dpp v92, v92 row_newbcast:0 row_mask:0xf bank_mask:0xf
	v_mov_b32_dpp v93, v93 row_newbcast:0 row_mask:0xf bank_mask:0xf
	v_mov_b32_dpp v94, v94 row_newbcast:0 row_mask:0xf bank_mask:0xf
	v_mov_b32_dpp v95, v95 row_newbcast:0 row_mask:0xf bank_mask:0xf
	v_mov_b32_dpp v100, v100 row_newbcast:0 row_mask:0xf bank_mask:0xf
	v_mov_b32_dpp v101, v101 row_newbcast:0 row_mask:0xf bank_mask:0xf
	v_mov_b32_dpp v102, v102 row_newbcast:0 row_mask:0xf bank_mask:0xf
	v_mov_b32_dpp v103, v103 row_newbcast:0 row_mask:0xf bank_mask:0xf
	v_mov_b32_dpp v124, v124 row_newbcast:0 row_mask:0xf bank_mask:0xf
	v_mov_b32_dpp v125, v125 row_newbcast:0 row_mask:0xf bank_mask:0xf
	v_mov_b32_dpp v126, v126 row_newbcast:0 row_mask:0xf bank_mask:0xf
	v_mov_b32_dpp v127, v127 row_newbcast:0 row_mask:0xf bank_mask:0xf
	v_mov_b32_dpp v128, v128 row_newbcast:0 row_mask:0xf bank_mask:0xf
	v_mov_b32_dpp v129, v129 row_newbcast:0 row_mask:0xf bank_mask:0xf
	v_mov_b32_dpp v130, v130 row_newbcast:0 row_mask:0xf bank_mask:0xf
	v_mov_b32_dpp v131, v131 row_newbcast:0 row_mask:0xf bank_mask:0xf
	v_mov_b32_dpp v132, v132 row_newbcast:0 row_mask:0xf bank_mask:0xf
	v_mov_b32_dpp v133, v133 row_newbcast:0 row_mask:0xf bank_mask:0xf
	v_mov_b32_dpp v134, v134 row_newbcast:0 row_mask:0xf bank_mask:0xf
	v_mov_b32_dpp v135, v135 row_newbcast:0 row_mask:0xf bank_mask:0xf
	v_mov_b32_dpp v136, v136 row_newbcast:0 row_mask:0xf bank_mask:0xf
	v_mov_b32_dpp v137, v137 row_newbcast:0 row_mask:0xf bank_mask:0xf
	v_mov_b32_dpp v138, v138 row_newbcast:0 row_mask:0xf bank_mask:0xf
	v_mov_b32_dpp v139, v139 row_newbcast:0 row_mask:0xf bank_mask:0xf
	s_nop 1
	v_mfma_f32_16x16x32_bf16 v[164:167], v[104:107], v[12:15], 0
	v_mfma_f32_16x16x32_bf16 v[168:171], v[112:115], v[20:23], 0
	v_mfma_f32_16x16x32_bf16 v[172:175], v[120:123], v[28:31], 0
	v_mfma_f32_16x16x32_bf16 v[164:167], v[108:111], v[16:19], v[164:167]
	v_mfma_f32_16x16x32_bf16 v[168:171], v[116:119], v[24:27], v[168:171]
	v_mov_b32_dpp v90, v88 row_shr:1 row_mask:0xf bank_mask:0xf
	v_mov_b32_dpp v91, v89 row_shr:1 row_mask:0xf bank_mask:0xf
	v_and_b32_e32 v90, v5, v90
	v_and_b32_e32 v91, v5, v91
	v_lshlrev_b32_e32 v184, 16, v88
	v_and_b32_e32 v185, 0xffff0000, v88
	v_lshlrev_b32_e32 v220, 16, v90
	v_and_b32_e32 v221, 0xffff0000, v90
	v_sub_f32_e32 v220, v220, v184
	v_sub_f32_e32 v221, v221, v185
	v_fmac_f32_e32 v184, v92, v220
	v_fmac_f32_e32 v185, v93, v221
	v_lshlrev_b32_e32 v186, 16, v89
	v_and_b32_e32 v187, 0xffff0000, v89
	v_lshlrev_b32_e32 v220, 16, v91
	v_and_b32_e32 v221, 0xffff0000, v91
	v_sub_f32_e32 v220, v220, v186
	v_sub_f32_e32 v221, v221, v187
	v_fmac_f32_e32 v186, v94, v220
	v_fmac_f32_e32 v187, v95, v221
	v_mov_b32_dpp v98, v96 row_shr:1 row_mask:0xf bank_mask:0xf
	v_mov_b32_dpp v99, v97 row_shr:1 row_mask:0xf bank_mask:0xf
	v_and_b32_e32 v98, v5, v98
	v_and_b32_e32 v99, v5, v99
	v_lshlrev_b32_e32 v228, 16, v96
	v_and_b32_e32 v229, 0xffff0000, v96
	v_lshlrev_b32_e32 v220, 16, v98
	v_and_b32_e32 v221, 0xffff0000, v98
	v_sub_f32_e32 v220, v220, v228
	v_sub_f32_e32 v221, v221, v229
	v_fmac_f32_e32 v228, v100, v220
	v_fmac_f32_e32 v229, v101, v221
	v_lshlrev_b32_e32 v230, 16, v97
	v_and_b32_e32 v231, 0xffff0000, v97
	v_lshlrev_b32_e32 v220, 16, v99
	v_and_b32_e32 v221, 0xffff0000, v99
	v_sub_f32_e32 v220, v220, v230
	v_sub_f32_e32 v221, v221, v231
	v_fmac_f32_e32 v230, v102, v220
	v_fmac_f32_e32 v231, v103, v221
	s_nop 7
	v_add_f32_e32 v164, v124, v164
	v_add_f32_e32 v168, v128, v168
	v_add_f32_e32 v172, v136, v172
	v_add_f32_e32 v165, v125, v165
	v_add_f32_e32 v169, v129, v169
	v_add_f32_e32 v173, v137, v173
	v_add_f32_e32 v166, v126, v166
	v_add_f32_e32 v170, v130, v170
	v_add_f32_e32 v174, v138, v174
	v_add_f32_e32 v167, v127, v167
	v_add_f32_e32 v171, v131, v171
	v_add_f32_e32 v175, v139, v175
	v_mul_f32_e32 v164, 0xbfb8aa3b, v164
	v_exp_f32_e32 v164, v164
	s_nop 0
	v_add_f32_e32 v164, 1.0, v164
	v_rcp_f32_e32 v164, v164
	v_mul_f32_e32 v168, 0xbfb8aa3b, v168
	v_exp_f32_e32 v168, v168
	s_nop 0
	v_add_f32_e32 v168, 1.0, v168
	v_rcp_f32_e32 v168, v168
	v_mul_f32_e32 v172, 0xbfb8aa3b, v172
	v_exp_f32_e32 v172, v172
	s_nop 0
	v_add_f32_e32 v172, 1.0, v172
	v_rcp_f32_e32 v172, v172
	v_mul_f32_e32 v165, 0xbfb8aa3b, v165
	v_exp_f32_e32 v165, v165
	s_nop 0
	v_add_f32_e32 v165, 1.0, v165
	v_rcp_f32_e32 v165, v165
	v_mul_f32_e32 v169, 0xbfb8aa3b, v169
	v_exp_f32_e32 v169, v169
	s_nop 0
	v_add_f32_e32 v169, 1.0, v169
	v_rcp_f32_e32 v169, v169
	v_mul_f32_e32 v173, 0xbfb8aa3b, v173
	v_exp_f32_e32 v173, v173
	s_nop 0
	v_add_f32_e32 v173, 1.0, v173
	v_rcp_f32_e32 v173, v173
	v_mul_f32_e32 v166, 0xbfb8aa3b, v166
	v_exp_f32_e32 v166, v166
	s_nop 0
	v_add_f32_e32 v166, 1.0, v166
	v_rcp_f32_e32 v166, v166
	v_mul_f32_e32 v170, 0xbfb8aa3b, v170
	v_exp_f32_e32 v170, v170
	s_nop 0
	v_add_f32_e32 v170, 1.0, v170
	v_rcp_f32_e32 v170, v170
	v_mul_f32_e32 v174, 0xbfb8aa3b, v174
	v_exp_f32_e32 v174, v174
	s_nop 0
	v_add_f32_e32 v174, 1.0, v174
	v_rcp_f32_e32 v174, v174
	v_mul_f32_e32 v167, 0xbfb8aa3b, v167
	v_exp_f32_e32 v167, v167
	s_nop 0
	v_add_f32_e32 v167, 1.0, v167
	v_rcp_f32_e32 v167, v167
	v_mul_f32_e32 v171, 0xbfb8aa3b, v171
	v_exp_f32_e32 v171, v171
	s_nop 0
	v_add_f32_e32 v171, 1.0, v171
	v_rcp_f32_e32 v171, v171
	v_mul_f32_e32 v175, 0xbfb8aa3b, v175
	v_exp_f32_e32 v175, v175
	s_nop 0
	v_add_f32_e32 v175, 1.0, v175
	v_rcp_f32_e32 v175, v175
	v_mul_f32_e32 v164, 0x3f1b4598, v164
	v_mul_f32_e32 v165, 0x3f1b4598, v165
	v_mul_f32_e32 v166, 0x3f1b4598, v166
	v_mul_f32_e32 v167, 0x3f1b4598, v167
	s_cmp_eq_u32 s32, 0
	s_cbranch_scc1 .Lprep2_l0_0_2
	v_lshlrev_b32_e32 v220, 16, v140
	v_and_b32_e32 v221, 0xffff0000, v140
	v_lshlrev_b32_e32 v222, 16, v141
	v_and_b32_e32 v223, 0xffff0000, v141
	v_sub_f32_e32 v220, v220, v228
	v_fmac_f32_e32 v228, v220, v172
	v_sub_f32_e32 v221, v221, v229
	v_fmac_f32_e32 v229, v221, v173
	v_sub_f32_e32 v222, v222, v230
	v_fmac_f32_e32 v230, v222, v174
	v_sub_f32_e32 v223, v223, v231
	v_fmac_f32_e32 v231, v223, v175
	s_branch .Lprep2_l0d_0_2

.Lprep2_l0d_0_2:
	global_store_dwordx2 v8, v[140:141], s[0:1] offset:64
	v_mul_f32_e32 v220, v156, v34
	v_mul_f32_e32 v224, v220, v168
	v_add_f32_e32 v168, -1.0, v168
	v_fma_f32 v168, v168, v132, 1.0
	v_mul_f32_e32 v168, v212, v168
	v_mul_f32_e32 v221, v157, v34
	v_mul_f32_e32 v225, v221, v169
	v_add_f32_e32 v169, -1.0, v169
	v_fma_f32 v169, v169, v133, 1.0
	v_mul_f32_e32 v169, v213, v169
	v_mul_f32_e32 v222, v158, v34
	v_mul_f32_e32 v226, v222, v170
	v_add_f32_e32 v170, -1.0, v170
	v_fma_f32 v170, v170, v134, 1.0
	v_mul_f32_e32 v170, v214, v170
	v_mul_f32_e32 v223, v159, v34
	v_mul_f32_e32 v227, v223, v171
	v_add_f32_e32 v171, -1.0, v171
	v_fma_f32 v171, v171, v135, 1.0
	v_mul_f32_e32 v171, v215, v171
	v_cvt_pk_bf16_f32 v88, v184, v185
	v_cvt_pk_bf16_f32 v89, v186, v187
	ds_write_b64 v9, v[88:89] offset:64
	v_cvt_pk_bf16_f32 v88, v168, v169
	v_cvt_pk_bf16_f32 v89, v170, v171
	ds_write_b64 v9, v[88:89] offset:2368
	v_cvt_pk_bf16_f32 v88, v228, v229
	v_cvt_pk_bf16_f32 v89, v230, v231
	ds_write_b64 v9, v[88:89] offset:4672
	v_cvt_pk_bf16_f32 v88, v220, v221
	v_cvt_pk_bf16_f32 v89, v222, v223
	ds_write_b64 v9, v[88:89] offset:6976
	v_cvt_pk_bf16_f32 v88, v224, v225
	v_cvt_pk_bf16_f32 v89, v226, v227
	ds_write_b64 v9, v[88:89] offset:9280
	v_cvt_pk_bf16_f32 v88, v164, v165
	v_cvt_pk_bf16_f32 v89, v166, v167
	ds_write_b64 v9, v[88:89] offset:11584
	s_waitcnt vmcnt(1)
	v_mov_b32_dpp v44, v44 row_newbcast:0 row_mask:0xf bank_mask:0xf
	v_mov_b32_dpp v45, v45 row_newbcast:0 row_mask:0xf bank_mask:0xf
	v_mov_b32_dpp v46, v46 row_newbcast:0 row_mask:0xf bank_mask:0xf
	v_mov_b32_dpp v47, v47 row_newbcast:0 row_mask:0xf bank_mask:0xf
	v_mov_b32_dpp v52, v52 row_newbcast:0 row_mask:0xf bank_mask:0xf
	v_mov_b32_dpp v53, v53 row_newbcast:0 row_mask:0xf bank_mask:0xf
	v_mov_b32_dpp v54, v54 row_newbcast:0 row_mask:0xf bank_mask:0xf
	v_mov_b32_dpp v55, v55 row_newbcast:0 row_mask:0xf bank_mask:0xf
	v_mov_b32_dpp v76, v76 row_newbcast:0 row_mask:0xf bank_mask:0xf
	v_mov_b32_dpp v77, v77 row_newbcast:0 row_mask:0xf bank_mask:0xf
	v_mov_b32_dpp v78, v78 row_newbcast:0 row_mask:0xf bank_mask:0xf
	v_mov_b32_dpp v79, v79 row_newbcast:0 row_mask:0xf bank_mask:0xf
	v_mov_b32_dpp v80, v80 row_newbcast:0 row_mask:0xf bank_mask:0xf
	v_mov_b32_dpp v81, v81 row_newbcast:0 row_mask:0xf bank_mask:0xf
	v_mov_b32_dpp v82, v82 row_newbcast:0 row_mask:0xf bank_mask:0xf
	v_mov_b32_dpp v83, v83 row_newbcast:0 row_mask:0xf bank_mask:0xf
	v_mov_b32_dpp v84, v84 row_newbcast:0 row_mask:0xf bank_mask:0xf
	v_mov_b32_dpp v85, v85 row_newbcast:0 row_mask:0xf bank_mask:0xf
	v_mov_b32_dpp v86, v86 row_newbcast:0 row_mask:0xf bank_mask:0xf
	v_mov_b32_dpp v87, v87 row_newbcast:0 row_mask:0xf bank_mask:0xf
	v_mov_b32_dpp v142, v142 row_newbcast:0 row_mask:0xf bank_mask:0xf
	v_mov_b32_dpp v143, v143 row_newbcast:0 row_mask:0xf bank_mask:0xf
	v_mov_b32_dpp v144, v144 row_newbcast:0 row_mask:0xf bank_mask:0xf
	v_mov_b32_dpp v145, v145 row_newbcast:0 row_mask:0xf bank_mask:0xf
	s_nop 1
	v_mfma_f32_16x16x32_bf16 v[164:167], v[56:59], v[12:15], 0
	v_mfma_f32_16x16x32_bf16 v[168:171], v[64:67], v[20:23], 0
	v_mfma_f32_16x16x32_bf16 v[172:175], v[72:75], v[28:31], 0
	v_mfma_f32_16x16x32_bf16 v[164:167], v[60:63], v[16:19], v[164:167]
	v_mfma_f32_16x16x32_bf16 v[168:171], v[68:71], v[24:27], v[168:171]
	v_mov_b32_dpp v42, v40 row_shr:1 row_mask:0xf bank_mask:0xf
	v_mov_b32_dpp v43, v41 row_shr:1 row_mask:0xf bank_mask:0xf
	v_and_b32_e32 v42, v5, v42
	v_and_b32_e32 v43, v5, v43
	v_lshlrev_b32_e32 v184, 16, v40
	v_and_b32_e32 v185, 0xffff0000, v40
	v_lshlrev_b32_e32 v220, 16, v42
	v_and_b32_e32 v221, 0xffff0000, v42
	v_sub_f32_e32 v220, v220, v184
	v_sub_f32_e32 v221, v221, v185
	v_fmac_f32_e32 v184, v44, v220
	v_fmac_f32_e32 v185, v45, v221
	v_lshlrev_b32_e32 v186, 16, v41
	v_and_b32_e32 v187, 0xffff0000, v41
	v_lshlrev_b32_e32 v220, 16, v43
	v_and_b32_e32 v221, 0xffff0000, v43
	v_sub_f32_e32 v220, v220, v186
	v_sub_f32_e32 v221, v221, v187
	v_fmac_f32_e32 v186, v46, v220
	v_fmac_f32_e32 v187, v47, v221
	v_mov_b32_dpp v50, v48 row_shr:1 row_mask:0xf bank_mask:0xf
	v_mov_b32_dpp v51, v49 row_shr:1 row_mask:0xf bank_mask:0xf
	v_and_b32_e32 v50, v5, v50
	v_and_b32_e32 v51, v5, v51
	v_lshlrev_b32_e32 v228, 16, v48
	v_and_b32_e32 v229, 0xffff0000, v48
	v_lshlrev_b32_e32 v220, 16, v50
	v_and_b32_e32 v221, 0xffff0000, v50
	v_sub_f32_e32 v220, v220, v228
	v_sub_f32_e32 v221, v221, v229
	v_fmac_f32_e32 v228, v52, v220
	v_fmac_f32_e32 v229, v53, v221
	v_lshlrev_b32_e32 v230, 16, v49
	v_and_b32_e32 v231, 0xffff0000, v49
	v_lshlrev_b32_e32 v220, 16, v51
	v_and_b32_e32 v221, 0xffff0000, v51
	v_sub_f32_e32 v220, v220, v230
	v_sub_f32_e32 v221, v221, v231
	v_fmac_f32_e32 v230, v54, v220
	v_fmac_f32_e32 v231, v55, v221
	s_nop 7
	v_add_f32_e32 v164, v76, v164
	v_add_f32_e32 v168, v80, v168
	v_add_f32_e32 v172, v142, v172
	v_add_f32_e32 v165, v77, v165
	v_add_f32_e32 v169, v81, v169
	v_add_f32_e32 v173, v143, v173
	v_add_f32_e32 v166, v78, v166
	v_add_f32_e32 v170, v82, v170
	v_add_f32_e32 v174, v144, v174
	v_add_f32_e32 v167, v79, v167
	v_add_f32_e32 v171, v83, v171
	v_add_f32_e32 v175, v145, v175
	v_mul_f32_e32 v164, 0xbfb8aa3b, v164
	v_exp_f32_e32 v164, v164
	s_nop 0
	v_add_f32_e32 v164, 1.0, v164
	v_rcp_f32_e32 v164, v164
	v_mul_f32_e32 v168, 0xbfb8aa3b, v168
	v_exp_f32_e32 v168, v168
	s_nop 0
	v_add_f32_e32 v168, 1.0, v168
	v_rcp_f32_e32 v168, v168
	v_mul_f32_e32 v172, 0xbfb8aa3b, v172
	v_exp_f32_e32 v172, v172
	s_nop 0
	v_add_f32_e32 v172, 1.0, v172
	v_rcp_f32_e32 v172, v172
	v_mul_f32_e32 v165, 0xbfb8aa3b, v165
	v_exp_f32_e32 v165, v165
	s_nop 0
	v_add_f32_e32 v165, 1.0, v165
	v_rcp_f32_e32 v165, v165
	v_mul_f32_e32 v169, 0xbfb8aa3b, v169
	v_exp_f32_e32 v169, v169
	s_nop 0
	v_add_f32_e32 v169, 1.0, v169
	v_rcp_f32_e32 v169, v169
	v_mul_f32_e32 v173, 0xbfb8aa3b, v173
	v_exp_f32_e32 v173, v173
	s_nop 0
	v_add_f32_e32 v173, 1.0, v173
	v_rcp_f32_e32 v173, v173
	v_mul_f32_e32 v166, 0xbfb8aa3b, v166
	v_exp_f32_e32 v166, v166
	s_nop 0
	v_add_f32_e32 v166, 1.0, v166
	v_rcp_f32_e32 v166, v166
	v_mul_f32_e32 v170, 0xbfb8aa3b, v170
	v_exp_f32_e32 v170, v170
	s_nop 0
	v_add_f32_e32 v170, 1.0, v170
	v_rcp_f32_e32 v170, v170
	v_mul_f32_e32 v174, 0xbfb8aa3b, v174
	v_exp_f32_e32 v174, v174
	s_nop 0
	v_add_f32_e32 v174, 1.0, v174
	v_rcp_f32_e32 v174, v174
	v_mul_f32_e32 v167, 0xbfb8aa3b, v167
	v_exp_f32_e32 v167, v167
	s_nop 0
	v_add_f32_e32 v167, 1.0, v167
	v_rcp_f32_e32 v167, v167
	v_mul_f32_e32 v171, 0xbfb8aa3b, v171
	v_exp_f32_e32 v171, v171
	s_nop 0
	v_add_f32_e32 v171, 1.0, v171
	v_rcp_f32_e32 v171, v171
	v_mul_f32_e32 v175, 0xbfb8aa3b, v175
	v_exp_f32_e32 v175, v175
	s_nop 0
	v_add_f32_e32 v175, 1.0, v175
	v_rcp_f32_e32 v175, v175
	v_mul_f32_e32 v164, 0x3f1b4598, v164
	v_mul_f32_e32 v165, 0x3f1b4598, v165
	v_mul_f32_e32 v166, 0x3f1b4598, v166
	v_mul_f32_e32 v167, 0x3f1b4598, v167
	s_cmp_eq_u32 s32, 0
	s_cbranch_scc1 .Lprep2_l0_0_3
	v_lshlrev_b32_e32 v220, 16, v146
	v_and_b32_e32 v221, 0xffff0000, v146
	v_lshlrev_b32_e32 v222, 16, v147
	v_and_b32_e32 v223, 0xffff0000, v147
	v_sub_f32_e32 v220, v220, v228
	v_fmac_f32_e32 v228, v220, v172
	v_sub_f32_e32 v221, v221, v229
	v_fmac_f32_e32 v229, v221, v173
	v_sub_f32_e32 v222, v222, v230
	v_fmac_f32_e32 v230, v222, v174
	v_sub_f32_e32 v223, v223, v231
	v_fmac_f32_e32 v231, v223, v175
	s_branch .Lprep2_l0d_0_3

.Lprep2_l0d_0_3:
	global_store_dwordx2 v8, v[146:147], s[0:1] offset:96
	v_mul_f32_e32 v220, v160, v34
	v_mul_f32_e32 v224, v220, v168
	v_add_f32_e32 v168, -1.0, v168
	v_fma_f32 v168, v168, v84, 1.0
	v_mul_f32_e32 v168, v216, v168
	v_mul_f32_e32 v221, v161, v34
	v_mul_f32_e32 v225, v221, v169
	v_add_f32_e32 v169, -1.0, v169
	v_fma_f32 v169, v169, v85, 1.0
	v_mul_f32_e32 v169, v217, v169
	v_mul_f32_e32 v222, v162, v34
	v_mul_f32_e32 v226, v222, v170
	v_add_f32_e32 v170, -1.0, v170
	v_fma_f32 v170, v170, v86, 1.0
	v_mul_f32_e32 v170, v218, v170
	v_mul_f32_e32 v223, v163, v34
	v_mul_f32_e32 v227, v223, v171
	v_add_f32_e32 v171, -1.0, v171
	v_fma_f32 v171, v171, v87, 1.0
	v_mul_f32_e32 v171, v219, v171
	v_cvt_pk_bf16_f32 v40, v184, v185
	v_cvt_pk_bf16_f32 v41, v186, v187
	ds_write_b64 v9, v[40:41] offset:96
	v_cvt_pk_bf16_f32 v40, v168, v169
	v_cvt_pk_bf16_f32 v41, v170, v171
	ds_write_b64 v9, v[40:41] offset:2400
	v_cvt_pk_bf16_f32 v40, v228, v229
	v_cvt_pk_bf16_f32 v41, v230, v231
	ds_write_b64 v9, v[40:41] offset:4704
	v_cvt_pk_bf16_f32 v40, v220, v221
	v_cvt_pk_bf16_f32 v41, v222, v223
	ds_write_b64 v9, v[40:41] offset:7008
	v_cvt_pk_bf16_f32 v40, v224, v225
	v_cvt_pk_bf16_f32 v41, v226, v227
	ds_write_b64 v9, v[40:41] offset:9312
	v_cvt_pk_bf16_f32 v40, v164, v165
	v_cvt_pk_bf16_f32 v41, v166, v167
	ds_write_b64 v9, v[40:41] offset:11616
	v_add_u32_e32 v176, 0x2000, v6
	v_add_u32_e32 v177, 0x3000, v6
	v_add_u32_e32 v181, 0x1000, v7
	v_add_u32_e32 v182, 0x42000, v6
	v_add_u32_e32 v183, 0x43000, v6
	s_waitcnt lgkmcnt(0)
	ds_read_b128 v[148:151], v10 offset:0
	ds_read_b128 v[152:155], v10 offset:1152
	ds_read_b128 v[156:159], v10 offset:2304
	ds_read_b128 v[160:163], v10 offset:3456
	ds_read_b128 v[204:207], v10 offset:4608
	ds_read_b128 v[208:211], v10 offset:5760
	ds_read_b128 v[212:215], v10 offset:6912
	ds_read_b128 v[216:219], v10 offset:8064
	ds_read_b128 v[164:167], v10 offset:9216
	ds_read_b128 v[168:171], v10 offset:10368
	ds_read_b128 v[172:175], v10 offset:11520
	ds_read_b128 v[220:223], v10 offset:12672
	global_load_dwordx2 v[40:41], v2, s[40:41] offset:1152
	global_load_dwordx2 v[52:53], v2, s[40:41] offset:1184
	global_load_dwordx2 v[64:65], v2, s[40:41] offset:1216
	global_load_dwordx2 v[76:77], v2, s[40:41] offset:1248
	s_mov_b32 exec_lo, 0x10001
	s_mov_b32 exec_hi, 0x10001
	global_load_dwordx2 v[42:43], v2, s[42:43] offset:1152
	global_load_dwordx4 v[44:47], v1, s[46:47] offset:256
	global_load_dwordx4 v[48:51], v1, s[56:57] offset:256
	global_load_dwordx2 v[54:55], v2, s[42:43] offset:1184
	global_load_dwordx4 v[56:59], v1, s[46:47] offset:320
	global_load_dwordx4 v[60:63], v1, s[56:57] offset:320
	global_load_dwordx2 v[66:67], v2, s[42:43] offset:1216
	global_load_dwordx4 v[68:71], v1, s[46:47] offset:384
	global_load_dwordx4 v[72:75], v1, s[56:57] offset:384
	global_load_dwordx2 v[78:79], v2, s[42:43] offset:1248
	global_load_dwordx4 v[80:83], v1, s[46:47] offset:448
	global_load_dwordx4 v[84:87], v1, s[56:57] offset:448
	s_mov_b64 exec, -1
	global_load_dwordx2 v[88:89], v2, s[40:41] offset:128
	global_load_dwordx2 v[96:97], v2, s[40:41] offset:2176
	global_load_dwordx4 v[104:107], v176, s[60:61] offset:0
	global_load_dwordx4 v[108:111], v176, s[60:61] offset:64
	global_load_dwordx4 v[112:115], v182, s[60:61] offset:0
	global_load_dwordx4 v[116:119], v182, s[60:61] offset:64
	global_load_dwordx4 v[120:123], v181, s[100:101] offset:0
	global_load_dwordx2 v[140:141], v8, s[0:1] offset:128
	s_mov_b32 exec_lo, 0x10001
	s_mov_b32 exec_hi, 0x10001
	global_load_dwordx2 v[90:91], v2, s[42:43] offset:128
	global_load_dwordx2 v[98:99], v2, s[42:43] offset:2176
	global_load_dwordx4 v[92:95], v1, s[46:47] offset:-1792
	global_load_dwordx4 v[100:103], v1, s[46:47] offset:2304
	global_load_dwordx4 v[124:127], v1, s[50:51] offset:256
	global_load_dwordx4 v[128:131], v1, s[52:53] offset:256
	global_load_dwordx4 v[132:135], v1, s[58:59] offset:256
	global_load_dwordx4 v[136:139], v1, s[54:55] offset:256
	s_mov_b64 exec, -1
	s_add_u32 vcc_lo, s24, 0x10e47000
	s_addc_u32 vcc_hi, s25, 0
	s_waitcnt lgkmcnt(11)
	global_store_dwordx4 v11, v[148:151], vcc offset:0
	s_waitcnt lgkmcnt(10)
	global_store_dwordx4 v32, v[152:155], vcc offset:0
	s_add_u32 vcc_lo, s24, 0x11e47000
	s_addc_u32 vcc_hi, s25, 0
	s_waitcnt lgkmcnt(9)
	global_store_dwordx4 v11, v[156:159], vcc offset:0
	s_waitcnt lgkmcnt(8)
	global_store_dwordx4 v32, v[160:163], vcc offset:0
	s_add_u32 vcc_lo, s24, 0x12e47000
	s_addc_u32 vcc_hi, s25, 0
	s_waitcnt lgkmcnt(7)
	global_store_dwordx4 v11, v[204:207], vcc offset:0
	s_waitcnt lgkmcnt(6)
	global_store_dwordx4 v32, v[208:211], vcc offset:0
	s_add_u32 vcc_lo, s24, 0x13e47000
	s_addc_u32 vcc_hi, s25, 0
	s_waitcnt lgkmcnt(5)
	global_store_dwordx4 v11, v[212:215], vcc offset:0
	s_waitcnt lgkmcnt(4)
	global_store_dwordx4 v32, v[216:219], vcc offset:0
	s_add_u32 vcc_lo, s24, 0x14e47000
	s_addc_u32 vcc_hi, s25, 0
	s_waitcnt lgkmcnt(3)
	global_store_dwordx4 v11, v[164:167], vcc offset:0
	s_waitcnt lgkmcnt(2)
	global_store_dwordx4 v32, v[168:171], vcc offset:0
	s_add_u32 vcc_lo, s24, 0x15e47000
	s_addc_u32 vcc_hi, s25, 0
	s_waitcnt lgkmcnt(1)
	global_store_dwordx4 v11, v[172:175], vcc offset:0
	s_waitcnt lgkmcnt(0)
	global_store_dwordx4 v32, v[220:223], vcc offset:0
	s_waitcnt vmcnt(28)
	v_mov_b32_dpp v44, v44 row_newbcast:0 row_mask:0xf bank_mask:0xf
	v_mov_b32_dpp v45, v45 row_newbcast:0 row_mask:0xf bank_mask:0xf
	v_mov_b32_dpp v46, v46 row_newbcast:0 row_mask:0xf bank_mask:0xf
	v_mov_b32_dpp v47, v47 row_newbcast:0 row_mask:0xf bank_mask:0xf
	v_mov_b32_dpp v48, v48 row_newbcast:0 row_mask:0xf bank_mask:0xf
	v_mov_b32_dpp v49, v49 row_newbcast:0 row_mask:0xf bank_mask:0xf
	v_mov_b32_dpp v50, v50 row_newbcast:0 row_mask:0xf bank_mask:0xf
	v_mov_b32_dpp v51, v51 row_newbcast:0 row_mask:0xf bank_mask:0xf
	v_mov_b32_dpp v42, v40 row_shr:1 row_mask:0xf bank_mask:0xf
	v_mov_b32_dpp v43, v41 row_shr:1 row_mask:0xf bank_mask:0xf
	v_and_b32_e32 v42, v5, v42
	v_and_b32_e32 v43, v5, v43
	v_lshlrev_b32_e32 v204, 16, v40
	v_and_b32_e32 v205, 0xffff0000, v40
	v_lshlrev_b32_e32 v220, 16, v42
	v_and_b32_e32 v221, 0xffff0000, v42
	v_sub_f32_e32 v220, v220, v204
	v_sub_f32_e32 v221, v221, v205
	v_fmac_f32_e32 v204, v44, v220
	v_fmac_f32_e32 v205, v45, v221
	v_lshlrev_b32_e32 v206, 16, v41
	v_and_b32_e32 v207, 0xffff0000, v41
	v_lshlrev_b32_e32 v220, 16, v43
	v_and_b32_e32 v221, 0xffff0000, v43
	v_sub_f32_e32 v220, v220, v206
	v_sub_f32_e32 v221, v221, v207
	v_fmac_f32_e32 v206, v46, v220
	v_fmac_f32_e32 v207, v47, v221
	v_mul_f32_e32 v148, v204, v48
	v_mul_f32_e32 v149, v205, v49
	v_mul_f32_e32 v150, v206, v50
	v_mul_f32_e32 v151, v207, v51
	v_mul_f32_e32 v223, v148, v148
	v_fma_f32 v223, v149, v149, v223
	v_fma_f32 v223, v150, v150, v223
	v_fma_f32 v223, v151, v151, v223
	v_mov_b32_e32 v222, v223
	v_mov_b32_dpp v56, v56 row_newbcast:0 row_mask:0xf bank_mask:0xf
	v_mov_b32_dpp v57, v57 row_newbcast:0 row_mask:0xf bank_mask:0xf
	v_mov_b32_dpp v58, v58 row_newbcast:0 row_mask:0xf bank_mask:0xf
	v_mov_b32_dpp v59, v59 row_newbcast:0 row_mask:0xf bank_mask:0xf
	v_mov_b32_dpp v60, v60 row_newbcast:0 row_mask:0xf bank_mask:0xf
	v_mov_b32_dpp v61, v61 row_newbcast:0 row_mask:0xf bank_mask:0xf
	v_mov_b32_dpp v62, v62 row_newbcast:0 row_mask:0xf bank_mask:0xf
	v_mov_b32_dpp v63, v63 row_newbcast:0 row_mask:0xf bank_mask:0xf
	v_mov_b32_dpp v54, v52 row_shr:1 row_mask:0xf bank_mask:0xf
	v_mov_b32_dpp v55, v53 row_shr:1 row_mask:0xf bank_mask:0xf
	v_and_b32_e32 v54, v5, v54
	v_and_b32_e32 v55, v5, v55
	v_lshlrev_b32_e32 v208, 16, v52
	v_and_b32_e32 v209, 0xffff0000, v52
	v_lshlrev_b32_e32 v220, 16, v54
	v_and_b32_e32 v221, 0xffff0000, v54
	v_sub_f32_e32 v220, v220, v208
	v_sub_f32_e32 v221, v221, v209
	v_fmac_f32_e32 v208, v56, v220
	v_fmac_f32_e32 v209, v57, v221
	v_lshlrev_b32_e32 v210, 16, v53
	v_and_b32_e32 v211, 0xffff0000, v53
	v_lshlrev_b32_e32 v220, 16, v55
	v_and_b32_e32 v221, 0xffff0000, v55
	v_sub_f32_e32 v220, v220, v210
	v_sub_f32_e32 v221, v221, v211
	v_fmac_f32_e32 v210, v58, v220
	v_fmac_f32_e32 v211, v59, v221
	v_mul_f32_e32 v152, v208, v60
	v_mul_f32_e32 v153, v209, v61
	v_mul_f32_e32 v154, v210, v62
	v_mul_f32_e32 v155, v211, v63
	v_mul_f32_e32 v223, v152, v152
	v_fma_f32 v223, v153, v153, v223
	v_fma_f32 v223, v154, v154, v223
	v_fma_f32 v223, v155, v155, v223
	v_add_f32_e32 v222, v222, v223
	v_mov_b32_dpp v68, v68 row_newbcast:0 row_mask:0xf bank_mask:0xf
	v_mov_b32_dpp v69, v69 row_newbcast:0 row_mask:0xf bank_mask:0xf
	v_mov_b32_dpp v70, v70 row_newbcast:0 row_mask:0xf bank_mask:0xf
	v_mov_b32_dpp v71, v71 row_newbcast:0 row_mask:0xf bank_mask:0xf
	v_mov_b32_dpp v72, v72 row_newbcast:0 row_mask:0xf bank_mask:0xf
	v_mov_b32_dpp v73, v73 row_newbcast:0 row_mask:0xf bank_mask:0xf
	v_mov_b32_dpp v74, v74 row_newbcast:0 row_mask:0xf bank_mask:0xf
	v_mov_b32_dpp v75, v75 row_newbcast:0 row_mask:0xf bank_mask:0xf
	v_mov_b32_dpp v66, v64 row_shr:1 row_mask:0xf bank_mask:0xf
	v_mov_b32_dpp v67, v65 row_shr:1 row_mask:0xf bank_mask:0xf
	v_and_b32_e32 v66, v5, v66
	v_and_b32_e32 v67, v5, v67
	v_lshlrev_b32_e32 v212, 16, v64
	v_and_b32_e32 v213, 0xffff0000, v64
	v_lshlrev_b32_e32 v220, 16, v66
	v_and_b32_e32 v221, 0xffff0000, v66
	v_sub_f32_e32 v220, v220, v212
	v_sub_f32_e32 v221, v221, v213
	v_fmac_f32_e32 v212, v68, v220
	v_fmac_f32_e32 v213, v69, v221
	v_lshlrev_b32_e32 v214, 16, v65
	v_and_b32_e32 v215, 0xffff0000, v65
	v_lshlrev_b32_e32 v220, 16, v67
	v_and_b32_e32 v221, 0xffff0000, v67
	v_sub_f32_e32 v220, v220, v214
	v_sub_f32_e32 v221, v221, v215
	v_fmac_f32_e32 v214, v70, v220
	v_fmac_f32_e32 v215, v71, v221
	v_mul_f32_e32 v156, v212, v72
	v_mul_f32_e32 v157, v213, v73
	v_mul_f32_e32 v158, v214, v74
	v_mul_f32_e32 v159, v215, v75
	v_mul_f32_e32 v223, v156, v156
	v_fma_f32 v223, v157, v157, v223
	v_fma_f32 v223, v158, v158, v223
	v_fma_f32 v223, v159, v159, v223
	v_add_f32_e32 v222, v222, v223
	v_mov_b32_dpp v80, v80 row_newbcast:0 row_mask:0xf bank_mask:0xf
	v_mov_b32_dpp v81, v81 row_newbcast:0 row_mask:0xf bank_mask:0xf
	v_mov_b32_dpp v82, v82 row_newbcast:0 row_mask:0xf bank_mask:0xf
	v_mov_b32_dpp v83, v83 row_newbcast:0 row_mask:0xf bank_mask:0xf
	v_mov_b32_dpp v84, v84 row_newbcast:0 row_mask:0xf bank_mask:0xf
	v_mov_b32_dpp v85, v85 row_newbcast:0 row_mask:0xf bank_mask:0xf
	v_mov_b32_dpp v86, v86 row_newbcast:0 row_mask:0xf bank_mask:0xf
	v_mov_b32_dpp v87, v87 row_newbcast:0 row_mask:0xf bank_mask:0xf
	v_mov_b32_dpp v78, v76 row_shr:1 row_mask:0xf bank_mask:0xf
	v_mov_b32_dpp v79, v77 row_shr:1 row_mask:0xf bank_mask:0xf
	v_and_b32_e32 v78, v5, v78
	v_and_b32_e32 v79, v5, v79
	v_lshlrev_b32_e32 v216, 16, v76
	v_and_b32_e32 v217, 0xffff0000, v76
	v_lshlrev_b32_e32 v220, 16, v78
	v_and_b32_e32 v221, 0xffff0000, v78
	v_sub_f32_e32 v220, v220, v216
	v_sub_f32_e32 v221, v221, v217
	v_fmac_f32_e32 v216, v80, v220
	v_fmac_f32_e32 v217, v81, v221
	v_lshlrev_b32_e32 v218, 16, v77
	v_and_b32_e32 v219, 0xffff0000, v77
	v_lshlrev_b32_e32 v220, 16, v79
	v_and_b32_e32 v221, 0xffff0000, v79
	v_sub_f32_e32 v220, v220, v218
	v_sub_f32_e32 v221, v221, v219
	v_fmac_f32_e32 v218, v82, v220
	v_fmac_f32_e32 v219, v83, v221
	v_mul_f32_e32 v160, v216, v84
	v_mul_f32_e32 v161, v217, v85
	v_mul_f32_e32 v162, v218, v86
	v_mul_f32_e32 v163, v219, v87
	v_mul_f32_e32 v223, v160, v160
	v_fma_f32 v223, v161, v161, v223
	v_fma_f32 v223, v162, v162, v223
	v_fma_f32 v223, v163, v163, v223
	v_add_f32_e32 v222, v222, v223
	v_mov_b32_e32 v223, v222
	s_nop 1
	v_permlane16_swap_b32_e32 v222, v223
	s_nop 1
	v_add_f32_e32 v222, v222, v223
	v_mov_b32_e32 v223, v222
	s_nop 1
	v_permlane32_swap_b32_e32 v222, v223
	s_nop 1
	v_add_f32_e32 v222, v222, v223
	s_mov_b32 s34, 0xf800000
	v_cmp_gt_f32_e32 vcc, s34, v222
	v_mul_f32_e32 v220, 0x4f800000, v222
	s_nop 0
	v_cndmask_b32_e32 v222, v222, v220, vcc
	v_sqrt_f32_e32 v224, v222
	s_nop 0
	v_add_u32_e32 v225, -1, v224
	v_fma_f32 v226, -v225, v224, v222
	v_cmp_ge_f32_e64 s[62:63], 0, v226
	v_add_u32_e32 v227, 1, v224
	s_nop 0
	v_cndmask_b32_e64 v225, v224, v225, s[62:63]
	v_fma_f32 v226, -v227, v224, v222
	v_cmp_lt_f32_e64 s[62:63], 0, v226
	s_nop 1
	v_cndmask_b32_e64 v224, v225, v227, s[62:63]
	v_mul_f32_e32 v220, 0x37800000, v224
	v_cndmask_b32_e32 v224, v224, v220, vcc
	v_cmp_class_f32_e32 vcc, v222, v193
	s_nop 1
	v_cndmask_b32_e32 v222, v224, v222, vcc
	v_max_f32_e32 v222, 0x2b8cbccc, v222
	v_div_scale_f32 v224, s[62:63], v222, v222, 1.0
	v_rcp_f32_e32 v225, v224
	s_nop 0
	v_fma_f32 v226, -v224, v225, 1.0
	v_fmac_f32_e32 v225, v226, v225
	v_div_scale_f32 v227, vcc, 1.0, v222, 1.0
	v_mul_f32_e32 v220, v227, v225
	v_fma_f32 v221, -v224, v220, v227
	v_fmac_f32_e32 v220, v221, v225
	v_fma_f32 v224, -v224, v220, v227
	s_nop 1
	v_div_fmas_f32 v224, v224, v225, v220
	v_div_fixup_f32 v34, v224, v222, 1.0
	global_load_dwordx2 v[40:41], v2, s[40:41] offset:160
	global_load_dwordx2 v[48:49], v2, s[40:41] offset:2208
	global_load_dwordx4 v[56:59], v176, s[60:61] offset:2048
	global_load_dwordx4 v[60:63], v176, s[60:61] offset:2112
	global_load_dwordx4 v[64:67], v182, s[60:61] offset:2048
	global_load_dwordx4 v[68:71], v182, s[60:61] offset:2112
	global_load_dwordx4 v[72:75], v181, s[100:101] offset:1024
	global_load_dwordx2 v[146:147], v8, s[0:1] offset:160
	s_mov_b32 exec_lo, 0x10001
	s_mov_b32 exec_hi, 0x10001
	global_load_dwordx2 v[42:43], v2, s[42:43] offset:160
	global_load_dwordx2 v[50:51], v2, s[42:43] offset:2208
	global_load_dwordx4 v[44:47], v1, s[46:47] offset:-1728
	global_load_dwordx4 v[52:55], v1, s[46:47] offset:2368
	global_load_dwordx4 v[76:79], v1, s[50:51] offset:320
	global_load_dwordx4 v[80:83], v1, s[52:53] offset:320
	global_load_dwordx4 v[84:87], v1, s[58:59] offset:320
	global_load_dwordx4 v[142:145], v1, s[54:55] offset:320
	s_mov_b64 exec, -1
	s_waitcnt vmcnt(28)
	v_mov_b32_dpp v92, v92 row_newbcast:0 row_mask:0xf bank_mask:0xf
	v_mov_b32_dpp v93, v93 row_newbcast:0 row_mask:0xf bank_mask:0xf
	v_mov_b32_dpp v94, v94 row_newbcast:0 row_mask:0xf bank_mask:0xf
	v_mov_b32_dpp v95, v95 row_newbcast:0 row_mask:0xf bank_mask:0xf
	v_mov_b32_dpp v100, v100 row_newbcast:0 row_mask:0xf bank_mask:0xf
	v_mov_b32_dpp v101, v101 row_newbcast:0 row_mask:0xf bank_mask:0xf
	v_mov_b32_dpp v102, v102 row_newbcast:0 row_mask:0xf bank_mask:0xf
	v_mov_b32_dpp v103, v103 row_newbcast:0 row_mask:0xf bank_mask:0xf
	v_mov_b32_dpp v124, v124 row_newbcast:0 row_mask:0xf bank_mask:0xf
	v_mov_b32_dpp v125, v125 row_newbcast:0 row_mask:0xf bank_mask:0xf
	v_mov_b32_dpp v126, v126 row_newbcast:0 row_mask:0xf bank_mask:0xf
	v_mov_b32_dpp v127, v127 row_newbcast:0 row_mask:0xf bank_mask:0xf
	v_mov_b32_dpp v128, v128 row_newbcast:0 row_mask:0xf bank_mask:0xf
	v_mov_b32_dpp v129, v129 row_newbcast:0 row_mask:0xf bank_mask:0xf
	v_mov_b32_dpp v130, v130 row_newbcast:0 row_mask:0xf bank_mask:0xf
	v_mov_b32_dpp v131, v131 row_newbcast:0 row_mask:0xf bank_mask:0xf
	v_mov_b32_dpp v132, v132 row_newbcast:0 row_mask:0xf bank_mask:0xf
	v_mov_b32_dpp v133, v133 row_newbcast:0 row_mask:0xf bank_mask:0xf
	v_mov_b32_dpp v134, v134 row_newbcast:0 row_mask:0xf bank_mask:0xf
	v_mov_b32_dpp v135, v135 row_newbcast:0 row_mask:0xf bank_mask:0xf
	v_mov_b32_dpp v136, v136 row_newbcast:0 row_mask:0xf bank_mask:0xf
	v_mov_b32_dpp v137, v137 row_newbcast:0 row_mask:0xf bank_mask:0xf
	v_mov_b32_dpp v138, v138 row_newbcast:0 row_mask:0xf bank_mask:0xf
	v_mov_b32_dpp v139, v139 row_newbcast:0 row_mask:0xf bank_mask:0xf
	s_nop 1
	v_mfma_f32_16x16x32_bf16 v[164:167], v[104:107], v[12:15], 0
	v_mfma_f32_16x16x32_bf16 v[168:171], v[112:115], v[20:23], 0
	v_mfma_f32_16x16x32_bf16 v[172:175], v[120:123], v[28:31], 0
	v_mfma_f32_16x16x32_bf16 v[164:167], v[108:111], v[16:19], v[164:167]
	v_mfma_f32_16x16x32_bf16 v[168:171], v[116:119], v[24:27], v[168:171]
	v_mov_b32_dpp v90, v88 row_shr:1 row_mask:0xf bank_mask:0xf
	v_mov_b32_dpp v91, v89 row_shr:1 row_mask:0xf bank_mask:0xf
	v_and_b32_e32 v90, v5, v90
	v_and_b32_e32 v91, v5, v91
	v_lshlrev_b32_e32 v184, 16, v88
	v_and_b32_e32 v185, 0xffff0000, v88
	v_lshlrev_b32_e32 v220, 16, v90
	v_and_b32_e32 v221, 0xffff0000, v90
	v_sub_f32_e32 v220, v220, v184
	v_sub_f32_e32 v221, v221, v185
	v_fmac_f32_e32 v184, v92, v220
	v_fmac_f32_e32 v185, v93, v221
	v_lshlrev_b32_e32 v186, 16, v89
	v_and_b32_e32 v187, 0xffff0000, v89
	v_lshlrev_b32_e32 v220, 16, v91
	v_and_b32_e32 v221, 0xffff0000, v91
	v_sub_f32_e32 v220, v220, v186
	v_sub_f32_e32 v221, v221, v187
	v_fmac_f32_e32 v186, v94, v220
	v_fmac_f32_e32 v187, v95, v221
	v_mov_b32_dpp v98, v96 row_shr:1 row_mask:0xf bank_mask:0xf
	v_mov_b32_dpp v99, v97 row_shr:1 row_mask:0xf bank_mask:0xf
	v_and_b32_e32 v98, v5, v98
	v_and_b32_e32 v99, v5, v99
	v_lshlrev_b32_e32 v228, 16, v96
	v_and_b32_e32 v229, 0xffff0000, v96
	v_lshlrev_b32_e32 v220, 16, v98
	v_and_b32_e32 v221, 0xffff0000, v98
	v_sub_f32_e32 v220, v220, v228
	v_sub_f32_e32 v221, v221, v229
	v_fmac_f32_e32 v228, v100, v220
	v_fmac_f32_e32 v229, v101, v221
	v_lshlrev_b32_e32 v230, 16, v97
	v_and_b32_e32 v231, 0xffff0000, v97
	v_lshlrev_b32_e32 v220, 16, v99
	v_and_b32_e32 v221, 0xffff0000, v99
	v_sub_f32_e32 v220, v220, v230
	v_sub_f32_e32 v221, v221, v231
	v_fmac_f32_e32 v230, v102, v220
	v_fmac_f32_e32 v231, v103, v221
	s_nop 7
	v_add_f32_e32 v164, v124, v164
	v_add_f32_e32 v168, v128, v168
	v_add_f32_e32 v172, v136, v172
	v_add_f32_e32 v165, v125, v165
	v_add_f32_e32 v169, v129, v169
	v_add_f32_e32 v173, v137, v173
	v_add_f32_e32 v166, v126, v166
	v_add_f32_e32 v170, v130, v170
	v_add_f32_e32 v174, v138, v174
	v_add_f32_e32 v167, v127, v167
	v_add_f32_e32 v171, v131, v171
	v_add_f32_e32 v175, v139, v175
	v_mul_f32_e32 v164, 0xbfb8aa3b, v164
	v_exp_f32_e32 v164, v164
	s_nop 0
	v_add_f32_e32 v164, 1.0, v164
	v_rcp_f32_e32 v164, v164
	v_mul_f32_e32 v168, 0xbfb8aa3b, v168
	v_exp_f32_e32 v168, v168
	s_nop 0
	v_add_f32_e32 v168, 1.0, v168
	v_rcp_f32_e32 v168, v168
	v_mul_f32_e32 v172, 0xbfb8aa3b, v172
	v_exp_f32_e32 v172, v172
	s_nop 0
	v_add_f32_e32 v172, 1.0, v172
	v_rcp_f32_e32 v172, v172
	v_mul_f32_e32 v165, 0xbfb8aa3b, v165
	v_exp_f32_e32 v165, v165
	s_nop 0
	v_add_f32_e32 v165, 1.0, v165
	v_rcp_f32_e32 v165, v165
	v_mul_f32_e32 v169, 0xbfb8aa3b, v169
	v_exp_f32_e32 v169, v169
	s_nop 0
	v_add_f32_e32 v169, 1.0, v169
	v_rcp_f32_e32 v169, v169
	v_mul_f32_e32 v173, 0xbfb8aa3b, v173
	v_exp_f32_e32 v173, v173
	s_nop 0
	v_add_f32_e32 v173, 1.0, v173
	v_rcp_f32_e32 v173, v173
	v_mul_f32_e32 v166, 0xbfb8aa3b, v166
	v_exp_f32_e32 v166, v166
	s_nop 0
	v_add_f32_e32 v166, 1.0, v166
	v_rcp_f32_e32 v166, v166
	v_mul_f32_e32 v170, 0xbfb8aa3b, v170
	v_exp_f32_e32 v170, v170
	s_nop 0
	v_add_f32_e32 v170, 1.0, v170
	v_rcp_f32_e32 v170, v170
	v_mul_f32_e32 v174, 0xbfb8aa3b, v174
	v_exp_f32_e32 v174, v174
	s_nop 0
	v_add_f32_e32 v174, 1.0, v174
	v_rcp_f32_e32 v174, v174
	v_mul_f32_e32 v167, 0xbfb8aa3b, v167
	v_exp_f32_e32 v167, v167
	s_nop 0
	v_add_f32_e32 v167, 1.0, v167
	v_rcp_f32_e32 v167, v167
	v_mul_f32_e32 v171, 0xbfb8aa3b, v171
	v_exp_f32_e32 v171, v171
	s_nop 0
	v_add_f32_e32 v171, 1.0, v171
	v_rcp_f32_e32 v171, v171
	v_mul_f32_e32 v175, 0xbfb8aa3b, v175
	v_exp_f32_e32 v175, v175
	s_nop 0
	v_add_f32_e32 v175, 1.0, v175
	v_rcp_f32_e32 v175, v175
	v_mul_f32_e32 v164, 0x3f1b4598, v164
	v_mul_f32_e32 v165, 0x3f1b4598, v165
	v_mul_f32_e32 v166, 0x3f1b4598, v166
	v_mul_f32_e32 v167, 0x3f1b4598, v167
	s_cmp_eq_u32 s32, 0
	s_cbranch_scc1 .Lprep2_l0_1_0
	v_lshlrev_b32_e32 v220, 16, v140
	v_and_b32_e32 v221, 0xffff0000, v140
	v_lshlrev_b32_e32 v222, 16, v141
	v_and_b32_e32 v223, 0xffff0000, v141
	v_sub_f32_e32 v220, v220, v228
	v_fmac_f32_e32 v228, v220, v172
	v_sub_f32_e32 v221, v221, v229
	v_fmac_f32_e32 v229, v221, v173
	v_sub_f32_e32 v222, v222, v230
	v_fmac_f32_e32 v230, v222, v174
	v_sub_f32_e32 v223, v223, v231
	v_fmac_f32_e32 v231, v223, v175
	s_branch .Lprep2_l0d_1_0

.Lprep2_l0d_1_0:
	global_store_dwordx2 v8, v[140:141], s[0:1] offset:128
	v_mul_f32_e32 v220, v148, v34
	v_mul_f32_e32 v224, v220, v168
	v_add_f32_e32 v168, -1.0, v168
	v_fma_f32 v168, v168, v132, 1.0
	v_mul_f32_e32 v168, v204, v168
	v_mul_f32_e32 v221, v149, v34
	v_mul_f32_e32 v225, v221, v169
	v_add_f32_e32 v169, -1.0, v169
	v_fma_f32 v169, v169, v133, 1.0
	v_mul_f32_e32 v169, v205, v169
	v_mul_f32_e32 v222, v150, v34
	v_mul_f32_e32 v226, v222, v170
	v_add_f32_e32 v170, -1.0, v170
	v_fma_f32 v170, v170, v134, 1.0
	v_mul_f32_e32 v170, v206, v170
	v_mul_f32_e32 v223, v151, v34
	v_mul_f32_e32 v227, v223, v171
	v_add_f32_e32 v171, -1.0, v171
	v_fma_f32 v171, v171, v135, 1.0
	v_mul_f32_e32 v171, v207, v171
	v_cvt_pk_bf16_f32 v88, v184, v185
	v_cvt_pk_bf16_f32 v89, v186, v187
	ds_write_b64 v9, v[88:89] offset:0
	v_cvt_pk_bf16_f32 v88, v168, v169
	v_cvt_pk_bf16_f32 v89, v170, v171
	ds_write_b64 v9, v[88:89] offset:2304
	v_cvt_pk_bf16_f32 v88, v228, v229
	v_cvt_pk_bf16_f32 v89, v230, v231
	ds_write_b64 v9, v[88:89] offset:4608
	v_cvt_pk_bf16_f32 v88, v220, v221
	v_cvt_pk_bf16_f32 v89, v222, v223
	ds_write_b64 v9, v[88:89] offset:6912
	v_cvt_pk_bf16_f32 v88, v224, v225
	v_cvt_pk_bf16_f32 v89, v226, v227
	ds_write_b64 v9, v[88:89] offset:9216
	v_cvt_pk_bf16_f32 v88, v164, v165
	v_cvt_pk_bf16_f32 v89, v166, v167
	ds_write_b64 v9, v[88:89] offset:11520
	global_load_dwordx2 v[88:89], v2, s[40:41] offset:192
	global_load_dwordx2 v[96:97], v2, s[40:41] offset:2240
	global_load_dwordx4 v[104:107], v177, s[60:61] offset:0
	global_load_dwordx4 v[108:111], v177, s[60:61] offset:64
	global_load_dwordx4 v[112:115], v183, s[60:61] offset:0
	global_load_dwordx4 v[116:119], v183, s[60:61] offset:64
	global_load_dwordx4 v[120:123], v181, s[100:101] offset:2048
	global_load_dwordx2 v[140:141], v8, s[0:1] offset:192
	s_mov_b32 exec_lo, 0x10001
	s_mov_b32 exec_hi, 0x10001
	global_load_dwordx2 v[90:91], v2, s[42:43] offset:192
	global_load_dwordx2 v[98:99], v2, s[42:43] offset:2240
	global_load_dwordx4 v[92:95], v1, s[46:47] offset:-1664
	global_load_dwordx4 v[100:103], v1, s[46:47] offset:2432
	global_load_dwordx4 v[124:127], v1, s[50:51] offset:384
	global_load_dwordx4 v[128:131], v1, s[52:53] offset:384
	global_load_dwordx4 v[132:135], v1, s[58:59] offset:384
	global_load_dwordx4 v[136:139], v1, s[54:55] offset:384
	s_mov_b64 exec, -1
	s_waitcnt vmcnt(17)
	v_mov_b32_dpp v44, v44 row_newbcast:0 row_mask:0xf bank_mask:0xf
	v_mov_b32_dpp v45, v45 row_newbcast:0 row_mask:0xf bank_mask:0xf
	v_mov_b32_dpp v46, v46 row_newbcast:0 row_mask:0xf bank_mask:0xf
	v_mov_b32_dpp v47, v47 row_newbcast:0 row_mask:0xf bank_mask:0xf
	v_mov_b32_dpp v52, v52 row_newbcast:0 row_mask:0xf bank_mask:0xf
	v_mov_b32_dpp v53, v53 row_newbcast:0 row_mask:0xf bank_mask:0xf
	v_mov_b32_dpp v54, v54 row_newbcast:0 row_mask:0xf bank_mask:0xf
	v_mov_b32_dpp v55, v55 row_newbcast:0 row_mask:0xf bank_mask:0xf
	v_mov_b32_dpp v76, v76 row_newbcast:0 row_mask:0xf bank_mask:0xf
	v_mov_b32_dpp v77, v77 row_newbcast:0 row_mask:0xf bank_mask:0xf
	v_mov_b32_dpp v78, v78 row_newbcast:0 row_mask:0xf bank_mask:0xf
	v_mov_b32_dpp v79, v79 row_newbcast:0 row_mask:0xf bank_mask:0xf
	v_mov_b32_dpp v80, v80 row_newbcast:0 row_mask:0xf bank_mask:0xf
	v_mov_b32_dpp v81, v81 row_newbcast:0 row_mask:0xf bank_mask:0xf
	v_mov_b32_dpp v82, v82 row_newbcast:0 row_mask:0xf bank_mask:0xf
	v_mov_b32_dpp v83, v83 row_newbcast:0 row_mask:0xf bank_mask:0xf
	v_mov_b32_dpp v84, v84 row_newbcast:0 row_mask:0xf bank_mask:0xf
	v_mov_b32_dpp v85, v85 row_newbcast:0 row_mask:0xf bank_mask:0xf
	v_mov_b32_dpp v86, v86 row_newbcast:0 row_mask:0xf bank_mask:0xf
	v_mov_b32_dpp v87, v87 row_newbcast:0 row_mask:0xf bank_mask:0xf
	v_mov_b32_dpp v142, v142 row_newbcast:0 row_mask:0xf bank_mask:0xf
	v_mov_b32_dpp v143, v143 row_newbcast:0 row_mask:0xf bank_mask:0xf
	v_mov_b32_dpp v144, v144 row_newbcast:0 row_mask:0xf bank_mask:0xf
	v_mov_b32_dpp v145, v145 row_newbcast:0 row_mask:0xf bank_mask:0xf
	s_nop 1
	v_mfma_f32_16x16x32_bf16 v[164:167], v[56:59], v[12:15], 0
	v_mfma_f32_16x16x32_bf16 v[168:171], v[64:67], v[20:23], 0
	v_mfma_f32_16x16x32_bf16 v[172:175], v[72:75], v[28:31], 0
	v_mfma_f32_16x16x32_bf16 v[164:167], v[60:63], v[16:19], v[164:167]
	v_mfma_f32_16x16x32_bf16 v[168:171], v[68:71], v[24:27], v[168:171]
	v_mov_b32_dpp v42, v40 row_shr:1 row_mask:0xf bank_mask:0xf
	v_mov_b32_dpp v43, v41 row_shr:1 row_mask:0xf bank_mask:0xf
	v_and_b32_e32 v42, v5, v42
	v_and_b32_e32 v43, v5, v43
	v_lshlrev_b32_e32 v184, 16, v40
	v_and_b32_e32 v185, 0xffff0000, v40
	v_lshlrev_b32_e32 v220, 16, v42
	v_and_b32_e32 v221, 0xffff0000, v42
	v_sub_f32_e32 v220, v220, v184
	v_sub_f32_e32 v221, v221, v185
	v_fmac_f32_e32 v184, v44, v220
	v_fmac_f32_e32 v185, v45, v221
	v_lshlrev_b32_e32 v186, 16, v41
	v_and_b32_e32 v187, 0xffff0000, v41
	v_lshlrev_b32_e32 v220, 16, v43
	v_and_b32_e32 v221, 0xffff0000, v43
	v_sub_f32_e32 v220, v220, v186
	v_sub_f32_e32 v221, v221, v187
	v_fmac_f32_e32 v186, v46, v220
	v_fmac_f32_e32 v187, v47, v221
	v_mov_b32_dpp v50, v48 row_shr:1 row_mask:0xf bank_mask:0xf
	v_mov_b32_dpp v51, v49 row_shr:1 row_mask:0xf bank_mask:0xf
	v_and_b32_e32 v50, v5, v50
	v_and_b32_e32 v51, v5, v51
	v_lshlrev_b32_e32 v228, 16, v48
	v_and_b32_e32 v229, 0xffff0000, v48
	v_lshlrev_b32_e32 v220, 16, v50
	v_and_b32_e32 v221, 0xffff0000, v50
	v_sub_f32_e32 v220, v220, v228
	v_sub_f32_e32 v221, v221, v229
	v_fmac_f32_e32 v228, v52, v220
	v_fmac_f32_e32 v229, v53, v221
	v_lshlrev_b32_e32 v230, 16, v49
	v_and_b32_e32 v231, 0xffff0000, v49
	v_lshlrev_b32_e32 v220, 16, v51
	v_and_b32_e32 v221, 0xffff0000, v51
	v_sub_f32_e32 v220, v220, v230
	v_sub_f32_e32 v221, v221, v231
	v_fmac_f32_e32 v230, v54, v220
	v_fmac_f32_e32 v231, v55, v221
	s_nop 7
	v_add_f32_e32 v164, v76, v164
	v_add_f32_e32 v168, v80, v168
	v_add_f32_e32 v172, v142, v172
	v_add_f32_e32 v165, v77, v165
	v_add_f32_e32 v169, v81, v169
	v_add_f32_e32 v173, v143, v173
	v_add_f32_e32 v166, v78, v166
	v_add_f32_e32 v170, v82, v170
	v_add_f32_e32 v174, v144, v174
	v_add_f32_e32 v167, v79, v167
	v_add_f32_e32 v171, v83, v171
	v_add_f32_e32 v175, v145, v175
	v_mul_f32_e32 v164, 0xbfb8aa3b, v164
	v_exp_f32_e32 v164, v164
	s_nop 0
	v_add_f32_e32 v164, 1.0, v164
	v_rcp_f32_e32 v164, v164
	v_mul_f32_e32 v168, 0xbfb8aa3b, v168
	v_exp_f32_e32 v168, v168
	s_nop 0
	v_add_f32_e32 v168, 1.0, v168
	v_rcp_f32_e32 v168, v168
	v_mul_f32_e32 v172, 0xbfb8aa3b, v172
	v_exp_f32_e32 v172, v172
	s_nop 0
	v_add_f32_e32 v172, 1.0, v172
	v_rcp_f32_e32 v172, v172
	v_mul_f32_e32 v165, 0xbfb8aa3b, v165
	v_exp_f32_e32 v165, v165
	s_nop 0
	v_add_f32_e32 v165, 1.0, v165
	v_rcp_f32_e32 v165, v165
	v_mul_f32_e32 v169, 0xbfb8aa3b, v169
	v_exp_f32_e32 v169, v169
	s_nop 0
	v_add_f32_e32 v169, 1.0, v169
	v_rcp_f32_e32 v169, v169
	v_mul_f32_e32 v173, 0xbfb8aa3b, v173
	v_exp_f32_e32 v173, v173
	s_nop 0
	v_add_f32_e32 v173, 1.0, v173
	v_rcp_f32_e32 v173, v173
	v_mul_f32_e32 v166, 0xbfb8aa3b, v166
	v_exp_f32_e32 v166, v166
	s_nop 0
	v_add_f32_e32 v166, 1.0, v166
	v_rcp_f32_e32 v166, v166
	v_mul_f32_e32 v170, 0xbfb8aa3b, v170
	v_exp_f32_e32 v170, v170
	s_nop 0
	v_add_f32_e32 v170, 1.0, v170
	v_rcp_f32_e32 v170, v170
	v_mul_f32_e32 v174, 0xbfb8aa3b, v174
	v_exp_f32_e32 v174, v174
	s_nop 0
	v_add_f32_e32 v174, 1.0, v174
	v_rcp_f32_e32 v174, v174
	v_mul_f32_e32 v167, 0xbfb8aa3b, v167
	v_exp_f32_e32 v167, v167
	s_nop 0
	v_add_f32_e32 v167, 1.0, v167
	v_rcp_f32_e32 v167, v167
	v_mul_f32_e32 v171, 0xbfb8aa3b, v171
	v_exp_f32_e32 v171, v171
	s_nop 0
	v_add_f32_e32 v171, 1.0, v171
	v_rcp_f32_e32 v171, v171
	v_mul_f32_e32 v175, 0xbfb8aa3b, v175
	v_exp_f32_e32 v175, v175
	s_nop 0
	v_add_f32_e32 v175, 1.0, v175
	v_rcp_f32_e32 v175, v175
	v_mul_f32_e32 v164, 0x3f1b4598, v164
	v_mul_f32_e32 v165, 0x3f1b4598, v165
	v_mul_f32_e32 v166, 0x3f1b4598, v166
	v_mul_f32_e32 v167, 0x3f1b4598, v167
	s_cmp_eq_u32 s32, 0
	s_cbranch_scc1 .Lprep2_l0_1_1
	v_lshlrev_b32_e32 v220, 16, v146
	v_and_b32_e32 v221, 0xffff0000, v146
	v_lshlrev_b32_e32 v222, 16, v147
	v_and_b32_e32 v223, 0xffff0000, v147
	v_sub_f32_e32 v220, v220, v228
	v_fmac_f32_e32 v228, v220, v172
	v_sub_f32_e32 v221, v221, v229
	v_fmac_f32_e32 v229, v221, v173
	v_sub_f32_e32 v222, v222, v230
	v_fmac_f32_e32 v230, v222, v174
	v_sub_f32_e32 v223, v223, v231
	v_fmac_f32_e32 v231, v223, v175
	s_branch .Lprep2_l0d_1_1

.Lprep2_l0d_1_1:
	global_store_dwordx2 v8, v[146:147], s[0:1] offset:160
	v_mul_f32_e32 v220, v152, v34
	v_mul_f32_e32 v224, v220, v168
	v_add_f32_e32 v168, -1.0, v168
	v_fma_f32 v168, v168, v84, 1.0
	v_mul_f32_e32 v168, v208, v168
	v_mul_f32_e32 v221, v153, v34
	v_mul_f32_e32 v225, v221, v169
	v_add_f32_e32 v169, -1.0, v169
	v_fma_f32 v169, v169, v85, 1.0
	v_mul_f32_e32 v169, v209, v169
	v_mul_f32_e32 v222, v154, v34
	v_mul_f32_e32 v226, v222, v170
	v_add_f32_e32 v170, -1.0, v170
	v_fma_f32 v170, v170, v86, 1.0
	v_mul_f32_e32 v170, v210, v170
	v_mul_f32_e32 v223, v155, v34
	v_mul_f32_e32 v227, v223, v171
	v_add_f32_e32 v171, -1.0, v171
	v_fma_f32 v171, v171, v87, 1.0
	v_mul_f32_e32 v171, v211, v171
	v_cvt_pk_bf16_f32 v40, v184, v185
	v_cvt_pk_bf16_f32 v41, v186, v187
	ds_write_b64 v9, v[40:41] offset:32
	v_cvt_pk_bf16_f32 v40, v168, v169
	v_cvt_pk_bf16_f32 v41, v170, v171
	ds_write_b64 v9, v[40:41] offset:2336
	v_cvt_pk_bf16_f32 v40, v228, v229
	v_cvt_pk_bf16_f32 v41, v230, v231
	ds_write_b64 v9, v[40:41] offset:4640
	v_cvt_pk_bf16_f32 v40, v220, v221
	v_cvt_pk_bf16_f32 v41, v222, v223
	ds_write_b64 v9, v[40:41] offset:6944
	v_cvt_pk_bf16_f32 v40, v224, v225
	v_cvt_pk_bf16_f32 v41, v226, v227
	ds_write_b64 v9, v[40:41] offset:9248
	v_cvt_pk_bf16_f32 v40, v164, v165
	v_cvt_pk_bf16_f32 v41, v166, v167
	ds_write_b64 v9, v[40:41] offset:11552
	global_load_dwordx2 v[40:41], v2, s[40:41] offset:224
	global_load_dwordx2 v[48:49], v2, s[40:41] offset:2272
	global_load_dwordx4 v[56:59], v177, s[60:61] offset:2048
	global_load_dwordx4 v[60:63], v177, s[60:61] offset:2112
	global_load_dwordx4 v[64:67], v183, s[60:61] offset:2048
	global_load_dwordx4 v[68:71], v183, s[60:61] offset:2112
	global_load_dwordx4 v[72:75], v181, s[100:101] offset:3072
	global_load_dwordx2 v[146:147], v8, s[0:1] offset:224
	s_mov_b32 exec_lo, 0x10001
	s_mov_b32 exec_hi, 0x10001
	global_load_dwordx2 v[42:43], v2, s[42:43] offset:224
	global_load_dwordx2 v[50:51], v2, s[42:43] offset:2272
	global_load_dwordx4 v[44:47], v1, s[46:47] offset:-1600
	global_load_dwordx4 v[52:55], v1, s[46:47] offset:2496
	global_load_dwordx4 v[76:79], v1, s[50:51] offset:448
	global_load_dwordx4 v[80:83], v1, s[52:53] offset:448
	global_load_dwordx4 v[84:87], v1, s[58:59] offset:448
	global_load_dwordx4 v[142:145], v1, s[54:55] offset:448
	s_mov_b64 exec, -1
	s_waitcnt vmcnt(17)
	v_mov_b32_dpp v92, v92 row_newbcast:0 row_mask:0xf bank_mask:0xf
	v_mov_b32_dpp v93, v93 row_newbcast:0 row_mask:0xf bank_mask:0xf
	v_mov_b32_dpp v94, v94 row_newbcast:0 row_mask:0xf bank_mask:0xf
	v_mov_b32_dpp v95, v95 row_newbcast:0 row_mask:0xf bank_mask:0xf
	v_mov_b32_dpp v100, v100 row_newbcast:0 row_mask:0xf bank_mask:0xf
	v_mov_b32_dpp v101, v101 row_newbcast:0 row_mask:0xf bank_mask:0xf
	v_mov_b32_dpp v102, v102 row_newbcast:0 row_mask:0xf bank_mask:0xf
	v_mov_b32_dpp v103, v103 row_newbcast:0 row_mask:0xf bank_mask:0xf
	v_mov_b32_dpp v124, v124 row_newbcast:0 row_mask:0xf bank_mask:0xf
	v_mov_b32_dpp v125, v125 row_newbcast:0 row_mask:0xf bank_mask:0xf
	v_mov_b32_dpp v126, v126 row_newbcast:0 row_mask:0xf bank_mask:0xf
	v_mov_b32_dpp v127, v127 row_newbcast:0 row_mask:0xf bank_mask:0xf
	v_mov_b32_dpp v128, v128 row_newbcast:0 row_mask:0xf bank_mask:0xf
	v_mov_b32_dpp v129, v129 row_newbcast:0 row_mask:0xf bank_mask:0xf
	v_mov_b32_dpp v130, v130 row_newbcast:0 row_mask:0xf bank_mask:0xf
	v_mov_b32_dpp v131, v131 row_newbcast:0 row_mask:0xf bank_mask:0xf
	v_mov_b32_dpp v132, v132 row_newbcast:0 row_mask:0xf bank_mask:0xf
	v_mov_b32_dpp v133, v133 row_newbcast:0 row_mask:0xf bank_mask:0xf
	v_mov_b32_dpp v134, v134 row_newbcast:0 row_mask:0xf bank_mask:0xf
	v_mov_b32_dpp v135, v135 row_newbcast:0 row_mask:0xf bank_mask:0xf
	v_mov_b32_dpp v136, v136 row_newbcast:0 row_mask:0xf bank_mask:0xf
	v_mov_b32_dpp v137, v137 row_newbcast:0 row_mask:0xf bank_mask:0xf
	v_mov_b32_dpp v138, v138 row_newbcast:0 row_mask:0xf bank_mask:0xf
	v_mov_b32_dpp v139, v139 row_newbcast:0 row_mask:0xf bank_mask:0xf
	s_nop 1
	v_mfma_f32_16x16x32_bf16 v[164:167], v[104:107], v[12:15], 0
	v_mfma_f32_16x16x32_bf16 v[168:171], v[112:115], v[20:23], 0
	v_mfma_f32_16x16x32_bf16 v[172:175], v[120:123], v[28:31], 0
	v_mfma_f32_16x16x32_bf16 v[164:167], v[108:111], v[16:19], v[164:167]
	v_mfma_f32_16x16x32_bf16 v[168:171], v[116:119], v[24:27], v[168:171]
	v_mov_b32_dpp v90, v88 row_shr:1 row_mask:0xf bank_mask:0xf
	v_mov_b32_dpp v91, v89 row_shr:1 row_mask:0xf bank_mask:0xf
	v_and_b32_e32 v90, v5, v90
	v_and_b32_e32 v91, v5, v91
	v_lshlrev_b32_e32 v184, 16, v88
	v_and_b32_e32 v185, 0xffff0000, v88
	v_lshlrev_b32_e32 v220, 16, v90
	v_and_b32_e32 v221, 0xffff0000, v90
	v_sub_f32_e32 v220, v220, v184
	v_sub_f32_e32 v221, v221, v185
	v_fmac_f32_e32 v184, v92, v220
	v_fmac_f32_e32 v185, v93, v221
	v_lshlrev_b32_e32 v186, 16, v89
	v_and_b32_e32 v187, 0xffff0000, v89
	v_lshlrev_b32_e32 v220, 16, v91
	v_and_b32_e32 v221, 0xffff0000, v91
	v_sub_f32_e32 v220, v220, v186
	v_sub_f32_e32 v221, v221, v187
	v_fmac_f32_e32 v186, v94, v220
	v_fmac_f32_e32 v187, v95, v221
	v_mov_b32_dpp v98, v96 row_shr:1 row_mask:0xf bank_mask:0xf
	v_mov_b32_dpp v99, v97 row_shr:1 row_mask:0xf bank_mask:0xf
	v_and_b32_e32 v98, v5, v98
	v_and_b32_e32 v99, v5, v99
	v_lshlrev_b32_e32 v228, 16, v96
	v_and_b32_e32 v229, 0xffff0000, v96
	v_lshlrev_b32_e32 v220, 16, v98
	v_and_b32_e32 v221, 0xffff0000, v98
	v_sub_f32_e32 v220, v220, v228
	v_sub_f32_e32 v221, v221, v229
	v_fmac_f32_e32 v228, v100, v220
	v_fmac_f32_e32 v229, v101, v221
	v_lshlrev_b32_e32 v230, 16, v97
	v_and_b32_e32 v231, 0xffff0000, v97
	v_lshlrev_b32_e32 v220, 16, v99
	v_and_b32_e32 v221, 0xffff0000, v99
	v_sub_f32_e32 v220, v220, v230
	v_sub_f32_e32 v221, v221, v231
	v_fmac_f32_e32 v230, v102, v220
	v_fmac_f32_e32 v231, v103, v221
	s_nop 7
	v_add_f32_e32 v164, v124, v164
	v_add_f32_e32 v168, v128, v168
	v_add_f32_e32 v172, v136, v172
	v_add_f32_e32 v165, v125, v165
	v_add_f32_e32 v169, v129, v169
	v_add_f32_e32 v173, v137, v173
	v_add_f32_e32 v166, v126, v166
	v_add_f32_e32 v170, v130, v170
	v_add_f32_e32 v174, v138, v174
	v_add_f32_e32 v167, v127, v167
	v_add_f32_e32 v171, v131, v171
	v_add_f32_e32 v175, v139, v175
	v_mul_f32_e32 v164, 0xbfb8aa3b, v164
	v_exp_f32_e32 v164, v164
	s_nop 0
	v_add_f32_e32 v164, 1.0, v164
	v_rcp_f32_e32 v164, v164
	v_mul_f32_e32 v168, 0xbfb8aa3b, v168
	v_exp_f32_e32 v168, v168
	s_nop 0
	v_add_f32_e32 v168, 1.0, v168
	v_rcp_f32_e32 v168, v168
	v_mul_f32_e32 v172, 0xbfb8aa3b, v172
	v_exp_f32_e32 v172, v172
	s_nop 0
	v_add_f32_e32 v172, 1.0, v172
	v_rcp_f32_e32 v172, v172
	v_mul_f32_e32 v165, 0xbfb8aa3b, v165
	v_exp_f32_e32 v165, v165
	s_nop 0
	v_add_f32_e32 v165, 1.0, v165
	v_rcp_f32_e32 v165, v165
	v_mul_f32_e32 v169, 0xbfb8aa3b, v169
	v_exp_f32_e32 v169, v169
	s_nop 0
	v_add_f32_e32 v169, 1.0, v169
	v_rcp_f32_e32 v169, v169
	v_mul_f32_e32 v173, 0xbfb8aa3b, v173
	v_exp_f32_e32 v173, v173
	s_nop 0
	v_add_f32_e32 v173, 1.0, v173
	v_rcp_f32_e32 v173, v173
	v_mul_f32_e32 v166, 0xbfb8aa3b, v166
	v_exp_f32_e32 v166, v166
	s_nop 0
	v_add_f32_e32 v166, 1.0, v166
	v_rcp_f32_e32 v166, v166
	v_mul_f32_e32 v170, 0xbfb8aa3b, v170
	v_exp_f32_e32 v170, v170
	s_nop 0
	v_add_f32_e32 v170, 1.0, v170
	v_rcp_f32_e32 v170, v170
	v_mul_f32_e32 v174, 0xbfb8aa3b, v174
	v_exp_f32_e32 v174, v174
	s_nop 0
	v_add_f32_e32 v174, 1.0, v174
	v_rcp_f32_e32 v174, v174
	v_mul_f32_e32 v167, 0xbfb8aa3b, v167
	v_exp_f32_e32 v167, v167
	s_nop 0
	v_add_f32_e32 v167, 1.0, v167
	v_rcp_f32_e32 v167, v167
	v_mul_f32_e32 v171, 0xbfb8aa3b, v171
	v_exp_f32_e32 v171, v171
	s_nop 0
	v_add_f32_e32 v171, 1.0, v171
	v_rcp_f32_e32 v171, v171
	v_mul_f32_e32 v175, 0xbfb8aa3b, v175
	v_exp_f32_e32 v175, v175
	s_nop 0
	v_add_f32_e32 v175, 1.0, v175
	v_rcp_f32_e32 v175, v175
	v_mul_f32_e32 v164, 0x3f1b4598, v164
	v_mul_f32_e32 v165, 0x3f1b4598, v165
	v_mul_f32_e32 v166, 0x3f1b4598, v166
	v_mul_f32_e32 v167, 0x3f1b4598, v167
	s_cmp_eq_u32 s32, 0
	s_cbranch_scc1 .Lprep2_l0_1_2
	v_lshlrev_b32_e32 v220, 16, v140
	v_and_b32_e32 v221, 0xffff0000, v140
	v_lshlrev_b32_e32 v222, 16, v141
	v_and_b32_e32 v223, 0xffff0000, v141
	v_sub_f32_e32 v220, v220, v228
	v_fmac_f32_e32 v228, v220, v172
	v_sub_f32_e32 v221, v221, v229
	v_fmac_f32_e32 v229, v221, v173
	v_sub_f32_e32 v222, v222, v230
	v_fmac_f32_e32 v230, v222, v174
	v_sub_f32_e32 v223, v223, v231
	v_fmac_f32_e32 v231, v223, v175
	s_branch .Lprep2_l0d_1_2

.Lprep2_l0d_1_2:
	global_store_dwordx2 v8, v[140:141], s[0:1] offset:192
	v_mul_f32_e32 v220, v156, v34
	v_mul_f32_e32 v224, v220, v168
	v_add_f32_e32 v168, -1.0, v168
	v_fma_f32 v168, v168, v132, 1.0
	v_mul_f32_e32 v168, v212, v168
	v_mul_f32_e32 v221, v157, v34
	v_mul_f32_e32 v225, v221, v169
	v_add_f32_e32 v169, -1.0, v169
	v_fma_f32 v169, v169, v133, 1.0
	v_mul_f32_e32 v169, v213, v169
	v_mul_f32_e32 v222, v158, v34
	v_mul_f32_e32 v226, v222, v170
	v_add_f32_e32 v170, -1.0, v170
	v_fma_f32 v170, v170, v134, 1.0
	v_mul_f32_e32 v170, v214, v170
	v_mul_f32_e32 v223, v159, v34
	v_mul_f32_e32 v227, v223, v171
	v_add_f32_e32 v171, -1.0, v171
	v_fma_f32 v171, v171, v135, 1.0
	v_mul_f32_e32 v171, v215, v171
	v_cvt_pk_bf16_f32 v88, v184, v185
	v_cvt_pk_bf16_f32 v89, v186, v187
	ds_write_b64 v9, v[88:89] offset:64
	v_cvt_pk_bf16_f32 v88, v168, v169
	v_cvt_pk_bf16_f32 v89, v170, v171
	ds_write_b64 v9, v[88:89] offset:2368
	v_cvt_pk_bf16_f32 v88, v228, v229
	v_cvt_pk_bf16_f32 v89, v230, v231
	ds_write_b64 v9, v[88:89] offset:4672
	v_cvt_pk_bf16_f32 v88, v220, v221
	v_cvt_pk_bf16_f32 v89, v222, v223
	ds_write_b64 v9, v[88:89] offset:6976
	v_cvt_pk_bf16_f32 v88, v224, v225
	v_cvt_pk_bf16_f32 v89, v226, v227
	ds_write_b64 v9, v[88:89] offset:9280
	v_cvt_pk_bf16_f32 v88, v164, v165
	v_cvt_pk_bf16_f32 v89, v166, v167
	ds_write_b64 v9, v[88:89] offset:11584
	s_waitcnt vmcnt(1)
	v_mov_b32_dpp v44, v44 row_newbcast:0 row_mask:0xf bank_mask:0xf
	v_mov_b32_dpp v45, v45 row_newbcast:0 row_mask:0xf bank_mask:0xf
	v_mov_b32_dpp v46, v46 row_newbcast:0 row_mask:0xf bank_mask:0xf
	v_mov_b32_dpp v47, v47 row_newbcast:0 row_mask:0xf bank_mask:0xf
	v_mov_b32_dpp v52, v52 row_newbcast:0 row_mask:0xf bank_mask:0xf
	v_mov_b32_dpp v53, v53 row_newbcast:0 row_mask:0xf bank_mask:0xf
	v_mov_b32_dpp v54, v54 row_newbcast:0 row_mask:0xf bank_mask:0xf
	v_mov_b32_dpp v55, v55 row_newbcast:0 row_mask:0xf bank_mask:0xf
	v_mov_b32_dpp v76, v76 row_newbcast:0 row_mask:0xf bank_mask:0xf
	v_mov_b32_dpp v77, v77 row_newbcast:0 row_mask:0xf bank_mask:0xf
	v_mov_b32_dpp v78, v78 row_newbcast:0 row_mask:0xf bank_mask:0xf
	v_mov_b32_dpp v79, v79 row_newbcast:0 row_mask:0xf bank_mask:0xf
	v_mov_b32_dpp v80, v80 row_newbcast:0 row_mask:0xf bank_mask:0xf
	v_mov_b32_dpp v81, v81 row_newbcast:0 row_mask:0xf bank_mask:0xf
	v_mov_b32_dpp v82, v82 row_newbcast:0 row_mask:0xf bank_mask:0xf
	v_mov_b32_dpp v83, v83 row_newbcast:0 row_mask:0xf bank_mask:0xf
	v_mov_b32_dpp v84, v84 row_newbcast:0 row_mask:0xf bank_mask:0xf
	v_mov_b32_dpp v85, v85 row_newbcast:0 row_mask:0xf bank_mask:0xf
	v_mov_b32_dpp v86, v86 row_newbcast:0 row_mask:0xf bank_mask:0xf
	v_mov_b32_dpp v87, v87 row_newbcast:0 row_mask:0xf bank_mask:0xf
	v_mov_b32_dpp v142, v142 row_newbcast:0 row_mask:0xf bank_mask:0xf
	v_mov_b32_dpp v143, v143 row_newbcast:0 row_mask:0xf bank_mask:0xf
	v_mov_b32_dpp v144, v144 row_newbcast:0 row_mask:0xf bank_mask:0xf
	v_mov_b32_dpp v145, v145 row_newbcast:0 row_mask:0xf bank_mask:0xf
	s_nop 1
	v_mfma_f32_16x16x32_bf16 v[164:167], v[56:59], v[12:15], 0
	v_mfma_f32_16x16x32_bf16 v[168:171], v[64:67], v[20:23], 0
	v_mfma_f32_16x16x32_bf16 v[172:175], v[72:75], v[28:31], 0
	v_mfma_f32_16x16x32_bf16 v[164:167], v[60:63], v[16:19], v[164:167]
	v_mfma_f32_16x16x32_bf16 v[168:171], v[68:71], v[24:27], v[168:171]
	v_mov_b32_dpp v42, v40 row_shr:1 row_mask:0xf bank_mask:0xf
	v_mov_b32_dpp v43, v41 row_shr:1 row_mask:0xf bank_mask:0xf
	v_and_b32_e32 v42, v5, v42
	v_and_b32_e32 v43, v5, v43
	v_lshlrev_b32_e32 v184, 16, v40
	v_and_b32_e32 v185, 0xffff0000, v40
	v_lshlrev_b32_e32 v220, 16, v42
	v_and_b32_e32 v221, 0xffff0000, v42
	v_sub_f32_e32 v220, v220, v184
	v_sub_f32_e32 v221, v221, v185
	v_fmac_f32_e32 v184, v44, v220
	v_fmac_f32_e32 v185, v45, v221
	v_lshlrev_b32_e32 v186, 16, v41
	v_and_b32_e32 v187, 0xffff0000, v41
	v_lshlrev_b32_e32 v220, 16, v43
	v_and_b32_e32 v221, 0xffff0000, v43
	v_sub_f32_e32 v220, v220, v186
	v_sub_f32_e32 v221, v221, v187
	v_fmac_f32_e32 v186, v46, v220
	v_fmac_f32_e32 v187, v47, v221
	v_mov_b32_dpp v50, v48 row_shr:1 row_mask:0xf bank_mask:0xf
	v_mov_b32_dpp v51, v49 row_shr:1 row_mask:0xf bank_mask:0xf
	v_and_b32_e32 v50, v5, v50
	v_and_b32_e32 v51, v5, v51
	v_lshlrev_b32_e32 v228, 16, v48
	v_and_b32_e32 v229, 0xffff0000, v48
	v_lshlrev_b32_e32 v220, 16, v50
	v_and_b32_e32 v221, 0xffff0000, v50
	v_sub_f32_e32 v220, v220, v228
	v_sub_f32_e32 v221, v221, v229
	v_fmac_f32_e32 v228, v52, v220
	v_fmac_f32_e32 v229, v53, v221
	v_lshlrev_b32_e32 v230, 16, v49
	v_and_b32_e32 v231, 0xffff0000, v49
	v_lshlrev_b32_e32 v220, 16, v51
	v_and_b32_e32 v221, 0xffff0000, v51
	v_sub_f32_e32 v220, v220, v230
	v_sub_f32_e32 v221, v221, v231
	v_fmac_f32_e32 v230, v54, v220
	v_fmac_f32_e32 v231, v55, v221
	s_nop 7
	v_add_f32_e32 v164, v76, v164
	v_add_f32_e32 v168, v80, v168
	v_add_f32_e32 v172, v142, v172
	v_add_f32_e32 v165, v77, v165
	v_add_f32_e32 v169, v81, v169
	v_add_f32_e32 v173, v143, v173
	v_add_f32_e32 v166, v78, v166
	v_add_f32_e32 v170, v82, v170
	v_add_f32_e32 v174, v144, v174
	v_add_f32_e32 v167, v79, v167
	v_add_f32_e32 v171, v83, v171
	v_add_f32_e32 v175, v145, v175
	v_mul_f32_e32 v164, 0xbfb8aa3b, v164
	v_exp_f32_e32 v164, v164
	s_nop 0
	v_add_f32_e32 v164, 1.0, v164
	v_rcp_f32_e32 v164, v164
	v_mul_f32_e32 v168, 0xbfb8aa3b, v168
	v_exp_f32_e32 v168, v168
	s_nop 0
	v_add_f32_e32 v168, 1.0, v168
	v_rcp_f32_e32 v168, v168
	v_mul_f32_e32 v172, 0xbfb8aa3b, v172
	v_exp_f32_e32 v172, v172
	s_nop 0
	v_add_f32_e32 v172, 1.0, v172
	v_rcp_f32_e32 v172, v172
	v_mul_f32_e32 v165, 0xbfb8aa3b, v165
	v_exp_f32_e32 v165, v165
	s_nop 0
	v_add_f32_e32 v165, 1.0, v165
	v_rcp_f32_e32 v165, v165
	v_mul_f32_e32 v169, 0xbfb8aa3b, v169
	v_exp_f32_e32 v169, v169
	s_nop 0
	v_add_f32_e32 v169, 1.0, v169
	v_rcp_f32_e32 v169, v169
	v_mul_f32_e32 v173, 0xbfb8aa3b, v173
	v_exp_f32_e32 v173, v173
	s_nop 0
	v_add_f32_e32 v173, 1.0, v173
	v_rcp_f32_e32 v173, v173
	v_mul_f32_e32 v166, 0xbfb8aa3b, v166
	v_exp_f32_e32 v166, v166
	s_nop 0
	v_add_f32_e32 v166, 1.0, v166
	v_rcp_f32_e32 v166, v166
	v_mul_f32_e32 v170, 0xbfb8aa3b, v170
	v_exp_f32_e32 v170, v170
	s_nop 0
	v_add_f32_e32 v170, 1.0, v170
	v_rcp_f32_e32 v170, v170
	v_mul_f32_e32 v174, 0xbfb8aa3b, v174
	v_exp_f32_e32 v174, v174
	s_nop 0
	v_add_f32_e32 v174, 1.0, v174
	v_rcp_f32_e32 v174, v174
	v_mul_f32_e32 v167, 0xbfb8aa3b, v167
	v_exp_f32_e32 v167, v167
	s_nop 0
	v_add_f32_e32 v167, 1.0, v167
	v_rcp_f32_e32 v167, v167
	v_mul_f32_e32 v171, 0xbfb8aa3b, v171
	v_exp_f32_e32 v171, v171
	s_nop 0
	v_add_f32_e32 v171, 1.0, v171
	v_rcp_f32_e32 v171, v171
	v_mul_f32_e32 v175, 0xbfb8aa3b, v175
	v_exp_f32_e32 v175, v175
	s_nop 0
	v_add_f32_e32 v175, 1.0, v175
	v_rcp_f32_e32 v175, v175
	v_mul_f32_e32 v164, 0x3f1b4598, v164
	v_mul_f32_e32 v165, 0x3f1b4598, v165
	v_mul_f32_e32 v166, 0x3f1b4598, v166
	v_mul_f32_e32 v167, 0x3f1b4598, v167
	s_cmp_eq_u32 s32, 0
	s_cbranch_scc1 .Lprep2_l0_1_3
	v_lshlrev_b32_e32 v220, 16, v146
	v_and_b32_e32 v221, 0xffff0000, v146
	v_lshlrev_b32_e32 v222, 16, v147
	v_and_b32_e32 v223, 0xffff0000, v147
	v_sub_f32_e32 v220, v220, v228
	v_fmac_f32_e32 v228, v220, v172
	v_sub_f32_e32 v221, v221, v229
	v_fmac_f32_e32 v229, v221, v173
	v_sub_f32_e32 v222, v222, v230
	v_fmac_f32_e32 v230, v222, v174
	v_sub_f32_e32 v223, v223, v231
	v_fmac_f32_e32 v231, v223, v175
	s_branch .Lprep2_l0d_1_3

.LBB0_861:
	s_or_b64 exec, exec, s[58:59]
	v_and_b32_e32 v216, 64, v179
	v_xor_b32_e32 v2, 16, v179
	v_add_u32_e32 v216, 64, v216
	v_cmp_lt_i32_e64 s[0:1], v2, v216
	v_max_f32_e32 v217, v162, v162
	v_max_f32_e32 v219, v158, v158
	v_cndmask_b32_e64 v2, v179, v2, s[0:1]
	v_lshlrev_b32_e32 v218, 2, v2
	v_max_f32_e32 v2, v163, v163
	v_max_f32_e32 v2, v217, v2
	v_max_f32_e32 v217, v159, v159
	v_max_f32_e32 v217, v219, v217
	v_max3_f32 v2, v160, v161, v2
	v_max3_f32 v217, v156, v157, v217
	v_max3_f32 v2, v2, s29, v217
	v_max_f32_e32 v217, v155, v155
	v_max_f32_e32 v219, v154, v154
	v_max_f32_e32 v217, v219, v217
	v_max_f32_e32 v219, v151, v151
	v_max_f32_e32 v220, v150, v150
	v_max_f32_e32 v219, v220, v219
	v_max3_f32 v217, v152, v153, v217
	v_max3_f32 v219, v148, v149, v219
	v_max3_f32 v2, v2, v217, v219
	v_mov_b32_e32 v217, v2
	s_nop 1
	v_permlane16_swap_b32_e32 v2, v217
	s_nop 1
	v_max_f32_e32 v2, v2, v217
	v_mov_b32_e32 v217, v2
	s_nop 1
	v_permlane32_swap_b32_e32 v2, v217
	s_nop 1
	v_max3_f32 v230, v215, v2, v217
	v_sub_f32_e32 v148, v148, v230
	v_sub_f32_e32 v152, v152, v230
	v_exp_f32_e32 v227, v148
	v_sub_f32_e32 v148, v149, v230
	v_exp_f32_e32 v223, v152
	v_sub_f32_e32 v152, v153, v230
	v_exp_f32_e32 v149, v148
	v_sub_f32_e32 v148, v150, v230
	v_exp_f32_e32 v153, v152
	v_sub_f32_e32 v152, v154, v230
	v_exp_f32_e32 v229, v148
	v_sub_f32_e32 v148, v151, v230
	v_exp_f32_e32 v225, v152
	v_sub_f32_e32 v152, v155, v230
	v_exp_f32_e32 v151, v148
	v_max_f32_e32 v148, v147, v147
	v_max_f32_e32 v150, v146, v146
	v_exp_f32_e32 v155, v152
	v_max_f32_e32 v148, v150, v148
	v_max_f32_e32 v150, v143, v143
	v_max_f32_e32 v152, v142, v142
	v_max_f32_e32 v150, v152, v150
	v_max3_f32 v148, v144, v145, v148
	v_max3_f32 v150, v140, v141, v150
	v_max3_f32 v148, v148, s29, v150
	v_max_f32_e32 v150, v139, v139
	v_max_f32_e32 v152, v138, v138
	v_max_f32_e32 v150, v152, v150
	v_max_f32_e32 v152, v135, v135
	v_max_f32_e32 v154, v134, v134
	v_max_f32_e32 v152, v154, v152
	v_max3_f32 v150, v136, v137, v150
	v_max3_f32 v152, v132, v133, v152
	v_max3_f32 v148, v148, v150, v152
	v_mov_b32_e32 v150, v148
	v_sub_f32_e32 v160, v160, v230
	v_sub_f32_e32 v2, v215, v230
	v_exp_f32_e32 v215, v160
	v_sub_f32_e32 v160, v161, v230
	s_nop 1
	v_permlane16_swap_b32_e32 v148, v150
	s_nop 1
	v_max_f32_e32 v148, v148, v150
	v_mov_b32_e32 v150, v148
	v_sub_f32_e32 v156, v156, v230
	v_exp_f32_e32 v161, v160
	v_sub_f32_e32 v160, v162, v230
	v_exp_f32_e32 v219, v156
	s_nop 1
	v_permlane32_swap_b32_e32 v148, v150
	s_nop 1
	v_max3_f32 v231, v214, v148, v150
	v_sub_f32_e32 v156, v157, v230
	v_sub_f32_e32 v144, v144, v231
	v_exp_f32_e32 v217, v160
	v_sub_f32_e32 v160, v163, v230
	v_exp_f32_e32 v157, v156
	v_sub_f32_e32 v156, v158, v230
	v_sub_f32_e32 v232, v214, v231
	v_exp_f32_e32 v214, v144
	v_sub_f32_e32 v144, v145, v231
	v_sub_f32_e32 v140, v140, v231
	v_exp_f32_e32 v163, v160
	v_exp_f32_e32 v221, v156
	v_sub_f32_e32 v156, v159, v230
	v_exp_f32_e32 v160, v144
	v_sub_f32_e32 v144, v146, v231
	v_exp_f32_e32 v218, v140
	v_sub_f32_e32 v140, v141, v231
	v_exp_f32_e32 v159, v156
	v_exp_f32_e32 v216, v144
	v_sub_f32_e32 v144, v147, v231
	v_exp_f32_e32 v156, v140
	v_sub_f32_e32 v140, v142, v231
	v_exp_f32_e32 v162, v144
	v_exp_f32_e32 v220, v140
	v_sub_f32_e32 v140, v143, v231
	v_exp_f32_e32 v158, v140
	v_pk_add_f32 v[140:141], v[214:215], 0 op_sel_hi:[1,0]
	v_sub_f32_e32 v136, v136, v231
	v_pk_add_f32 v[140:141], v[160:161], v[140:141]
	v_exp_f32_e32 v222, v136
	v_pk_add_f32 v[140:141], v[216:217], v[140:141]
	v_sub_f32_e32 v136, v137, v231
	v_pk_add_f32 v[140:141], v[162:163], v[140:141]
	v_exp_f32_e32 v152, v136
	v_pk_add_f32 v[140:141], v[218:219], v[140:141]
	v_sub_f32_e32 v136, v138, v231
	v_pk_add_f32 v[140:141], v[156:157], v[140:141]
	v_exp_f32_e32 v224, v136
	v_pk_add_f32 v[140:141], v[220:221], v[140:141]
	v_sub_f32_e32 v136, v139, v231
	v_sub_f32_e32 v132, v132, v231
	v_pk_add_f32 v[140:141], v[158:159], v[140:141]
	v_exp_f32_e32 v154, v136
	v_exp_f32_e32 v226, v132
	v_sub_f32_e32 v132, v133, v231
	v_pk_add_f32 v[140:141], v[222:223], v[140:141]
	v_exp_f32_e32 v148, v132
	v_sub_f32_e32 v132, v134, v231
	v_exp_f32_e32 v228, v132
	v_sub_f32_e32 v132, v135, v231
	v_pk_add_f32 v[134:135], v[152:153], v[140:141]
	v_exp_f32_e32 v2, v2
	v_pk_add_f32 v[134:135], v[224:225], v[134:135]
	v_exp_f32_e32 v150, v132
	v_pk_add_f32 v[134:135], v[154:155], v[134:135]
	v_exp_f32_e32 v132, v232
	v_pk_add_f32 v[134:135], v[226:227], v[134:135]
	v_mov_b32_e32 v133, v2
	v_pk_add_f32 v[134:135], v[148:149], v[134:135]
	v_pk_mul_f32 v[98:99], v[98:99], v[2:3] op_sel_hi:[1,0]
	v_pk_add_f32 v[134:135], v[228:229], v[134:135]
	v_pk_mul_f32 v[96:97], v[96:97], v[2:3] op_sel_hi:[1,0]
	v_pk_add_f32 v[134:135], v[150:151], v[134:135]
	v_pk_mul_f32 v[30:31], v[30:31], v[2:3] op_sel_hi:[1,0]
	v_pk_mul_f32 v[28:29], v[28:29], v[2:3] op_sel_hi:[1,0]
	v_pk_mul_f32 v[26:27], v[26:27], v[2:3] op_sel_hi:[1,0]
	v_pk_mul_f32 v[24:25], v[24:25], v[2:3] op_sel_hi:[1,0]
	v_pk_mul_f32 v[22:23], v[22:23], v[2:3] op_sel_hi:[1,0]
	v_pk_mul_f32 v[20:21], v[20:21], v[2:3] op_sel_hi:[1,0]
	v_pk_fma_f32 v[164:165], v[164:165], v[132:133], v[134:135]
	v_pk_mul_f32 v[18:19], v[18:19], v[132:133] op_sel_hi:[1,0]
	v_pk_mul_f32 v[16:17], v[16:17], v[132:133] op_sel_hi:[1,0]
	v_pk_mul_f32 v[14:15], v[14:15], v[132:133] op_sel_hi:[1,0]
	v_pk_mul_f32 v[12:13], v[12:13], v[132:133] op_sel_hi:[1,0]
	v_pk_mul_f32 v[10:11], v[10:11], v[132:133] op_sel_hi:[1,0]
	v_pk_mul_f32 v[8:9], v[8:9], v[132:133] op_sel_hi:[1,0]
	v_pk_mul_f32 v[6:7], v[6:7], v[132:133] op_sel_hi:[1,0]
	v_pk_mul_f32 v[4:5], v[4:5], v[132:133] op_sel_hi:[1,0]
	v_cvt_pk_bf16_f32 v132, v215, v161
	v_cvt_pk_bf16_f32 v133, v217, v163
	v_cvt_pk_bf16_f32 v134, v219, v157
	v_cvt_pk_bf16_f32 v135, v221, v159
	v_cvt_pk_bf16_f32 v136, v214, v160
	v_cvt_pk_bf16_f32 v137, v216, v162
	v_cvt_pk_bf16_f32 v138, v218, v156
	v_cvt_pk_bf16_f32 v139, v220, v158
	v_cvt_pk_bf16_f32 v140, v223, v153
	v_cvt_pk_bf16_f32 v141, v225, v155
	v_cvt_pk_bf16_f32 v142, v227, v149
	v_cvt_pk_bf16_f32 v143, v229, v151
	v_cvt_pk_bf16_f32 v144, v222, v152
	v_cvt_pk_bf16_f32 v145, v224, v154
	v_cvt_pk_bf16_f32 v146, v226, v148
	v_cvt_pk_bf16_f32 v147, v228, v150
	s_nop 0
	s_waitcnt lgkmcnt(0)
	v_mfma_f32_16x16x32_bf16 v[96:99], v[100:103], v[132:135], v[96:99]
	v_mov_b32_e32 v215, v230
	v_mov_b32_e32 v214, v231
	v_mfma_f32_16x16x32_bf16 v[16:19], v[100:103], v[136:139], v[16:19]
	v_mfma_f32_16x16x32_bf16 v[28:31], v[108:111], v[132:135], v[28:31]
	v_mfma_f32_16x16x32_bf16 v[12:15], v[108:111], v[136:139], v[12:15]
	v_mfma_f32_16x16x32_bf16 v[24:27], v[120:123], v[132:135], v[24:27]
	v_mfma_f32_16x16x32_bf16 v[8:11], v[120:123], v[136:139], v[8:11]
	v_mfma_f32_16x16x32_bf16 v[20:23], v[128:131], v[132:135], v[20:23]
	v_mfma_f32_16x16x32_bf16 v[4:7], v[128:131], v[136:139], v[4:7]
	v_mfma_f32_16x16x32_bf16 v[96:99], v[104:107], v[140:143], v[96:99]
	v_mfma_f32_16x16x32_bf16 v[16:19], v[104:107], v[144:147], v[16:19]
	v_mfma_f32_16x16x32_bf16 v[28:31], v[112:115], v[140:143], v[28:31]
	v_mfma_f32_16x16x32_bf16 v[12:15], v[112:115], v[144:147], v[12:15]
	v_mfma_f32_16x16x32_bf16 v[24:27], v[124:127], v[140:143], v[24:27]
	v_mfma_f32_16x16x32_bf16 v[8:11], v[124:127], v[144:147], v[8:11]
	v_mfma_f32_16x16x32_bf16 v[20:23], v[116:119], v[140:143], v[20:23]
	v_mfma_f32_16x16x32_bf16 v[4:7], v[116:119], v[144:147], v[4:7]

.LBB0_867:
	s_or_b64 exec, exec, s[58:59]
	v_and_b32_e32 v216, 64, v179
	v_xor_b32_e32 v2, 16, v179
	v_add_u32_e32 v216, 64, v216
	v_cmp_lt_i32_e64 s[0:1], v2, v216
	v_max_f32_e32 v217, v162, v162
	v_max_f32_e32 v219, v158, v158
	v_cndmask_b32_e64 v2, v179, v2, s[0:1]
	v_lshlrev_b32_e32 v218, 2, v2
	v_max_f32_e32 v2, v163, v163
	v_max_f32_e32 v2, v217, v2
	v_max_f32_e32 v217, v159, v159
	v_max_f32_e32 v217, v219, v217
	v_max3_f32 v2, v160, v161, v2
	v_max3_f32 v217, v156, v157, v217
	v_max3_f32 v2, v2, s29, v217
	v_max_f32_e32 v217, v155, v155
	v_max_f32_e32 v219, v154, v154
	v_max_f32_e32 v217, v219, v217
	v_max_f32_e32 v219, v151, v151
	v_max_f32_e32 v220, v150, v150
	v_max_f32_e32 v219, v220, v219
	v_max3_f32 v217, v152, v153, v217
	v_max3_f32 v219, v148, v149, v219
	v_max3_f32 v2, v2, v217, v219
	v_mov_b32_e32 v217, v2
	s_nop 1
	v_permlane16_swap_b32_e32 v2, v217
	s_nop 1
	v_max_f32_e32 v2, v2, v217
	v_mov_b32_e32 v217, v2
	s_nop 1
	v_permlane32_swap_b32_e32 v2, v217
	s_nop 1
	v_max3_f32 v230, v215, v2, v217
	v_sub_f32_e32 v148, v148, v230
	v_sub_f32_e32 v152, v152, v230
	v_exp_f32_e32 v227, v148
	v_sub_f32_e32 v148, v149, v230
	v_exp_f32_e32 v223, v152
	v_sub_f32_e32 v152, v153, v230
	v_exp_f32_e32 v149, v148
	v_sub_f32_e32 v148, v150, v230
	v_exp_f32_e32 v153, v152
	v_sub_f32_e32 v152, v154, v230
	v_exp_f32_e32 v229, v148
	v_sub_f32_e32 v148, v151, v230
	v_exp_f32_e32 v225, v152
	v_sub_f32_e32 v152, v155, v230
	v_exp_f32_e32 v151, v148
	v_max_f32_e32 v148, v147, v147
	v_max_f32_e32 v150, v146, v146
	v_exp_f32_e32 v155, v152
	v_max_f32_e32 v148, v150, v148
	v_max_f32_e32 v150, v143, v143
	v_max_f32_e32 v152, v142, v142
	v_max_f32_e32 v150, v152, v150
	v_max3_f32 v148, v144, v145, v148
	v_max3_f32 v150, v140, v141, v150
	v_max3_f32 v148, v148, s29, v150
	v_max_f32_e32 v150, v139, v139
	v_max_f32_e32 v152, v138, v138
	v_max_f32_e32 v150, v152, v150
	v_max_f32_e32 v152, v135, v135
	v_max_f32_e32 v154, v134, v134
	v_max_f32_e32 v152, v154, v152
	v_max3_f32 v150, v136, v137, v150
	v_max3_f32 v152, v132, v133, v152
	v_max3_f32 v148, v148, v150, v152
	v_mov_b32_e32 v150, v148
	v_sub_f32_e32 v160, v160, v230
	v_sub_f32_e32 v2, v215, v230
	v_exp_f32_e32 v215, v160
	v_sub_f32_e32 v160, v161, v230
	s_nop 1
	v_permlane16_swap_b32_e32 v148, v150
	s_nop 1
	v_max_f32_e32 v148, v148, v150
	v_mov_b32_e32 v150, v148
	v_exp_f32_e32 v161, v160
	v_sub_f32_e32 v160, v162, v230
	v_exp_f32_e32 v217, v160
	v_sub_f32_e32 v160, v163, v230
	s_nop 1
	v_permlane32_swap_b32_e32 v148, v150
	s_nop 1
	v_max3_f32 v231, v214, v148, v150
	v_sub_f32_e32 v144, v144, v231
	v_sub_f32_e32 v156, v156, v230
	v_sub_f32_e32 v232, v214, v231
	v_exp_f32_e32 v214, v144
	v_sub_f32_e32 v144, v145, v231
	v_exp_f32_e32 v163, v160
	v_exp_f32_e32 v219, v156
	v_sub_f32_e32 v156, v157, v230
	v_exp_f32_e32 v160, v144
	v_sub_f32_e32 v144, v146, v231
	v_exp_f32_e32 v157, v156
	v_sub_f32_e32 v156, v158, v230
	v_exp_f32_e32 v216, v144
	v_sub_f32_e32 v144, v147, v231
	v_sub_f32_e32 v140, v140, v231
	v_exp_f32_e32 v221, v156
	v_sub_f32_e32 v156, v159, v230
	v_exp_f32_e32 v162, v144
	v_exp_f32_e32 v218, v140
	v_sub_f32_e32 v140, v141, v231
	v_exp_f32_e32 v159, v156
	v_exp_f32_e32 v156, v140
	v_pk_add_f32 v[140:141], v[214:215], 0 op_sel_hi:[1,0]
	v_sub_f32_e32 v142, v142, v231
	v_pk_add_f32 v[140:141], v[160:161], v[140:141]
	v_exp_f32_e32 v220, v142
	v_pk_add_f32 v[140:141], v[216:217], v[140:141]
	v_sub_f32_e32 v142, v143, v231
	v_pk_add_f32 v[140:141], v[162:163], v[140:141]
	v_exp_f32_e32 v158, v142
	v_sub_f32_e32 v136, v136, v231
	v_sub_f32_e32 v132, v132, v231
	v_pk_add_f32 v[140:141], v[218:219], v[140:141]
	v_exp_f32_e32 v222, v136
	v_sub_f32_e32 v136, v137, v231
	v_exp_f32_e32 v226, v132
	v_sub_f32_e32 v132, v133, v231
	v_pk_add_f32 v[140:141], v[156:157], v[140:141]
	v_exp_f32_e32 v152, v136
	v_sub_f32_e32 v136, v138, v231
	v_exp_f32_e32 v148, v132
	v_sub_f32_e32 v132, v134, v231
	v_exp_f32_e32 v224, v136
	v_sub_f32_e32 v136, v139, v231
	v_exp_f32_e32 v228, v132
	v_sub_f32_e32 v132, v135, v231
	v_pk_add_f32 v[134:135], v[220:221], v[140:141]
	v_exp_f32_e32 v154, v136
	v_pk_add_f32 v[134:135], v[158:159], v[134:135]
	v_exp_f32_e32 v2, v2
	v_pk_add_f32 v[134:135], v[222:223], v[134:135]
	v_exp_f32_e32 v150, v132
	v_pk_add_f32 v[134:135], v[152:153], v[134:135]
	v_exp_f32_e32 v132, v232
	v_pk_add_f32 v[134:135], v[224:225], v[134:135]
	v_mov_b32_e32 v133, v2
	v_pk_add_f32 v[134:135], v[154:155], v[134:135]
	v_pk_mul_f32 v[98:99], v[98:99], v[2:3] op_sel_hi:[1,0]
	v_pk_add_f32 v[134:135], v[226:227], v[134:135]
	v_pk_mul_f32 v[96:97], v[96:97], v[2:3] op_sel_hi:[1,0]
	v_pk_add_f32 v[134:135], v[148:149], v[134:135]
	v_pk_mul_f32 v[30:31], v[30:31], v[2:3] op_sel_hi:[1,0]
	v_pk_add_f32 v[134:135], v[228:229], v[134:135]
	v_pk_mul_f32 v[28:29], v[28:29], v[2:3] op_sel_hi:[1,0]
	v_pk_add_f32 v[134:135], v[150:151], v[134:135]
	v_pk_mul_f32 v[26:27], v[26:27], v[2:3] op_sel_hi:[1,0]
	v_pk_mul_f32 v[24:25], v[24:25], v[2:3] op_sel_hi:[1,0]
	v_pk_mul_f32 v[22:23], v[22:23], v[2:3] op_sel_hi:[1,0]
	v_pk_mul_f32 v[20:21], v[20:21], v[2:3] op_sel_hi:[1,0]
	v_pk_fma_f32 v[164:165], v[164:165], v[132:133], v[134:135]
	v_pk_mul_f32 v[18:19], v[18:19], v[132:133] op_sel_hi:[1,0]
	v_pk_mul_f32 v[16:17], v[16:17], v[132:133] op_sel_hi:[1,0]
	v_pk_mul_f32 v[14:15], v[14:15], v[132:133] op_sel_hi:[1,0]
	v_pk_mul_f32 v[12:13], v[12:13], v[132:133] op_sel_hi:[1,0]
	v_pk_mul_f32 v[10:11], v[10:11], v[132:133] op_sel_hi:[1,0]
	v_pk_mul_f32 v[8:9], v[8:9], v[132:133] op_sel_hi:[1,0]
	v_pk_mul_f32 v[6:7], v[6:7], v[132:133] op_sel_hi:[1,0]
	v_pk_mul_f32 v[4:5], v[4:5], v[132:133] op_sel_hi:[1,0]
	v_cvt_pk_bf16_f32 v132, v215, v161
	v_cvt_pk_bf16_f32 v133, v217, v163
	v_cvt_pk_bf16_f32 v134, v219, v157
	v_cvt_pk_bf16_f32 v135, v221, v159
	v_cvt_pk_bf16_f32 v136, v214, v160
	v_cvt_pk_bf16_f32 v137, v216, v162
	v_cvt_pk_bf16_f32 v138, v218, v156
	v_cvt_pk_bf16_f32 v139, v220, v158
	v_cvt_pk_bf16_f32 v140, v223, v153
	v_cvt_pk_bf16_f32 v141, v225, v155
	v_cvt_pk_bf16_f32 v142, v227, v149
	v_cvt_pk_bf16_f32 v143, v229, v151
	v_cvt_pk_bf16_f32 v144, v222, v152
	v_cvt_pk_bf16_f32 v145, v224, v154
	v_cvt_pk_bf16_f32 v146, v226, v148
	v_cvt_pk_bf16_f32 v147, v228, v150
	s_nop 0
	s_waitcnt lgkmcnt(0)
	v_mfma_f32_16x16x32_bf16 v[96:99], v[100:103], v[132:135], v[96:99]
	v_mov_b32_e32 v215, v230
	v_mov_b32_e32 v214, v231
	v_mfma_f32_16x16x32_bf16 v[16:19], v[100:103], v[136:139], v[16:19]
	v_mfma_f32_16x16x32_bf16 v[28:31], v[108:111], v[132:135], v[28:31]
	v_mfma_f32_16x16x32_bf16 v[12:15], v[108:111], v[136:139], v[12:15]
	v_mfma_f32_16x16x32_bf16 v[24:27], v[120:123], v[132:135], v[24:27]
	v_mfma_f32_16x16x32_bf16 v[8:11], v[120:123], v[136:139], v[8:11]
	v_mfma_f32_16x16x32_bf16 v[20:23], v[128:131], v[132:135], v[20:23]
	v_mfma_f32_16x16x32_bf16 v[4:7], v[128:131], v[136:139], v[4:7]
	v_mfma_f32_16x16x32_bf16 v[96:99], v[104:107], v[140:143], v[96:99]
	v_mfma_f32_16x16x32_bf16 v[16:19], v[104:107], v[144:147], v[16:19]
	v_mfma_f32_16x16x32_bf16 v[28:31], v[112:115], v[140:143], v[28:31]
	v_mfma_f32_16x16x32_bf16 v[12:15], v[112:115], v[144:147], v[12:15]
	v_mfma_f32_16x16x32_bf16 v[24:27], v[124:127], v[140:143], v[24:27]
	v_mfma_f32_16x16x32_bf16 v[8:11], v[124:127], v[144:147], v[8:11]
	v_mfma_f32_16x16x32_bf16 v[20:23], v[116:119], v[140:143], v[20:23]
	v_mfma_f32_16x16x32_bf16 v[4:7], v[116:119], v[144:147], v[4:7]
